# fused epilogue conv, scaling and gating arithmetic switched to packed f32 ops (v_pk_fma_f32, v_pk_mul_f32, v_pk_add_f32), same f32 numerics
# speedup vs baseline: 1.0275x; 1.0113x over previous
.LepB_fast:
	s_mov_b32 s76, 0xbfb8aa3b
	s_mov_b32 s77, 0xbfb8aa3b
	s_mov_b32 s78, 1.0
	s_mov_b32 s79, 1.0
	s_and_b32 s32, s12, 1
	v_and_b32_e32 v237, 15, v170
	v_and_b32_e32 v236, 64, v170
	v_lshl_add_u32 v236, v237, 2, v236
	v_mul_u32_u24_e32 v168, 0x1600, v236
	v_lshl_add_u32 v168, v172, 1, v168
	v_lshl_add_u32 v236, v236, 2, s57
	v_lshl_add_u32 v177, v172, 2, s57
	ds_read_b128 v[210:213], v236
	ds_read_b128 v[214:217], v236 offset:512
	ds_read_b128 v[202:205], v177 offset:1024
	ds_read_b128 v[206:209], v177 offset:1040
	ds_read_b128 v[218:221], v177 offset:1536
	ds_read_b128 v[222:225], v177 offset:1552
	ds_read_b128 v[116:119], v177 offset:2048
	ds_read_b128 v[124:127], v177 offset:2560
	ds_read_b128 v[128:131], v177 offset:4096
	ds_read_b128 v[132:135], v177 offset:5120
	ds_read_b128 v[160:163], v177 offset:3072
	ds_read_b128 v[164:167], v177 offset:3584
	ds_read_b128 v[178:181], v177 offset:4608
	ds_read_b128 v[182:185], v177 offset:5632
	s_mul_i32 s4, s88, 0x160000
	s_lshl_b32 s67, s66, 8
	s_add_i32 s4, s4, s67
	s_add_i32 s4, s4, 0x9300000
	s_add_u32 s4, s4, s70
	s_addc_u32 s5, s71, 0
	s_mov_b32 s67, 0x20800
	v_lshl_add_u32 v169, v172, 2, s67
	v_cmp_eq_u32_e64 s[2:3], 0, v237
	v_cmp_eq_u32_e64 s[28:29], 15, v237
	v_and_b32_e32 v231, 8, v237
	v_lshlrev_b32_e32 v231, 9, v231
	s_lshl_b32 s67, s32, 10
	v_add3_u32 v231, v231, v169, s67
	s_waitcnt lgkmcnt(12)
	v_fmamk_f32 v210, v210, 0x3a800000, v176
	v_fmamk_f32 v211, v211, 0x3a800000, v176
	v_fmamk_f32 v212, v212, 0x3a800000, v176
	v_fmamk_f32 v213, v213, 0x3a800000, v176
	v_fmamk_f32 v214, v214, 0x3a800000, v176
	v_fmamk_f32 v215, v215, 0x3a800000, v176
	v_fmamk_f32 v216, v216, 0x3a800000, v176
	v_fmamk_f32 v217, v217, 0x3a800000, v176
	s_mov_b32 s67, 0x800000
	v_mul_f32_e32 v226, 0x4b800000, v210
	v_mul_f32_e32 v227, 0x4b800000, v211
	v_mul_f32_e32 v228, 0x4b800000, v212
	v_mul_f32_e32 v229, 0x4b800000, v213
	v_mul_f32_e32 v232, 0x4b800000, v214
	v_mul_f32_e32 v233, 0x4b800000, v215
	v_mul_f32_e32 v234, 0x4b800000, v216
	v_mul_f32_e32 v235, 0x4b800000, v217
	v_cmp_gt_f32_e32 vcc, s67, v210
	s_nop 1
	v_cndmask_b32_e32 v210, v210, v226, vcc
	v_rsq_f32_e32 v210, v210
	s_nop 0
	v_mul_f32_e32 v226, 0x45800000, v210
	v_cndmask_b32_e32 v210, v210, v226, vcc
	v_cmp_gt_f32_e32 vcc, s67, v211
	s_nop 1
	v_cndmask_b32_e32 v211, v211, v227, vcc
	v_rsq_f32_e32 v211, v211
	s_nop 0
	v_mul_f32_e32 v227, 0x45800000, v211
	v_cndmask_b32_e32 v211, v211, v227, vcc
	v_cmp_gt_f32_e32 vcc, s67, v212
	s_nop 1
	v_cndmask_b32_e32 v212, v212, v228, vcc
	v_rsq_f32_e32 v212, v212
	s_nop 0
	v_mul_f32_e32 v228, 0x45800000, v212
	v_cndmask_b32_e32 v212, v212, v228, vcc
	v_cmp_gt_f32_e32 vcc, s67, v213
	s_nop 1
	v_cndmask_b32_e32 v213, v213, v229, vcc
	v_rsq_f32_e32 v213, v213
	s_nop 0
	v_mul_f32_e32 v229, 0x45800000, v213
	v_cndmask_b32_e32 v213, v213, v229, vcc
	v_cmp_gt_f32_e32 vcc, s67, v214
	s_nop 1
	v_cndmask_b32_e32 v214, v214, v232, vcc
	v_rsq_f32_e32 v214, v214
	s_nop 0
	v_mul_f32_e32 v232, 0x45800000, v214
	v_cndmask_b32_e32 v214, v214, v232, vcc
	v_cmp_gt_f32_e32 vcc, s67, v215
	s_nop 1
	v_cndmask_b32_e32 v215, v215, v233, vcc
	v_rsq_f32_e32 v215, v215
	s_nop 0
	v_mul_f32_e32 v233, 0x45800000, v215
	v_cndmask_b32_e32 v215, v215, v233, vcc
	v_cmp_gt_f32_e32 vcc, s67, v216
	s_nop 1
	v_cndmask_b32_e32 v216, v216, v234, vcc
	v_rsq_f32_e32 v216, v216
	s_nop 0
	v_mul_f32_e32 v234, 0x45800000, v216
	v_cndmask_b32_e32 v216, v216, v234, vcc
	v_cmp_gt_f32_e32 vcc, s67, v217
	s_nop 1
	v_cndmask_b32_e32 v217, v217, v235, vcc
	v_rsq_f32_e32 v217, v217
	s_nop 0
	v_mul_f32_e32 v235, 0x45800000, v217
	v_cndmask_b32_e32 v217, v217, v235, vcc
	s_waitcnt lgkmcnt(8)
	v_pk_fma_f32 v[140:141], v[140:141], v[210:211], v[202:203] op_sel:[0,0,0] op_sel_hi:[1,0,1]
	v_pk_fma_f32 v[142:143], v[142:143], v[210:211], v[204:205] op_sel:[0,0,0] op_sel_hi:[1,0,1]
	v_pk_fma_f32 v[136:137], v[136:137], v[210:211], v[206:207] op_sel:[0,0,0] op_sel_hi:[1,0,1]
	v_pk_fma_f32 v[138:139], v[138:139], v[210:211], v[208:209] op_sel:[0,0,0] op_sel_hi:[1,0,1]
	v_pk_fma_f32 v[120:121], v[120:121], v[210:211], v[218:219] op_sel:[0,0,0] op_sel_hi:[1,0,1]
	v_pk_fma_f32 v[122:123], v[122:123], v[210:211], v[220:221] op_sel:[0,0,0] op_sel_hi:[1,0,1]
	v_pk_fma_f32 v[112:113], v[112:113], v[210:211], v[222:223] op_sel:[0,0,0] op_sel_hi:[1,0,1]
	v_pk_fma_f32 v[114:115], v[114:115], v[210:211], v[224:225] op_sel:[0,0,0] op_sel_hi:[1,0,1]
	v_pk_fma_f32 v[108:109], v[108:109], v[210:211], v[202:203] op_sel:[0,1,0] op_sel_hi:[1,1,1]
	v_pk_fma_f32 v[110:111], v[110:111], v[210:211], v[204:205] op_sel:[0,1,0] op_sel_hi:[1,1,1]
	v_pk_fma_f32 v[104:105], v[104:105], v[210:211], v[206:207] op_sel:[0,1,0] op_sel_hi:[1,1,1]
	v_pk_fma_f32 v[106:107], v[106:107], v[210:211], v[208:209] op_sel:[0,1,0] op_sel_hi:[1,1,1]
	v_pk_fma_f32 v[100:101], v[100:101], v[210:211], v[218:219] op_sel:[0,1,0] op_sel_hi:[1,1,1]
	v_pk_fma_f32 v[102:103], v[102:103], v[210:211], v[220:221] op_sel:[0,1,0] op_sel_hi:[1,1,1]
	v_pk_fma_f32 v[96:97], v[96:97], v[210:211], v[222:223] op_sel:[0,1,0] op_sel_hi:[1,1,1]
	v_pk_fma_f32 v[98:99], v[98:99], v[210:211], v[224:225] op_sel:[0,1,0] op_sel_hi:[1,1,1]
	v_pk_fma_f32 v[92:93], v[92:93], v[212:213], v[202:203] op_sel:[0,0,0] op_sel_hi:[1,0,1]
	v_pk_fma_f32 v[94:95], v[94:95], v[212:213], v[204:205] op_sel:[0,0,0] op_sel_hi:[1,0,1]
	v_pk_fma_f32 v[88:89], v[88:89], v[212:213], v[206:207] op_sel:[0,0,0] op_sel_hi:[1,0,1]
	v_pk_fma_f32 v[90:91], v[90:91], v[212:213], v[208:209] op_sel:[0,0,0] op_sel_hi:[1,0,1]
	v_pk_fma_f32 v[84:85], v[84:85], v[212:213], v[218:219] op_sel:[0,0,0] op_sel_hi:[1,0,1]
	v_pk_fma_f32 v[86:87], v[86:87], v[212:213], v[220:221] op_sel:[0,0,0] op_sel_hi:[1,0,1]
	v_pk_fma_f32 v[80:81], v[80:81], v[212:213], v[222:223] op_sel:[0,0,0] op_sel_hi:[1,0,1]
	v_pk_fma_f32 v[82:83], v[82:83], v[212:213], v[224:225] op_sel:[0,0,0] op_sel_hi:[1,0,1]
	v_pk_fma_f32 v[76:77], v[76:77], v[212:213], v[202:203] op_sel:[0,1,0] op_sel_hi:[1,1,1]
	v_pk_fma_f32 v[78:79], v[78:79], v[212:213], v[204:205] op_sel:[0,1,0] op_sel_hi:[1,1,1]
	v_pk_fma_f32 v[72:73], v[72:73], v[212:213], v[206:207] op_sel:[0,1,0] op_sel_hi:[1,1,1]
	v_pk_fma_f32 v[74:75], v[74:75], v[212:213], v[208:209] op_sel:[0,1,0] op_sel_hi:[1,1,1]
	v_pk_fma_f32 v[68:69], v[68:69], v[212:213], v[218:219] op_sel:[0,1,0] op_sel_hi:[1,1,1]
	v_pk_fma_f32 v[70:71], v[70:71], v[212:213], v[220:221] op_sel:[0,1,0] op_sel_hi:[1,1,1]
	v_pk_fma_f32 v[64:65], v[64:65], v[212:213], v[222:223] op_sel:[0,1,0] op_sel_hi:[1,1,1]
	v_pk_fma_f32 v[66:67], v[66:67], v[212:213], v[224:225] op_sel:[0,1,0] op_sel_hi:[1,1,1]
	v_pk_fma_f32 v[60:61], v[60:61], v[214:215], v[202:203] op_sel:[0,0,0] op_sel_hi:[1,0,1]
	v_pk_fma_f32 v[62:63], v[62:63], v[214:215], v[204:205] op_sel:[0,0,0] op_sel_hi:[1,0,1]
	v_pk_fma_f32 v[56:57], v[56:57], v[214:215], v[206:207] op_sel:[0,0,0] op_sel_hi:[1,0,1]
	v_pk_fma_f32 v[58:59], v[58:59], v[214:215], v[208:209] op_sel:[0,0,0] op_sel_hi:[1,0,1]
	v_pk_fma_f32 v[52:53], v[52:53], v[214:215], v[218:219] op_sel:[0,0,0] op_sel_hi:[1,0,1]
	v_pk_fma_f32 v[54:55], v[54:55], v[214:215], v[220:221] op_sel:[0,0,0] op_sel_hi:[1,0,1]
	v_pk_fma_f32 v[48:49], v[48:49], v[214:215], v[222:223] op_sel:[0,0,0] op_sel_hi:[1,0,1]
	v_pk_fma_f32 v[50:51], v[50:51], v[214:215], v[224:225] op_sel:[0,0,0] op_sel_hi:[1,0,1]
	v_pk_fma_f32 v[44:45], v[44:45], v[214:215], v[202:203] op_sel:[0,1,0] op_sel_hi:[1,1,1]
	v_pk_fma_f32 v[46:47], v[46:47], v[214:215], v[204:205] op_sel:[0,1,0] op_sel_hi:[1,1,1]
	v_pk_fma_f32 v[40:41], v[40:41], v[214:215], v[206:207] op_sel:[0,1,0] op_sel_hi:[1,1,1]
	v_pk_fma_f32 v[42:43], v[42:43], v[214:215], v[208:209] op_sel:[0,1,0] op_sel_hi:[1,1,1]
	v_pk_fma_f32 v[36:37], v[36:37], v[214:215], v[218:219] op_sel:[0,1,0] op_sel_hi:[1,1,1]
	v_pk_fma_f32 v[38:39], v[38:39], v[214:215], v[220:221] op_sel:[0,1,0] op_sel_hi:[1,1,1]
	v_pk_fma_f32 v[32:33], v[32:33], v[214:215], v[222:223] op_sel:[0,1,0] op_sel_hi:[1,1,1]
	v_pk_fma_f32 v[34:35], v[34:35], v[214:215], v[224:225] op_sel:[0,1,0] op_sel_hi:[1,1,1]
	v_pk_fma_f32 v[28:29], v[28:29], v[216:217], v[202:203] op_sel:[0,0,0] op_sel_hi:[1,0,1]
	v_pk_fma_f32 v[30:31], v[30:31], v[216:217], v[204:205] op_sel:[0,0,0] op_sel_hi:[1,0,1]
	v_pk_fma_f32 v[24:25], v[24:25], v[216:217], v[206:207] op_sel:[0,0,0] op_sel_hi:[1,0,1]
	v_pk_fma_f32 v[26:27], v[26:27], v[216:217], v[208:209] op_sel:[0,0,0] op_sel_hi:[1,0,1]
	v_pk_fma_f32 v[20:21], v[20:21], v[216:217], v[218:219] op_sel:[0,0,0] op_sel_hi:[1,0,1]
	v_pk_fma_f32 v[22:23], v[22:23], v[216:217], v[220:221] op_sel:[0,0,0] op_sel_hi:[1,0,1]
	v_pk_fma_f32 v[16:17], v[16:17], v[216:217], v[222:223] op_sel:[0,0,0] op_sel_hi:[1,0,1]
	v_pk_fma_f32 v[18:19], v[18:19], v[216:217], v[224:225] op_sel:[0,0,0] op_sel_hi:[1,0,1]
	v_pk_fma_f32 v[12:13], v[12:13], v[216:217], v[202:203] op_sel:[0,1,0] op_sel_hi:[1,1,1]
	v_pk_fma_f32 v[14:15], v[14:15], v[216:217], v[204:205] op_sel:[0,1,0] op_sel_hi:[1,1,1]
	v_pk_fma_f32 v[8:9], v[8:9], v[216:217], v[206:207] op_sel:[0,1,0] op_sel_hi:[1,1,1]
	v_pk_fma_f32 v[10:11], v[10:11], v[216:217], v[208:209] op_sel:[0,1,0] op_sel_hi:[1,1,1]
	v_pk_fma_f32 v[4:5], v[4:5], v[216:217], v[218:219] op_sel:[0,1,0] op_sel_hi:[1,1,1]
	v_pk_fma_f32 v[6:7], v[6:7], v[216:217], v[220:221] op_sel:[0,1,0] op_sel_hi:[1,1,1]
	v_pk_fma_f32 v[0:1], v[0:1], v[216:217], v[222:223] op_sel:[0,1,0] op_sel_hi:[1,1,1]
	v_pk_fma_f32 v[2:3], v[2:3], v[216:217], v[224:225] op_sel:[0,1,0] op_sel_hi:[1,1,1]
	v_mov_b32_e32 v214, 0
	v_mov_b32_e32 v215, 0
	v_mov_b32_e32 v216, 0
	v_mov_b32_e32 v217, 0
	s_lshl_b32 s100, s32, 12
	s_sub_i32 s100, 0x2000, s100
	s_mul_i32 s98, s32, 0x1400
	s_add_i32 s98, s98, 0xc00
	s_lshl_b32 s67, s32, 10
	s_add_i32 s99, s67, 5120
	s_add_i32 s94, s67, 1024
	s_mov_b64 exec, s[2:3]
	v_add_u32_e32 v250, s100, v169
	ds_write_b128 v250, v[140:143] offset:0
	ds_write_b128 v250, v[136:139] offset:16
	ds_write_b128 v250, v[120:123] offset:512
	ds_write_b128 v250, v[112:115] offset:528
	v_add_u32_e32 v250, s99, v169
	ds_write_b128 v250, v[60:63] offset:0
	ds_write_b128 v250, v[56:59] offset:16
	ds_write_b128 v250, v[52:55] offset:512
	ds_write_b128 v250, v[48:51] offset:528
	ds_write_b128 v169, v[214:217] offset:0
	ds_write_b128 v169, v[214:217] offset:16
	ds_write_b128 v169, v[214:217] offset:512
	ds_write_b128 v169, v[214:217] offset:528
	s_mov_b64 exec, s[28:29]
	v_add_u32_e32 v251, s94, v169
	ds_write_b128 v251, v[76:79] offset:0
	ds_write_b128 v251, v[72:75] offset:16
	ds_write_b128 v251, v[68:71] offset:512
	ds_write_b128 v251, v[64:67] offset:528
	v_add_u32_e32 v251, s98, v169
	ds_write_b128 v251, v[12:15] offset:0
	ds_write_b128 v251, v[8:11] offset:16
	ds_write_b128 v251, v[4:7] offset:512
	ds_write_b128 v251, v[0:3] offset:528
	ds_write_b128 v169, v[214:217] offset:7168
	ds_write_b128 v169, v[214:217] offset:7184
	ds_write_b128 v169, v[214:217] offset:7680
	ds_write_b128 v169, v[214:217] offset:7696
	s_mov_b64 exec, -1
	s_waitcnt lgkmcnt(0)
	s_barrier
	ds_read_b128 v[186:189], v231 offset:0
	ds_read_b128 v[190:193], v231 offset:512
	ds_read_b128 v[194:197], v231 offset:2048
	ds_read_b128 v[198:201], v231 offset:2560
	s_nop 0
	v_cndmask_b32_e64 v218, 0, v116, s[2:3]
	v_cndmask_b32_e64 v222, 0, v128, s[28:29]
	v_cndmask_b32_e64 v219, 0, v117, s[2:3]
	v_cndmask_b32_e64 v223, 0, v129, s[28:29]
	v_cndmask_b32_e64 v220, 0, v118, s[2:3]
	v_cndmask_b32_e64 v224, 0, v130, s[28:29]
	v_cndmask_b32_e64 v221, 0, v119, s[2:3]
	v_cndmask_b32_e64 v225, 0, v131, s[28:29]
	v_cndmask_b32_e64 v226, 0, v160, s[2:3]
	v_cndmask_b32_e64 v232, 0, v178, s[28:29]
	v_cndmask_b32_e64 v227, 0, v161, s[2:3]
	v_cndmask_b32_e64 v233, 0, v179, s[28:29]
	v_cndmask_b32_e64 v228, 0, v162, s[2:3]
	v_cndmask_b32_e64 v234, 0, v180, s[28:29]
	v_cndmask_b32_e64 v229, 0, v163, s[2:3]
	v_cndmask_b32_e64 v235, 0, v181, s[28:29]
	s_waitcnt lgkmcnt(0)
	s_nop 1
	v_pk_fma_f32 v[202:203], v[124:125], v[140:141], v[132:133]
	v_pk_fma_f32 v[204:205], v[126:127], v[142:143], v[134:135]
	v_fmac_f32_dpp v202, v76, v116 row_shr:1 row_mask:0xf bank_mask:0xf
	v_fmac_f32_dpp v203, v77, v117 row_shr:1 row_mask:0xf bank_mask:0xf
	v_fmac_f32_dpp v204, v78, v118 row_shr:1 row_mask:0xf bank_mask:0xf
	v_fmac_f32_dpp v205, v79, v119 row_shr:1 row_mask:0xf bank_mask:0xf
	v_pk_fma_f32 v[202:203], v[186:187], v[218:219], v[202:203]
	v_pk_fma_f32 v[204:205], v[188:189], v[220:221], v[204:205]
	v_pk_fma_f32 v[202:203], v[108:109], v[128:129], v[202:203]
	v_pk_fma_f32 v[204:205], v[110:111], v[130:131], v[204:205]
	v_pk_fma_f32 v[206:207], v[164:165], v[120:121], v[182:183]
	v_pk_fma_f32 v[208:209], v[166:167], v[122:123], v[184:185]
	v_fmac_f32_dpp v206, v68, v160 row_shr:1 row_mask:0xf bank_mask:0xf
	v_fmac_f32_dpp v207, v69, v161 row_shr:1 row_mask:0xf bank_mask:0xf
	v_fmac_f32_dpp v208, v70, v162 row_shr:1 row_mask:0xf bank_mask:0xf
	v_fmac_f32_dpp v209, v71, v163 row_shr:1 row_mask:0xf bank_mask:0xf
	v_pk_fma_f32 v[206:207], v[190:191], v[226:227], v[206:207]
	v_pk_fma_f32 v[208:209], v[192:193], v[228:229], v[208:209]
	v_pk_fma_f32 v[206:207], v[100:101], v[178:179], v[206:207]
	v_pk_fma_f32 v[208:209], v[102:103], v[180:181], v[208:209]
	v_pk_mul_f32 v[210:211], v[202:203], s[76:77]
	v_pk_mul_f32 v[212:213], v[204:205], s[76:77]
	v_exp_f32_e32 v210, v210
	v_exp_f32_e32 v211, v211
	v_exp_f32_e32 v212, v212
	v_exp_f32_e32 v213, v213
	v_pk_add_f32 v[210:211], v[210:211], s[78:79]
	v_pk_add_f32 v[212:213], v[212:213], s[78:79]
	v_rcp_f32_e32 v210, v210
	v_rcp_f32_e32 v211, v211
	v_rcp_f32_e32 v212, v212
	v_rcp_f32_e32 v213, v213
	v_pk_mul_f32 v[202:203], v[202:203], v[210:211]
	v_pk_mul_f32 v[204:205], v[204:205], v[212:213]
	v_pk_mul_f32 v[202:203], v[202:203], v[206:207]
	v_pk_mul_f32 v[204:205], v[204:205], v[208:209]
	v_cvt_pk_bf16_f32 v236, v202, v203
	v_cvt_pk_bf16_f32 v237, v204, v205
	v_pk_fma_f32 v[202:203], v[124:125], v[108:109], v[132:133]
	v_pk_fma_f32 v[204:205], v[126:127], v[110:111], v[134:135]
	v_pk_fma_f32 v[202:203], v[140:141], v[116:117], v[202:203]
	v_pk_fma_f32 v[204:205], v[142:143], v[118:119], v[204:205]
	v_pk_fma_f32 v[202:203], v[92:93], v[128:129], v[202:203]
	v_pk_fma_f32 v[204:205], v[94:95], v[130:131], v[204:205]
	v_pk_fma_f32 v[206:207], v[164:165], v[100:101], v[182:183]
	v_pk_fma_f32 v[208:209], v[166:167], v[102:103], v[184:185]
	v_pk_fma_f32 v[206:207], v[120:121], v[160:161], v[206:207]
	v_pk_fma_f32 v[208:209], v[122:123], v[162:163], v[208:209]
	v_pk_fma_f32 v[206:207], v[84:85], v[178:179], v[206:207]
	v_pk_fma_f32 v[208:209], v[86:87], v[180:181], v[208:209]
	v_pk_mul_f32 v[210:211], v[202:203], s[76:77]
	v_pk_mul_f32 v[212:213], v[204:205], s[76:77]
	v_exp_f32_e32 v210, v210
	v_exp_f32_e32 v211, v211
	v_exp_f32_e32 v212, v212
	v_exp_f32_e32 v213, v213
	v_pk_add_f32 v[210:211], v[210:211], s[78:79]
	v_pk_add_f32 v[212:213], v[212:213], s[78:79]
	v_rcp_f32_e32 v210, v210
	v_rcp_f32_e32 v211, v211
	v_rcp_f32_e32 v212, v212
	v_rcp_f32_e32 v213, v213
	v_pk_mul_f32 v[202:203], v[202:203], v[210:211]
	v_pk_mul_f32 v[204:205], v[204:205], v[212:213]
	v_pk_mul_f32 v[202:203], v[202:203], v[206:207]
	v_pk_mul_f32 v[204:205], v[204:205], v[208:209]
	v_cvt_pk_bf16_f32 v238, v202, v203
	v_cvt_pk_bf16_f32 v239, v204, v205
	v_pk_fma_f32 v[202:203], v[124:125], v[92:93], v[132:133]
	v_pk_fma_f32 v[204:205], v[126:127], v[94:95], v[134:135]
	v_pk_fma_f32 v[202:203], v[108:109], v[116:117], v[202:203]
	v_pk_fma_f32 v[204:205], v[110:111], v[118:119], v[204:205]
	v_pk_fma_f32 v[202:203], v[76:77], v[128:129], v[202:203]
	v_pk_fma_f32 v[204:205], v[78:79], v[130:131], v[204:205]
	v_pk_fma_f32 v[206:207], v[164:165], v[84:85], v[182:183]
	v_pk_fma_f32 v[208:209], v[166:167], v[86:87], v[184:185]
	v_pk_fma_f32 v[206:207], v[100:101], v[160:161], v[206:207]
	v_pk_fma_f32 v[208:209], v[102:103], v[162:163], v[208:209]
	v_pk_fma_f32 v[206:207], v[68:69], v[178:179], v[206:207]
	v_pk_fma_f32 v[208:209], v[70:71], v[180:181], v[208:209]
	v_pk_mul_f32 v[210:211], v[202:203], s[76:77]
	v_pk_mul_f32 v[212:213], v[204:205], s[76:77]
	v_exp_f32_e32 v210, v210
	v_exp_f32_e32 v211, v211
	v_exp_f32_e32 v212, v212
	v_exp_f32_e32 v213, v213
	v_pk_add_f32 v[210:211], v[210:211], s[78:79]
	v_pk_add_f32 v[212:213], v[212:213], s[78:79]
	v_rcp_f32_e32 v210, v210
	v_rcp_f32_e32 v211, v211
	v_rcp_f32_e32 v212, v212
	v_rcp_f32_e32 v213, v213
	v_pk_mul_f32 v[202:203], v[202:203], v[210:211]
	v_pk_mul_f32 v[204:205], v[204:205], v[212:213]
	v_pk_mul_f32 v[202:203], v[202:203], v[206:207]
	v_pk_mul_f32 v[204:205], v[204:205], v[208:209]
	v_cvt_pk_bf16_f32 v240, v202, v203
	v_cvt_pk_bf16_f32 v241, v204, v205
	v_pk_fma_f32 v[202:203], v[124:125], v[76:77], v[132:133]
	v_pk_fma_f32 v[204:205], v[126:127], v[78:79], v[134:135]
	v_pk_fma_f32 v[202:203], v[92:93], v[116:117], v[202:203]
	v_pk_fma_f32 v[204:205], v[94:95], v[118:119], v[204:205]
	v_fmac_f32_dpp v202, v140, v128 row_shl:1 row_mask:0xf bank_mask:0xf
	v_fmac_f32_dpp v203, v141, v129 row_shl:1 row_mask:0xf bank_mask:0xf
	v_fmac_f32_dpp v204, v142, v130 row_shl:1 row_mask:0xf bank_mask:0xf
	v_fmac_f32_dpp v205, v143, v131 row_shl:1 row_mask:0xf bank_mask:0xf
	v_pk_fma_f32 v[202:203], v[186:187], v[222:223], v[202:203]
	v_pk_fma_f32 v[204:205], v[188:189], v[224:225], v[204:205]
	v_pk_fma_f32 v[206:207], v[164:165], v[68:69], v[182:183]
	v_pk_fma_f32 v[208:209], v[166:167], v[70:71], v[184:185]
	v_pk_fma_f32 v[206:207], v[84:85], v[160:161], v[206:207]
	v_pk_fma_f32 v[208:209], v[86:87], v[162:163], v[208:209]
	v_fmac_f32_dpp v206, v120, v178 row_shl:1 row_mask:0xf bank_mask:0xf
	v_fmac_f32_dpp v207, v121, v179 row_shl:1 row_mask:0xf bank_mask:0xf
	v_fmac_f32_dpp v208, v122, v180 row_shl:1 row_mask:0xf bank_mask:0xf
	v_fmac_f32_dpp v209, v123, v181 row_shl:1 row_mask:0xf bank_mask:0xf
	v_pk_fma_f32 v[206:207], v[190:191], v[232:233], v[206:207]
	v_pk_fma_f32 v[208:209], v[192:193], v[234:235], v[208:209]
	v_pk_mul_f32 v[210:211], v[202:203], s[76:77]
	v_pk_mul_f32 v[212:213], v[204:205], s[76:77]
	v_exp_f32_e32 v210, v210
	v_exp_f32_e32 v211, v211
	v_exp_f32_e32 v212, v212
	v_exp_f32_e32 v213, v213
	v_pk_add_f32 v[210:211], v[210:211], s[78:79]
	v_pk_add_f32 v[212:213], v[212:213], s[78:79]
	v_rcp_f32_e32 v210, v210
	v_rcp_f32_e32 v211, v211
	v_rcp_f32_e32 v212, v212
	v_rcp_f32_e32 v213, v213
	v_pk_mul_f32 v[202:203], v[202:203], v[210:211]
	v_pk_mul_f32 v[204:205], v[204:205], v[212:213]
	v_pk_mul_f32 v[202:203], v[202:203], v[206:207]
	v_pk_mul_f32 v[204:205], v[204:205], v[208:209]
	v_cvt_pk_bf16_f32 v242, v202, v203
	v_cvt_pk_bf16_f32 v243, v204, v205
	v_pk_fma_f32 v[202:203], v[124:125], v[60:61], v[132:133]
	v_pk_fma_f32 v[204:205], v[126:127], v[62:63], v[134:135]
	v_fmac_f32_dpp v202, v12, v116 row_shr:1 row_mask:0xf bank_mask:0xf
	v_fmac_f32_dpp v203, v13, v117 row_shr:1 row_mask:0xf bank_mask:0xf
	v_fmac_f32_dpp v204, v14, v118 row_shr:1 row_mask:0xf bank_mask:0xf
	v_fmac_f32_dpp v205, v15, v119 row_shr:1 row_mask:0xf bank_mask:0xf
	v_pk_fma_f32 v[202:203], v[194:195], v[218:219], v[202:203]
	v_pk_fma_f32 v[204:205], v[196:197], v[220:221], v[204:205]
	v_pk_fma_f32 v[202:203], v[44:45], v[128:129], v[202:203]
	v_pk_fma_f32 v[204:205], v[46:47], v[130:131], v[204:205]
	v_pk_fma_f32 v[206:207], v[164:165], v[52:53], v[182:183]
	v_pk_fma_f32 v[208:209], v[166:167], v[54:55], v[184:185]
	v_fmac_f32_dpp v206, v4, v160 row_shr:1 row_mask:0xf bank_mask:0xf
	v_fmac_f32_dpp v207, v5, v161 row_shr:1 row_mask:0xf bank_mask:0xf
	v_fmac_f32_dpp v208, v6, v162 row_shr:1 row_mask:0xf bank_mask:0xf
	v_fmac_f32_dpp v209, v7, v163 row_shr:1 row_mask:0xf bank_mask:0xf
	v_pk_fma_f32 v[206:207], v[198:199], v[226:227], v[206:207]
	v_pk_fma_f32 v[208:209], v[200:201], v[228:229], v[208:209]
	v_pk_fma_f32 v[206:207], v[36:37], v[178:179], v[206:207]
	v_pk_fma_f32 v[208:209], v[38:39], v[180:181], v[208:209]
	v_pk_mul_f32 v[210:211], v[202:203], s[76:77]
	v_pk_mul_f32 v[212:213], v[204:205], s[76:77]
	v_exp_f32_e32 v210, v210
	v_exp_f32_e32 v211, v211
	v_exp_f32_e32 v212, v212
	v_exp_f32_e32 v213, v213
	v_pk_add_f32 v[210:211], v[210:211], s[78:79]
	v_pk_add_f32 v[212:213], v[212:213], s[78:79]
	v_rcp_f32_e32 v210, v210
	v_rcp_f32_e32 v211, v211
	v_rcp_f32_e32 v212, v212
	v_rcp_f32_e32 v213, v213
	v_pk_mul_f32 v[202:203], v[202:203], v[210:211]
	v_pk_mul_f32 v[204:205], v[204:205], v[212:213]
	v_pk_mul_f32 v[202:203], v[202:203], v[206:207]
	v_pk_mul_f32 v[204:205], v[204:205], v[208:209]
	v_cvt_pk_bf16_f32 v244, v202, v203
	v_cvt_pk_bf16_f32 v245, v204, v205
	v_pk_fma_f32 v[202:203], v[124:125], v[44:45], v[132:133]
	v_pk_fma_f32 v[204:205], v[126:127], v[46:47], v[134:135]
	v_pk_fma_f32 v[202:203], v[60:61], v[116:117], v[202:203]
	v_pk_fma_f32 v[204:205], v[62:63], v[118:119], v[204:205]
	v_pk_fma_f32 v[202:203], v[28:29], v[128:129], v[202:203]
	v_pk_fma_f32 v[204:205], v[30:31], v[130:131], v[204:205]
	v_pk_fma_f32 v[206:207], v[164:165], v[36:37], v[182:183]
	v_pk_fma_f32 v[208:209], v[166:167], v[38:39], v[184:185]
	v_pk_fma_f32 v[206:207], v[52:53], v[160:161], v[206:207]
	v_pk_fma_f32 v[208:209], v[54:55], v[162:163], v[208:209]
	v_pk_fma_f32 v[206:207], v[20:21], v[178:179], v[206:207]
	v_pk_fma_f32 v[208:209], v[22:23], v[180:181], v[208:209]
	v_pk_mul_f32 v[210:211], v[202:203], s[76:77]
	v_pk_mul_f32 v[212:213], v[204:205], s[76:77]
	v_exp_f32_e32 v210, v210
	v_exp_f32_e32 v211, v211
	v_exp_f32_e32 v212, v212
	v_exp_f32_e32 v213, v213
	v_pk_add_f32 v[210:211], v[210:211], s[78:79]
	v_pk_add_f32 v[212:213], v[212:213], s[78:79]
	v_rcp_f32_e32 v210, v210
	v_rcp_f32_e32 v211, v211
	v_rcp_f32_e32 v212, v212
	v_rcp_f32_e32 v213, v213
	v_pk_mul_f32 v[202:203], v[202:203], v[210:211]
	v_pk_mul_f32 v[204:205], v[204:205], v[212:213]
	v_pk_mul_f32 v[202:203], v[202:203], v[206:207]
	v_pk_mul_f32 v[204:205], v[204:205], v[208:209]
	v_cvt_pk_bf16_f32 v246, v202, v203
	v_cvt_pk_bf16_f32 v247, v204, v205
	v_pk_fma_f32 v[202:203], v[124:125], v[28:29], v[132:133]
	v_pk_fma_f32 v[204:205], v[126:127], v[30:31], v[134:135]
	v_pk_fma_f32 v[202:203], v[44:45], v[116:117], v[202:203]
	v_pk_fma_f32 v[204:205], v[46:47], v[118:119], v[204:205]
	v_pk_fma_f32 v[202:203], v[12:13], v[128:129], v[202:203]
	v_pk_fma_f32 v[204:205], v[14:15], v[130:131], v[204:205]
	v_pk_fma_f32 v[206:207], v[164:165], v[20:21], v[182:183]
	v_pk_fma_f32 v[208:209], v[166:167], v[22:23], v[184:185]
	v_pk_fma_f32 v[206:207], v[36:37], v[160:161], v[206:207]
	v_pk_fma_f32 v[208:209], v[38:39], v[162:163], v[208:209]
	v_pk_fma_f32 v[206:207], v[4:5], v[178:179], v[206:207]
	v_pk_fma_f32 v[208:209], v[6:7], v[180:181], v[208:209]
	v_pk_mul_f32 v[210:211], v[202:203], s[76:77]
	v_pk_mul_f32 v[212:213], v[204:205], s[76:77]
	v_exp_f32_e32 v210, v210
	v_exp_f32_e32 v211, v211
	v_exp_f32_e32 v212, v212
	v_exp_f32_e32 v213, v213
	v_pk_add_f32 v[210:211], v[210:211], s[78:79]
	v_pk_add_f32 v[212:213], v[212:213], s[78:79]
	v_rcp_f32_e32 v210, v210
	v_rcp_f32_e32 v211, v211
	v_rcp_f32_e32 v212, v212
	v_rcp_f32_e32 v213, v213
	v_pk_mul_f32 v[202:203], v[202:203], v[210:211]
	v_pk_mul_f32 v[204:205], v[204:205], v[212:213]
	v_pk_mul_f32 v[202:203], v[202:203], v[206:207]
	v_pk_mul_f32 v[204:205], v[204:205], v[208:209]
	v_cvt_pk_bf16_f32 v248, v202, v203
	v_cvt_pk_bf16_f32 v249, v204, v205
	v_pk_fma_f32 v[202:203], v[124:125], v[12:13], v[132:133]
	v_pk_fma_f32 v[204:205], v[126:127], v[14:15], v[134:135]
	v_pk_fma_f32 v[202:203], v[28:29], v[116:117], v[202:203]
	v_pk_fma_f32 v[204:205], v[30:31], v[118:119], v[204:205]
	v_fmac_f32_dpp v202, v60, v128 row_shl:1 row_mask:0xf bank_mask:0xf
	v_fmac_f32_dpp v203, v61, v129 row_shl:1 row_mask:0xf bank_mask:0xf
	v_fmac_f32_dpp v204, v62, v130 row_shl:1 row_mask:0xf bank_mask:0xf
	v_fmac_f32_dpp v205, v63, v131 row_shl:1 row_mask:0xf bank_mask:0xf
	v_pk_fma_f32 v[202:203], v[194:195], v[222:223], v[202:203]
	v_pk_fma_f32 v[204:205], v[196:197], v[224:225], v[204:205]
	v_pk_fma_f32 v[206:207], v[164:165], v[4:5], v[182:183]
	v_pk_fma_f32 v[208:209], v[166:167], v[6:7], v[184:185]
	v_pk_fma_f32 v[206:207], v[20:21], v[160:161], v[206:207]
	v_pk_fma_f32 v[208:209], v[22:23], v[162:163], v[208:209]
	v_fmac_f32_dpp v206, v52, v178 row_shl:1 row_mask:0xf bank_mask:0xf
	v_fmac_f32_dpp v207, v53, v179 row_shl:1 row_mask:0xf bank_mask:0xf
	v_fmac_f32_dpp v208, v54, v180 row_shl:1 row_mask:0xf bank_mask:0xf
	v_fmac_f32_dpp v209, v55, v181 row_shl:1 row_mask:0xf bank_mask:0xf
	v_pk_fma_f32 v[206:207], v[198:199], v[232:233], v[206:207]
	v_pk_fma_f32 v[208:209], v[200:201], v[234:235], v[208:209]
	v_pk_mul_f32 v[210:211], v[202:203], s[76:77]
	v_pk_mul_f32 v[212:213], v[204:205], s[76:77]
	v_exp_f32_e32 v210, v210
	v_exp_f32_e32 v211, v211
	v_exp_f32_e32 v212, v212
	v_exp_f32_e32 v213, v213
	v_pk_add_f32 v[210:211], v[210:211], s[78:79]
	v_pk_add_f32 v[212:213], v[212:213], s[78:79]
	v_rcp_f32_e32 v210, v210
	v_rcp_f32_e32 v211, v211
	v_rcp_f32_e32 v212, v212
	v_rcp_f32_e32 v213, v213
	v_pk_mul_f32 v[202:203], v[202:203], v[210:211]
	v_pk_mul_f32 v[204:205], v[204:205], v[212:213]
	v_pk_mul_f32 v[202:203], v[202:203], v[206:207]
	v_pk_mul_f32 v[204:205], v[204:205], v[208:209]
	v_cvt_pk_bf16_f32 v250, v202, v203
	v_cvt_pk_bf16_f32 v251, v204, v205
	ds_read_b128 v[116:119], v177 offset:2064
	ds_read_b128 v[124:127], v177 offset:2576
	ds_read_b128 v[128:131], v177 offset:4112
	ds_read_b128 v[132:135], v177 offset:5136
	ds_read_b128 v[160:163], v177 offset:3088
	ds_read_b128 v[164:167], v177 offset:3600
	ds_read_b128 v[178:181], v177 offset:4624
	ds_read_b128 v[182:185], v177 offset:5648
	v_mov_b32_e32 v140, v236
	v_mov_b32_e32 v141, v237
	v_mov_b32_e32 v108, v238
	v_mov_b32_e32 v109, v239
	v_mov_b32_e32 v92, v240
	v_mov_b32_e32 v93, v241
	v_mov_b32_e32 v76, v242
	v_mov_b32_e32 v77, v243
	v_mov_b32_e32 v60, v244
	v_mov_b32_e32 v61, v245
	v_mov_b32_e32 v44, v246
	v_mov_b32_e32 v45, v247
	v_mov_b32_e32 v28, v248
	v_mov_b32_e32 v29, v249
	v_mov_b32_e32 v12, v250
	v_mov_b32_e32 v13, v251
	ds_read_b128 v[186:189], v231 offset:16
	ds_read_b128 v[190:193], v231 offset:528
	ds_read_b128 v[194:197], v231 offset:2064
	ds_read_b128 v[198:201], v231 offset:2576
	s_waitcnt lgkmcnt(4)
	v_cndmask_b32_e64 v218, 0, v116, s[2:3]
	v_cndmask_b32_e64 v222, 0, v128, s[28:29]
	v_cndmask_b32_e64 v219, 0, v117, s[2:3]
	v_cndmask_b32_e64 v223, 0, v129, s[28:29]
	v_cndmask_b32_e64 v220, 0, v118, s[2:3]
	v_cndmask_b32_e64 v224, 0, v130, s[28:29]
	v_cndmask_b32_e64 v221, 0, v119, s[2:3]
	v_cndmask_b32_e64 v225, 0, v131, s[28:29]
	v_cndmask_b32_e64 v226, 0, v160, s[2:3]
	v_cndmask_b32_e64 v232, 0, v178, s[28:29]
	v_cndmask_b32_e64 v227, 0, v161, s[2:3]
	v_cndmask_b32_e64 v233, 0, v179, s[28:29]
	v_cndmask_b32_e64 v228, 0, v162, s[2:3]
	v_cndmask_b32_e64 v234, 0, v180, s[28:29]
	v_cndmask_b32_e64 v229, 0, v163, s[2:3]
	v_cndmask_b32_e64 v235, 0, v181, s[28:29]
	s_waitcnt lgkmcnt(0)
	s_nop 1
	v_pk_fma_f32 v[202:203], v[124:125], v[136:137], v[132:133]
	v_pk_fma_f32 v[204:205], v[126:127], v[138:139], v[134:135]
	v_fmac_f32_dpp v202, v72, v116 row_shr:1 row_mask:0xf bank_mask:0xf
	v_fmac_f32_dpp v203, v73, v117 row_shr:1 row_mask:0xf bank_mask:0xf
	v_fmac_f32_dpp v204, v74, v118 row_shr:1 row_mask:0xf bank_mask:0xf
	v_fmac_f32_dpp v205, v75, v119 row_shr:1 row_mask:0xf bank_mask:0xf
	v_pk_fma_f32 v[202:203], v[186:187], v[218:219], v[202:203]
	v_pk_fma_f32 v[204:205], v[188:189], v[220:221], v[204:205]
	v_pk_fma_f32 v[202:203], v[104:105], v[128:129], v[202:203]
	v_pk_fma_f32 v[204:205], v[106:107], v[130:131], v[204:205]
	v_pk_fma_f32 v[206:207], v[164:165], v[112:113], v[182:183]
	v_pk_fma_f32 v[208:209], v[166:167], v[114:115], v[184:185]
	v_fmac_f32_dpp v206, v64, v160 row_shr:1 row_mask:0xf bank_mask:0xf
	v_fmac_f32_dpp v207, v65, v161 row_shr:1 row_mask:0xf bank_mask:0xf
	v_fmac_f32_dpp v208, v66, v162 row_shr:1 row_mask:0xf bank_mask:0xf
	v_fmac_f32_dpp v209, v67, v163 row_shr:1 row_mask:0xf bank_mask:0xf
	v_pk_fma_f32 v[206:207], v[190:191], v[226:227], v[206:207]
	v_pk_fma_f32 v[208:209], v[192:193], v[228:229], v[208:209]
	v_pk_fma_f32 v[206:207], v[96:97], v[178:179], v[206:207]
	v_pk_fma_f32 v[208:209], v[98:99], v[180:181], v[208:209]
	v_pk_mul_f32 v[210:211], v[202:203], s[76:77]
	v_pk_mul_f32 v[212:213], v[204:205], s[76:77]
	v_exp_f32_e32 v210, v210
	v_exp_f32_e32 v211, v211
	v_exp_f32_e32 v212, v212
	v_exp_f32_e32 v213, v213
	v_pk_add_f32 v[210:211], v[210:211], s[78:79]
	v_pk_add_f32 v[212:213], v[212:213], s[78:79]
	v_rcp_f32_e32 v210, v210
	v_rcp_f32_e32 v211, v211
	v_rcp_f32_e32 v212, v212
	v_rcp_f32_e32 v213, v213
	v_pk_mul_f32 v[202:203], v[202:203], v[210:211]
	v_pk_mul_f32 v[204:205], v[204:205], v[212:213]
	v_pk_mul_f32 v[202:203], v[202:203], v[206:207]
	v_pk_mul_f32 v[204:205], v[204:205], v[208:209]
	v_cvt_pk_bf16_f32 v142, v202, v203
	v_cvt_pk_bf16_f32 v143, v204, v205
	v_pk_fma_f32 v[202:203], v[124:125], v[104:105], v[132:133]
	v_pk_fma_f32 v[204:205], v[126:127], v[106:107], v[134:135]
	v_pk_fma_f32 v[202:203], v[136:137], v[116:117], v[202:203]
	v_pk_fma_f32 v[204:205], v[138:139], v[118:119], v[204:205]
	v_pk_fma_f32 v[202:203], v[88:89], v[128:129], v[202:203]
	v_pk_fma_f32 v[204:205], v[90:91], v[130:131], v[204:205]
	v_pk_fma_f32 v[206:207], v[164:165], v[96:97], v[182:183]
	v_pk_fma_f32 v[208:209], v[166:167], v[98:99], v[184:185]
	v_pk_fma_f32 v[206:207], v[112:113], v[160:161], v[206:207]
	v_pk_fma_f32 v[208:209], v[114:115], v[162:163], v[208:209]
	v_pk_fma_f32 v[206:207], v[80:81], v[178:179], v[206:207]
	v_pk_fma_f32 v[208:209], v[82:83], v[180:181], v[208:209]
	v_pk_mul_f32 v[210:211], v[202:203], s[76:77]
	v_pk_mul_f32 v[212:213], v[204:205], s[76:77]
	v_exp_f32_e32 v210, v210
	v_exp_f32_e32 v211, v211
	v_exp_f32_e32 v212, v212
	v_exp_f32_e32 v213, v213
	v_pk_add_f32 v[210:211], v[210:211], s[78:79]
	v_pk_add_f32 v[212:213], v[212:213], s[78:79]
	v_rcp_f32_e32 v210, v210
	v_rcp_f32_e32 v211, v211
	v_rcp_f32_e32 v212, v212
	v_rcp_f32_e32 v213, v213
	v_pk_mul_f32 v[202:203], v[202:203], v[210:211]
	v_pk_mul_f32 v[204:205], v[204:205], v[212:213]
	v_pk_mul_f32 v[202:203], v[202:203], v[206:207]
	v_pk_mul_f32 v[204:205], v[204:205], v[208:209]
	v_cvt_pk_bf16_f32 v110, v202, v203
	v_cvt_pk_bf16_f32 v111, v204, v205
	v_pk_fma_f32 v[202:203], v[124:125], v[88:89], v[132:133]
	v_pk_fma_f32 v[204:205], v[126:127], v[90:91], v[134:135]
	v_pk_fma_f32 v[202:203], v[104:105], v[116:117], v[202:203]
	v_pk_fma_f32 v[204:205], v[106:107], v[118:119], v[204:205]
	v_pk_fma_f32 v[202:203], v[72:73], v[128:129], v[202:203]
	v_pk_fma_f32 v[204:205], v[74:75], v[130:131], v[204:205]
	v_pk_fma_f32 v[206:207], v[164:165], v[80:81], v[182:183]
	v_pk_fma_f32 v[208:209], v[166:167], v[82:83], v[184:185]
	v_pk_fma_f32 v[206:207], v[96:97], v[160:161], v[206:207]
	v_pk_fma_f32 v[208:209], v[98:99], v[162:163], v[208:209]
	v_pk_fma_f32 v[206:207], v[64:65], v[178:179], v[206:207]
	v_pk_fma_f32 v[208:209], v[66:67], v[180:181], v[208:209]
	v_pk_mul_f32 v[210:211], v[202:203], s[76:77]
	v_pk_mul_f32 v[212:213], v[204:205], s[76:77]
	v_exp_f32_e32 v210, v210
	v_exp_f32_e32 v211, v211
	v_exp_f32_e32 v212, v212
	v_exp_f32_e32 v213, v213
	v_pk_add_f32 v[210:211], v[210:211], s[78:79]
	v_pk_add_f32 v[212:213], v[212:213], s[78:79]
	v_rcp_f32_e32 v210, v210
	v_rcp_f32_e32 v211, v211
	v_rcp_f32_e32 v212, v212
	v_rcp_f32_e32 v213, v213
	v_pk_mul_f32 v[202:203], v[202:203], v[210:211]
	v_pk_mul_f32 v[204:205], v[204:205], v[212:213]
	v_pk_mul_f32 v[202:203], v[202:203], v[206:207]
	v_pk_mul_f32 v[204:205], v[204:205], v[208:209]
	v_cvt_pk_bf16_f32 v94, v202, v203
	v_cvt_pk_bf16_f32 v95, v204, v205
	v_pk_fma_f32 v[202:203], v[124:125], v[72:73], v[132:133]
	v_pk_fma_f32 v[204:205], v[126:127], v[74:75], v[134:135]
	v_pk_fma_f32 v[202:203], v[88:89], v[116:117], v[202:203]
	v_pk_fma_f32 v[204:205], v[90:91], v[118:119], v[204:205]
	v_fmac_f32_dpp v202, v136, v128 row_shl:1 row_mask:0xf bank_mask:0xf
	v_fmac_f32_dpp v203, v137, v129 row_shl:1 row_mask:0xf bank_mask:0xf
	v_fmac_f32_dpp v204, v138, v130 row_shl:1 row_mask:0xf bank_mask:0xf
	v_fmac_f32_dpp v205, v139, v131 row_shl:1 row_mask:0xf bank_mask:0xf
	v_pk_fma_f32 v[202:203], v[186:187], v[222:223], v[202:203]
	v_pk_fma_f32 v[204:205], v[188:189], v[224:225], v[204:205]
	v_pk_fma_f32 v[206:207], v[164:165], v[64:65], v[182:183]
	v_pk_fma_f32 v[208:209], v[166:167], v[66:67], v[184:185]
	v_pk_fma_f32 v[206:207], v[80:81], v[160:161], v[206:207]
	v_pk_fma_f32 v[208:209], v[82:83], v[162:163], v[208:209]
	v_fmac_f32_dpp v206, v112, v178 row_shl:1 row_mask:0xf bank_mask:0xf
	v_fmac_f32_dpp v207, v113, v179 row_shl:1 row_mask:0xf bank_mask:0xf
	v_fmac_f32_dpp v208, v114, v180 row_shl:1 row_mask:0xf bank_mask:0xf
	v_fmac_f32_dpp v209, v115, v181 row_shl:1 row_mask:0xf bank_mask:0xf
	v_pk_fma_f32 v[206:207], v[190:191], v[232:233], v[206:207]
	v_pk_fma_f32 v[208:209], v[192:193], v[234:235], v[208:209]
	v_pk_mul_f32 v[210:211], v[202:203], s[76:77]
	v_pk_mul_f32 v[212:213], v[204:205], s[76:77]
	v_exp_f32_e32 v210, v210
	v_exp_f32_e32 v211, v211
	v_exp_f32_e32 v212, v212
	v_exp_f32_e32 v213, v213
	v_pk_add_f32 v[210:211], v[210:211], s[78:79]
	v_pk_add_f32 v[212:213], v[212:213], s[78:79]
	v_rcp_f32_e32 v210, v210
	v_rcp_f32_e32 v211, v211
	v_rcp_f32_e32 v212, v212
	v_rcp_f32_e32 v213, v213
	v_pk_mul_f32 v[202:203], v[202:203], v[210:211]
	v_pk_mul_f32 v[204:205], v[204:205], v[212:213]
	v_pk_mul_f32 v[202:203], v[202:203], v[206:207]
	v_pk_mul_f32 v[204:205], v[204:205], v[208:209]
	v_cvt_pk_bf16_f32 v78, v202, v203
	v_cvt_pk_bf16_f32 v79, v204, v205
	v_pk_fma_f32 v[202:203], v[124:125], v[56:57], v[132:133]
	v_pk_fma_f32 v[204:205], v[126:127], v[58:59], v[134:135]
	v_fmac_f32_dpp v202, v8, v116 row_shr:1 row_mask:0xf bank_mask:0xf
	v_fmac_f32_dpp v203, v9, v117 row_shr:1 row_mask:0xf bank_mask:0xf
	v_fmac_f32_dpp v204, v10, v118 row_shr:1 row_mask:0xf bank_mask:0xf
	v_fmac_f32_dpp v205, v11, v119 row_shr:1 row_mask:0xf bank_mask:0xf
	v_pk_fma_f32 v[202:203], v[194:195], v[218:219], v[202:203]
	v_pk_fma_f32 v[204:205], v[196:197], v[220:221], v[204:205]
	v_pk_fma_f32 v[202:203], v[40:41], v[128:129], v[202:203]
	v_pk_fma_f32 v[204:205], v[42:43], v[130:131], v[204:205]
	v_pk_fma_f32 v[206:207], v[164:165], v[48:49], v[182:183]
	v_pk_fma_f32 v[208:209], v[166:167], v[50:51], v[184:185]
	v_fmac_f32_dpp v206, v0, v160 row_shr:1 row_mask:0xf bank_mask:0xf
	v_fmac_f32_dpp v207, v1, v161 row_shr:1 row_mask:0xf bank_mask:0xf
	v_fmac_f32_dpp v208, v2, v162 row_shr:1 row_mask:0xf bank_mask:0xf
	v_fmac_f32_dpp v209, v3, v163 row_shr:1 row_mask:0xf bank_mask:0xf
	v_pk_fma_f32 v[206:207], v[198:199], v[226:227], v[206:207]
	v_pk_fma_f32 v[208:209], v[200:201], v[228:229], v[208:209]
	v_pk_fma_f32 v[206:207], v[32:33], v[178:179], v[206:207]
	v_pk_fma_f32 v[208:209], v[34:35], v[180:181], v[208:209]
	v_pk_mul_f32 v[210:211], v[202:203], s[76:77]
	v_pk_mul_f32 v[212:213], v[204:205], s[76:77]
	v_exp_f32_e32 v210, v210
	v_exp_f32_e32 v211, v211
	v_exp_f32_e32 v212, v212
	v_exp_f32_e32 v213, v213
	v_pk_add_f32 v[210:211], v[210:211], s[78:79]
	v_pk_add_f32 v[212:213], v[212:213], s[78:79]
	v_rcp_f32_e32 v210, v210
	v_rcp_f32_e32 v211, v211
	v_rcp_f32_e32 v212, v212
	v_rcp_f32_e32 v213, v213
	v_pk_mul_f32 v[202:203], v[202:203], v[210:211]
	v_pk_mul_f32 v[204:205], v[204:205], v[212:213]
	v_pk_mul_f32 v[202:203], v[202:203], v[206:207]
	v_pk_mul_f32 v[204:205], v[204:205], v[208:209]
	v_cvt_pk_bf16_f32 v62, v202, v203
	v_cvt_pk_bf16_f32 v63, v204, v205
	v_pk_fma_f32 v[202:203], v[124:125], v[40:41], v[132:133]
	v_pk_fma_f32 v[204:205], v[126:127], v[42:43], v[134:135]
	v_pk_fma_f32 v[202:203], v[56:57], v[116:117], v[202:203]
	v_pk_fma_f32 v[204:205], v[58:59], v[118:119], v[204:205]
	v_pk_fma_f32 v[202:203], v[24:25], v[128:129], v[202:203]
	v_pk_fma_f32 v[204:205], v[26:27], v[130:131], v[204:205]
	v_pk_fma_f32 v[206:207], v[164:165], v[32:33], v[182:183]
	v_pk_fma_f32 v[208:209], v[166:167], v[34:35], v[184:185]
	v_pk_fma_f32 v[206:207], v[48:49], v[160:161], v[206:207]
	v_pk_fma_f32 v[208:209], v[50:51], v[162:163], v[208:209]
	v_pk_fma_f32 v[206:207], v[16:17], v[178:179], v[206:207]
	v_pk_fma_f32 v[208:209], v[18:19], v[180:181], v[208:209]
	v_pk_mul_f32 v[210:211], v[202:203], s[76:77]
	v_pk_mul_f32 v[212:213], v[204:205], s[76:77]
	v_exp_f32_e32 v210, v210
	v_exp_f32_e32 v211, v211
	v_exp_f32_e32 v212, v212
	v_exp_f32_e32 v213, v213
	v_pk_add_f32 v[210:211], v[210:211], s[78:79]
	v_pk_add_f32 v[212:213], v[212:213], s[78:79]
	v_rcp_f32_e32 v210, v210
	v_rcp_f32_e32 v211, v211
	v_rcp_f32_e32 v212, v212
	v_rcp_f32_e32 v213, v213
	v_pk_mul_f32 v[202:203], v[202:203], v[210:211]
	v_pk_mul_f32 v[204:205], v[204:205], v[212:213]
	v_pk_mul_f32 v[202:203], v[202:203], v[206:207]
	v_pk_mul_f32 v[204:205], v[204:205], v[208:209]
	v_cvt_pk_bf16_f32 v46, v202, v203
	v_cvt_pk_bf16_f32 v47, v204, v205
	v_pk_fma_f32 v[202:203], v[124:125], v[24:25], v[132:133]
	v_pk_fma_f32 v[204:205], v[126:127], v[26:27], v[134:135]
	v_pk_fma_f32 v[202:203], v[40:41], v[116:117], v[202:203]
	v_pk_fma_f32 v[204:205], v[42:43], v[118:119], v[204:205]
	v_pk_fma_f32 v[202:203], v[8:9], v[128:129], v[202:203]
	v_pk_fma_f32 v[204:205], v[10:11], v[130:131], v[204:205]
	v_pk_fma_f32 v[206:207], v[164:165], v[16:17], v[182:183]
	v_pk_fma_f32 v[208:209], v[166:167], v[18:19], v[184:185]
	v_pk_fma_f32 v[206:207], v[32:33], v[160:161], v[206:207]
	v_pk_fma_f32 v[208:209], v[34:35], v[162:163], v[208:209]
	v_pk_fma_f32 v[206:207], v[0:1], v[178:179], v[206:207]
	v_pk_fma_f32 v[208:209], v[2:3], v[180:181], v[208:209]
	v_pk_mul_f32 v[210:211], v[202:203], s[76:77]
	v_pk_mul_f32 v[212:213], v[204:205], s[76:77]
	v_exp_f32_e32 v210, v210
	v_exp_f32_e32 v211, v211
	v_exp_f32_e32 v212, v212
	v_exp_f32_e32 v213, v213
	v_pk_add_f32 v[210:211], v[210:211], s[78:79]
	v_pk_add_f32 v[212:213], v[212:213], s[78:79]
	v_rcp_f32_e32 v210, v210
	v_rcp_f32_e32 v211, v211
	v_rcp_f32_e32 v212, v212
	v_rcp_f32_e32 v213, v213
	v_pk_mul_f32 v[202:203], v[202:203], v[210:211]
	v_pk_mul_f32 v[204:205], v[204:205], v[212:213]
	v_pk_mul_f32 v[202:203], v[202:203], v[206:207]
	v_pk_mul_f32 v[204:205], v[204:205], v[208:209]
	v_cvt_pk_bf16_f32 v30, v202, v203
	v_cvt_pk_bf16_f32 v31, v204, v205
	v_pk_fma_f32 v[202:203], v[124:125], v[8:9], v[132:133]
	v_pk_fma_f32 v[204:205], v[126:127], v[10:11], v[134:135]
	v_pk_fma_f32 v[202:203], v[24:25], v[116:117], v[202:203]
	v_pk_fma_f32 v[204:205], v[26:27], v[118:119], v[204:205]
	v_fmac_f32_dpp v202, v56, v128 row_shl:1 row_mask:0xf bank_mask:0xf
	v_fmac_f32_dpp v203, v57, v129 row_shl:1 row_mask:0xf bank_mask:0xf
	v_fmac_f32_dpp v204, v58, v130 row_shl:1 row_mask:0xf bank_mask:0xf
	v_fmac_f32_dpp v205, v59, v131 row_shl:1 row_mask:0xf bank_mask:0xf
	v_pk_fma_f32 v[202:203], v[194:195], v[222:223], v[202:203]
	v_pk_fma_f32 v[204:205], v[196:197], v[224:225], v[204:205]
	v_pk_fma_f32 v[206:207], v[164:165], v[0:1], v[182:183]
	v_pk_fma_f32 v[208:209], v[166:167], v[2:3], v[184:185]
	v_pk_fma_f32 v[206:207], v[16:17], v[160:161], v[206:207]
	v_pk_fma_f32 v[208:209], v[18:19], v[162:163], v[208:209]
	v_fmac_f32_dpp v206, v48, v178 row_shl:1 row_mask:0xf bank_mask:0xf
	v_fmac_f32_dpp v207, v49, v179 row_shl:1 row_mask:0xf bank_mask:0xf
	v_fmac_f32_dpp v208, v50, v180 row_shl:1 row_mask:0xf bank_mask:0xf
	v_fmac_f32_dpp v209, v51, v181 row_shl:1 row_mask:0xf bank_mask:0xf
	v_pk_fma_f32 v[206:207], v[198:199], v[232:233], v[206:207]
	v_pk_fma_f32 v[208:209], v[200:201], v[234:235], v[208:209]
	v_pk_mul_f32 v[210:211], v[202:203], s[76:77]
	v_pk_mul_f32 v[212:213], v[204:205], s[76:77]
	v_exp_f32_e32 v210, v210
	v_exp_f32_e32 v211, v211
	v_exp_f32_e32 v212, v212
	v_exp_f32_e32 v213, v213
	v_pk_add_f32 v[210:211], v[210:211], s[78:79]
	v_pk_add_f32 v[212:213], v[212:213], s[78:79]
	v_rcp_f32_e32 v210, v210
	v_rcp_f32_e32 v211, v211
	v_rcp_f32_e32 v212, v212
	v_rcp_f32_e32 v213, v213
	v_pk_mul_f32 v[202:203], v[202:203], v[210:211]
	v_pk_mul_f32 v[204:205], v[204:205], v[212:213]
	v_pk_mul_f32 v[202:203], v[202:203], v[206:207]
	v_pk_mul_f32 v[204:205], v[204:205], v[208:209]
	v_cvt_pk_bf16_f32 v14, v202, v203
	v_cvt_pk_bf16_f32 v15, v204, v205
	global_store_dwordx4 v168, v[140:143], s[4:5]
	v_add_u32_e32 v250, 0x1600, v168
	global_store_dwordx4 v250, v[108:111], s[4:5]
	s_nop 0
	v_add_u32_e32 v250, 0x2c00, v168
	global_store_dwordx4 v250, v[92:95], s[4:5]
	s_nop 0
	v_add_u32_e32 v250, 0x4200, v168
	global_store_dwordx4 v250, v[76:79], s[4:5]
	s_nop 0
	v_add_u32_e32 v250, 0xb0000, v168
	global_store_dwordx4 v250, v[60:63], s[4:5]
	s_nop 0
	v_add_u32_e32 v250, 0xb1600, v168
	global_store_dwordx4 v250, v[44:47], s[4:5]
	s_nop 0
	v_add_u32_e32 v250, 0xb2c00, v168
	global_store_dwordx4 v250, v[28:31], s[4:5]
	s_nop 0
	v_add_u32_e32 v250, 0xb4200, v168
	global_store_dwordx4 v250, v[12:15], s[4:5]
	s_nop 0
	s_and_b64 s[2:3], s[6:7], exec
	s_cbranch_scc0 .LepB_nonext
	s_xor_b32 s101, s101, 1
	s_or_b32 s101, s101, 2
	s_and_b32 s57, s101, 1
	s_mulk_i32 s57, 0x1800
	s_add_i32 s57, s57, 0x22c00
	v_readfirstlane_b32 s67, v230
	s_cmp_lt_u32 s67, 64
	s_cbranch_scc0 .LepB_nfe
	s_add_i32 s4, s56, -32
	s_ashr_i32 s4, s4, 2
	s_add_i32 s4, s4, 1
	s_cmp_gt_i32 s56, 31
	s_cselect_b32 s4, s4, 0
	s_mul_hi_i32 s5, s4, 0x5800
	s_mulk_i32 s4, 0x5800
	v_readlane_b32 s67, v254, 49
	v_readlane_b32 s95, v254, 50
	s_nop 0
	s_add_u32 s4, s67, s4
	s_addc_u32 s5, s95, s5
	v_readlane_b32 s2, v254, 5
	v_readlane_b32 s3, v254, 6
	v_readlane_b32 s28, v254, 7
	v_readlane_b32 s29, v254, 8
	s_nop 0
	v_and_b32_e32 v238, 63, v230
	v_lshrrev_b32_e32 v239, 5, v238
	v_and_b32_e32 v240, 31, v238
	v_lshlrev_b32_e32 v240, 4, v240
	s_lshl_b32 s67, s54, 9
	v_add_u32_e32 v240, s67, v240
	v_mul_u32_u24_e32 v241, 0x2c00, v239
	v_mul_u32_u24_e32 v242, 0x5800, v239
	v_add_u32_e32 v241, v241, v240
	v_add_u32_e32 v242, v242, v240
	v_lshlrev_b32_e32 v243, 4, v238
	s_lshl_b32 s67, s56, 10
	v_add_u32_e32 v243, s67, v243
	s_mov_b32 m0, s57
	s_nop 0
	global_load_lds_dwordx4 v243, s[10:11]
	s_add_i32 m0, s57, 1024
	s_nop 0
	global_load_lds_dwordx4 v241, s[4:5]
	s_add_i32 m0, s57, 2048
	s_nop 0
	global_load_lds_dwordx4 v242, s[2:3]
	v_add_u32_e32 v243, 0x2c00, v242
	s_add_i32 m0, s57, 3072
	s_nop 0
	global_load_lds_dwordx4 v243, s[2:3]
	v_add_u32_e32 v243, 0xb000, v241
	s_add_i32 m0, s57, 4096
	s_nop 0
	global_load_lds_dwordx4 v243, s[2:3]
	s_add_i32 m0, s57, 5120
	s_nop 0
	global_load_lds_dwordx4 v241, s[28:29]

.LepD_fast:
	s_mov_b32 s90, 0xbfb8aa3b
	s_mov_b32 s91, 0xbfb8aa3b
	s_mov_b32 s92, 1.0
	s_mov_b32 s93, 1.0
	s_and_b32 s32, s10, 1
	v_and_b32_e32 v237, 15, v170
	v_and_b32_e32 v236, 64, v170
	v_lshl_add_u32 v236, v237, 2, v236
	v_mul_u32_u24_e32 v168, 0x1600, v236
	v_lshl_add_u32 v168, v172, 1, v168
	v_lshl_add_u32 v236, v236, 2, s55
	v_lshl_add_u32 v177, v172, 2, s55
	ds_read_b128 v[210:213], v236
	ds_read_b128 v[214:217], v236 offset:512
	ds_read_b128 v[202:205], v177 offset:1024
	ds_read_b128 v[206:209], v177 offset:1040
	ds_read_b128 v[218:221], v177 offset:1536
	ds_read_b128 v[222:225], v177 offset:1552
	ds_read_b128 v[116:119], v177 offset:2048
	ds_read_b128 v[124:127], v177 offset:2560
	ds_read_b128 v[128:131], v177 offset:4096
	ds_read_b128 v[132:135], v177 offset:5120
	ds_read_b128 v[160:163], v177 offset:3072
	ds_read_b128 v[164:167], v177 offset:3584
	ds_read_b128 v[178:181], v177 offset:4608
	ds_read_b128 v[182:185], v177 offset:5632
	s_mul_i32 s4, s88, 0x160000
	s_lshl_b32 s57, s66, 8
	s_add_i32 s4, s4, s57
	s_add_i32 s4, s4, 0xbf00000
	s_add_u32 s4, s4, s70
	s_addc_u32 s5, s71, 0
	s_mov_b32 s57, 0x20800
	v_lshl_add_u32 v169, v172, 2, s57
	v_cmp_eq_u32_e64 s[2:3], 0, v237
	v_cmp_eq_u32_e64 s[28:29], 15, v237
	v_and_b32_e32 v231, 8, v237
	v_lshlrev_b32_e32 v231, 9, v231
	s_lshl_b32 s57, s32, 10
	v_add3_u32 v231, v231, v169, s57
	s_waitcnt lgkmcnt(12)
	v_fmamk_f32 v210, v210, 0x3a800000, v176
	v_fmamk_f32 v211, v211, 0x3a800000, v176
	v_fmamk_f32 v212, v212, 0x3a800000, v176
	v_fmamk_f32 v213, v213, 0x3a800000, v176
	v_fmamk_f32 v214, v214, 0x3a800000, v176
	v_fmamk_f32 v215, v215, 0x3a800000, v176
	v_fmamk_f32 v216, v216, 0x3a800000, v176
	v_fmamk_f32 v217, v217, 0x3a800000, v176
	s_mov_b32 s57, 0x800000
	v_mul_f32_e32 v226, 0x4b800000, v210
	v_mul_f32_e32 v227, 0x4b800000, v211
	v_mul_f32_e32 v228, 0x4b800000, v212
	v_mul_f32_e32 v229, 0x4b800000, v213
	v_mul_f32_e32 v232, 0x4b800000, v214
	v_mul_f32_e32 v233, 0x4b800000, v215
	v_mul_f32_e32 v234, 0x4b800000, v216
	v_mul_f32_e32 v235, 0x4b800000, v217
	v_cmp_gt_f32_e32 vcc, s57, v210
	s_nop 1
	v_cndmask_b32_e32 v210, v210, v226, vcc
	v_rsq_f32_e32 v210, v210
	s_nop 0
	v_mul_f32_e32 v226, 0x45800000, v210
	v_cndmask_b32_e32 v210, v210, v226, vcc
	v_cmp_gt_f32_e32 vcc, s57, v211
	s_nop 1
	v_cndmask_b32_e32 v211, v211, v227, vcc
	v_rsq_f32_e32 v211, v211
	s_nop 0
	v_mul_f32_e32 v227, 0x45800000, v211
	v_cndmask_b32_e32 v211, v211, v227, vcc
	v_cmp_gt_f32_e32 vcc, s57, v212
	s_nop 1
	v_cndmask_b32_e32 v212, v212, v228, vcc
	v_rsq_f32_e32 v212, v212
	s_nop 0
	v_mul_f32_e32 v228, 0x45800000, v212
	v_cndmask_b32_e32 v212, v212, v228, vcc
	v_cmp_gt_f32_e32 vcc, s57, v213
	s_nop 1
	v_cndmask_b32_e32 v213, v213, v229, vcc
	v_rsq_f32_e32 v213, v213
	s_nop 0
	v_mul_f32_e32 v229, 0x45800000, v213
	v_cndmask_b32_e32 v213, v213, v229, vcc
	v_cmp_gt_f32_e32 vcc, s57, v214
	s_nop 1
	v_cndmask_b32_e32 v214, v214, v232, vcc
	v_rsq_f32_e32 v214, v214
	s_nop 0
	v_mul_f32_e32 v232, 0x45800000, v214
	v_cndmask_b32_e32 v214, v214, v232, vcc
	v_cmp_gt_f32_e32 vcc, s57, v215
	s_nop 1
	v_cndmask_b32_e32 v215, v215, v233, vcc
	v_rsq_f32_e32 v215, v215
	s_nop 0
	v_mul_f32_e32 v233, 0x45800000, v215
	v_cndmask_b32_e32 v215, v215, v233, vcc
	v_cmp_gt_f32_e32 vcc, s57, v216
	s_nop 1
	v_cndmask_b32_e32 v216, v216, v234, vcc
	v_rsq_f32_e32 v216, v216
	s_nop 0
	v_mul_f32_e32 v234, 0x45800000, v216
	v_cndmask_b32_e32 v216, v216, v234, vcc
	v_cmp_gt_f32_e32 vcc, s57, v217
	s_nop 1
	v_cndmask_b32_e32 v217, v217, v235, vcc
	v_rsq_f32_e32 v217, v217
	s_nop 0
	v_mul_f32_e32 v235, 0x45800000, v217
	v_cndmask_b32_e32 v217, v217, v235, vcc
	s_waitcnt lgkmcnt(8)
	v_pk_fma_f32 v[140:141], v[140:141], v[210:211], v[202:203] op_sel:[0,0,0] op_sel_hi:[1,0,1]
	v_pk_fma_f32 v[142:143], v[142:143], v[210:211], v[204:205] op_sel:[0,0,0] op_sel_hi:[1,0,1]
	v_pk_fma_f32 v[136:137], v[136:137], v[210:211], v[206:207] op_sel:[0,0,0] op_sel_hi:[1,0,1]
	v_pk_fma_f32 v[138:139], v[138:139], v[210:211], v[208:209] op_sel:[0,0,0] op_sel_hi:[1,0,1]
	v_pk_fma_f32 v[120:121], v[120:121], v[210:211], v[218:219] op_sel:[0,0,0] op_sel_hi:[1,0,1]
	v_pk_fma_f32 v[122:123], v[122:123], v[210:211], v[220:221] op_sel:[0,0,0] op_sel_hi:[1,0,1]
	v_pk_fma_f32 v[112:113], v[112:113], v[210:211], v[222:223] op_sel:[0,0,0] op_sel_hi:[1,0,1]
	v_pk_fma_f32 v[114:115], v[114:115], v[210:211], v[224:225] op_sel:[0,0,0] op_sel_hi:[1,0,1]
	v_pk_fma_f32 v[108:109], v[108:109], v[210:211], v[202:203] op_sel:[0,1,0] op_sel_hi:[1,1,1]
	v_pk_fma_f32 v[110:111], v[110:111], v[210:211], v[204:205] op_sel:[0,1,0] op_sel_hi:[1,1,1]
	v_pk_fma_f32 v[104:105], v[104:105], v[210:211], v[206:207] op_sel:[0,1,0] op_sel_hi:[1,1,1]
	v_pk_fma_f32 v[106:107], v[106:107], v[210:211], v[208:209] op_sel:[0,1,0] op_sel_hi:[1,1,1]
	v_pk_fma_f32 v[100:101], v[100:101], v[210:211], v[218:219] op_sel:[0,1,0] op_sel_hi:[1,1,1]
	v_pk_fma_f32 v[102:103], v[102:103], v[210:211], v[220:221] op_sel:[0,1,0] op_sel_hi:[1,1,1]
	v_pk_fma_f32 v[96:97], v[96:97], v[210:211], v[222:223] op_sel:[0,1,0] op_sel_hi:[1,1,1]
	v_pk_fma_f32 v[98:99], v[98:99], v[210:211], v[224:225] op_sel:[0,1,0] op_sel_hi:[1,1,1]
	v_pk_fma_f32 v[92:93], v[92:93], v[212:213], v[202:203] op_sel:[0,0,0] op_sel_hi:[1,0,1]
	v_pk_fma_f32 v[94:95], v[94:95], v[212:213], v[204:205] op_sel:[0,0,0] op_sel_hi:[1,0,1]
	v_pk_fma_f32 v[88:89], v[88:89], v[212:213], v[206:207] op_sel:[0,0,0] op_sel_hi:[1,0,1]
	v_pk_fma_f32 v[90:91], v[90:91], v[212:213], v[208:209] op_sel:[0,0,0] op_sel_hi:[1,0,1]
	v_pk_fma_f32 v[84:85], v[84:85], v[212:213], v[218:219] op_sel:[0,0,0] op_sel_hi:[1,0,1]
	v_pk_fma_f32 v[86:87], v[86:87], v[212:213], v[220:221] op_sel:[0,0,0] op_sel_hi:[1,0,1]
	v_pk_fma_f32 v[80:81], v[80:81], v[212:213], v[222:223] op_sel:[0,0,0] op_sel_hi:[1,0,1]
	v_pk_fma_f32 v[82:83], v[82:83], v[212:213], v[224:225] op_sel:[0,0,0] op_sel_hi:[1,0,1]
	v_pk_fma_f32 v[76:77], v[76:77], v[212:213], v[202:203] op_sel:[0,1,0] op_sel_hi:[1,1,1]
	v_pk_fma_f32 v[78:79], v[78:79], v[212:213], v[204:205] op_sel:[0,1,0] op_sel_hi:[1,1,1]
	v_pk_fma_f32 v[72:73], v[72:73], v[212:213], v[206:207] op_sel:[0,1,0] op_sel_hi:[1,1,1]
	v_pk_fma_f32 v[74:75], v[74:75], v[212:213], v[208:209] op_sel:[0,1,0] op_sel_hi:[1,1,1]
	v_pk_fma_f32 v[68:69], v[68:69], v[212:213], v[218:219] op_sel:[0,1,0] op_sel_hi:[1,1,1]
	v_pk_fma_f32 v[70:71], v[70:71], v[212:213], v[220:221] op_sel:[0,1,0] op_sel_hi:[1,1,1]
	v_pk_fma_f32 v[64:65], v[64:65], v[212:213], v[222:223] op_sel:[0,1,0] op_sel_hi:[1,1,1]
	v_pk_fma_f32 v[66:67], v[66:67], v[212:213], v[224:225] op_sel:[0,1,0] op_sel_hi:[1,1,1]
	v_pk_fma_f32 v[60:61], v[60:61], v[214:215], v[202:203] op_sel:[0,0,0] op_sel_hi:[1,0,1]
	v_pk_fma_f32 v[62:63], v[62:63], v[214:215], v[204:205] op_sel:[0,0,0] op_sel_hi:[1,0,1]
	v_pk_fma_f32 v[56:57], v[56:57], v[214:215], v[206:207] op_sel:[0,0,0] op_sel_hi:[1,0,1]
	v_pk_fma_f32 v[58:59], v[58:59], v[214:215], v[208:209] op_sel:[0,0,0] op_sel_hi:[1,0,1]
	v_pk_fma_f32 v[52:53], v[52:53], v[214:215], v[218:219] op_sel:[0,0,0] op_sel_hi:[1,0,1]
	v_pk_fma_f32 v[54:55], v[54:55], v[214:215], v[220:221] op_sel:[0,0,0] op_sel_hi:[1,0,1]
	v_pk_fma_f32 v[48:49], v[48:49], v[214:215], v[222:223] op_sel:[0,0,0] op_sel_hi:[1,0,1]
	v_pk_fma_f32 v[50:51], v[50:51], v[214:215], v[224:225] op_sel:[0,0,0] op_sel_hi:[1,0,1]
	v_pk_fma_f32 v[44:45], v[44:45], v[214:215], v[202:203] op_sel:[0,1,0] op_sel_hi:[1,1,1]
	v_pk_fma_f32 v[46:47], v[46:47], v[214:215], v[204:205] op_sel:[0,1,0] op_sel_hi:[1,1,1]
	v_pk_fma_f32 v[40:41], v[40:41], v[214:215], v[206:207] op_sel:[0,1,0] op_sel_hi:[1,1,1]
	v_pk_fma_f32 v[42:43], v[42:43], v[214:215], v[208:209] op_sel:[0,1,0] op_sel_hi:[1,1,1]
	v_pk_fma_f32 v[36:37], v[36:37], v[214:215], v[218:219] op_sel:[0,1,0] op_sel_hi:[1,1,1]
	v_pk_fma_f32 v[38:39], v[38:39], v[214:215], v[220:221] op_sel:[0,1,0] op_sel_hi:[1,1,1]
	v_pk_fma_f32 v[32:33], v[32:33], v[214:215], v[222:223] op_sel:[0,1,0] op_sel_hi:[1,1,1]
	v_pk_fma_f32 v[34:35], v[34:35], v[214:215], v[224:225] op_sel:[0,1,0] op_sel_hi:[1,1,1]
	v_pk_fma_f32 v[28:29], v[28:29], v[216:217], v[202:203] op_sel:[0,0,0] op_sel_hi:[1,0,1]
	v_pk_fma_f32 v[30:31], v[30:31], v[216:217], v[204:205] op_sel:[0,0,0] op_sel_hi:[1,0,1]
	v_pk_fma_f32 v[24:25], v[24:25], v[216:217], v[206:207] op_sel:[0,0,0] op_sel_hi:[1,0,1]
	v_pk_fma_f32 v[26:27], v[26:27], v[216:217], v[208:209] op_sel:[0,0,0] op_sel_hi:[1,0,1]
	v_pk_fma_f32 v[20:21], v[20:21], v[216:217], v[218:219] op_sel:[0,0,0] op_sel_hi:[1,0,1]
	v_pk_fma_f32 v[22:23], v[22:23], v[216:217], v[220:221] op_sel:[0,0,0] op_sel_hi:[1,0,1]
	v_pk_fma_f32 v[16:17], v[16:17], v[216:217], v[222:223] op_sel:[0,0,0] op_sel_hi:[1,0,1]
	v_pk_fma_f32 v[18:19], v[18:19], v[216:217], v[224:225] op_sel:[0,0,0] op_sel_hi:[1,0,1]
	v_pk_fma_f32 v[12:13], v[12:13], v[216:217], v[202:203] op_sel:[0,1,0] op_sel_hi:[1,1,1]
	v_pk_fma_f32 v[14:15], v[14:15], v[216:217], v[204:205] op_sel:[0,1,0] op_sel_hi:[1,1,1]
	v_pk_fma_f32 v[8:9], v[8:9], v[216:217], v[206:207] op_sel:[0,1,0] op_sel_hi:[1,1,1]
	v_pk_fma_f32 v[10:11], v[10:11], v[216:217], v[208:209] op_sel:[0,1,0] op_sel_hi:[1,1,1]
	v_pk_fma_f32 v[4:5], v[4:5], v[216:217], v[218:219] op_sel:[0,1,0] op_sel_hi:[1,1,1]
	v_pk_fma_f32 v[6:7], v[6:7], v[216:217], v[220:221] op_sel:[0,1,0] op_sel_hi:[1,1,1]
	v_pk_fma_f32 v[0:1], v[0:1], v[216:217], v[222:223] op_sel:[0,1,0] op_sel_hi:[1,1,1]
	v_pk_fma_f32 v[2:3], v[2:3], v[216:217], v[224:225] op_sel:[0,1,0] op_sel_hi:[1,1,1]
	v_mov_b32_e32 v214, 0
	v_mov_b32_e32 v215, 0
	v_mov_b32_e32 v216, 0
	v_mov_b32_e32 v217, 0
	s_lshl_b32 s67, s32, 12
	s_sub_i32 s67, 0x2000, s67
	s_mul_i32 s89, s32, 0x1400
	s_add_i32 s89, s89, 0xc00
	s_lshl_b32 s57, s32, 10
	s_add_i32 s100, s57, 5120
	s_add_i32 s98, s57, 1024
	s_mov_b64 exec, s[2:3]
	v_add_u32_e32 v250, s67, v169
	ds_write_b128 v250, v[140:143] offset:0
	ds_write_b128 v250, v[136:139] offset:16
	ds_write_b128 v250, v[120:123] offset:512
	ds_write_b128 v250, v[112:115] offset:528
	v_add_u32_e32 v250, s100, v169
	ds_write_b128 v250, v[60:63] offset:0
	ds_write_b128 v250, v[56:59] offset:16
	ds_write_b128 v250, v[52:55] offset:512
	ds_write_b128 v250, v[48:51] offset:528
	ds_write_b128 v169, v[214:217] offset:0
	ds_write_b128 v169, v[214:217] offset:16
	ds_write_b128 v169, v[214:217] offset:512
	ds_write_b128 v169, v[214:217] offset:528
	s_mov_b64 exec, s[28:29]
	v_add_u32_e32 v251, s98, v169
	ds_write_b128 v251, v[76:79] offset:0
	ds_write_b128 v251, v[72:75] offset:16
	ds_write_b128 v251, v[68:71] offset:512
	ds_write_b128 v251, v[64:67] offset:528
	v_add_u32_e32 v251, s89, v169
	ds_write_b128 v251, v[12:15] offset:0
	ds_write_b128 v251, v[8:11] offset:16
	ds_write_b128 v251, v[4:7] offset:512
	ds_write_b128 v251, v[0:3] offset:528
	ds_write_b128 v169, v[214:217] offset:7168
	ds_write_b128 v169, v[214:217] offset:7184
	ds_write_b128 v169, v[214:217] offset:7680
	ds_write_b128 v169, v[214:217] offset:7696
	s_mov_b64 exec, -1
	s_cmp_eq_u32 s32, 0
	s_cselect_b64 s[76:77], s[2:3], 0
	s_cselect_b64 s[78:79], 0, s[28:29]
	s_mul_i32 s80, s88, 0x16000
	s_add_u32 s80, s80, 0x5b00000
	s_add_u32 s80, s80, s70
	s_addc_u32 s81, s71, 0
	v_lshl_or_b32 v252, s66, 7, v172
	v_lshlrev_b32_e32 v252, 2, v252
	s_mov_b64 exec, s[76:77]
	global_store_dwordx4 v252, v[140:143], s[80:81]
	global_store_dwordx4 v252, v[136:139], s[80:81] offset:16
	v_add_u32_e32 v250, 0x2c00, v252
	global_store_dwordx4 v250, v[120:123], s[80:81]
	global_store_dwordx4 v250, v[112:115], s[80:81] offset:16
	s_mov_b64 exec, s[78:79]
	v_add_u32_e32 v250, 0xb000, v252
	global_store_dwordx4 v250, v[12:15], s[80:81]
	global_store_dwordx4 v250, v[8:11], s[80:81] offset:16
	v_add_u32_e32 v250, 0xdc00, v252
	global_store_dwordx4 v250, v[4:7], s[80:81]
	global_store_dwordx4 v250, v[0:3], s[80:81] offset:16
	s_mov_b64 exec, -1
	s_waitcnt lgkmcnt(0)
	s_barrier
	ds_read_b128 v[186:189], v231 offset:0
	ds_read_b128 v[190:193], v231 offset:512
	ds_read_b128 v[194:197], v231 offset:2048
	ds_read_b128 v[198:201], v231 offset:2560
	s_nop 0
	v_cndmask_b32_e64 v218, 0, v116, s[2:3]
	v_cndmask_b32_e64 v222, 0, v128, s[28:29]
	v_cndmask_b32_e64 v219, 0, v117, s[2:3]
	v_cndmask_b32_e64 v223, 0, v129, s[28:29]
	v_cndmask_b32_e64 v220, 0, v118, s[2:3]
	v_cndmask_b32_e64 v224, 0, v130, s[28:29]
	v_cndmask_b32_e64 v221, 0, v119, s[2:3]
	v_cndmask_b32_e64 v225, 0, v131, s[28:29]
	v_cndmask_b32_e64 v226, 0, v160, s[2:3]
	v_cndmask_b32_e64 v232, 0, v178, s[28:29]
	v_cndmask_b32_e64 v227, 0, v161, s[2:3]
	v_cndmask_b32_e64 v233, 0, v179, s[28:29]
	v_cndmask_b32_e64 v228, 0, v162, s[2:3]
	v_cndmask_b32_e64 v234, 0, v180, s[28:29]
	v_cndmask_b32_e64 v229, 0, v163, s[2:3]
	v_cndmask_b32_e64 v235, 0, v181, s[28:29]
	s_waitcnt lgkmcnt(0)
	s_nop 1
	v_pk_fma_f32 v[202:203], v[124:125], v[140:141], v[132:133]
	v_pk_fma_f32 v[204:205], v[126:127], v[142:143], v[134:135]
	v_fmac_f32_dpp v202, v76, v116 row_shr:1 row_mask:0xf bank_mask:0xf
	v_fmac_f32_dpp v203, v77, v117 row_shr:1 row_mask:0xf bank_mask:0xf
	v_fmac_f32_dpp v204, v78, v118 row_shr:1 row_mask:0xf bank_mask:0xf
	v_fmac_f32_dpp v205, v79, v119 row_shr:1 row_mask:0xf bank_mask:0xf
	v_pk_fma_f32 v[202:203], v[186:187], v[218:219], v[202:203]
	v_pk_fma_f32 v[204:205], v[188:189], v[220:221], v[204:205]
	v_pk_fma_f32 v[202:203], v[108:109], v[128:129], v[202:203]
	v_pk_fma_f32 v[204:205], v[110:111], v[130:131], v[204:205]
	v_pk_fma_f32 v[206:207], v[164:165], v[120:121], v[182:183]
	v_pk_fma_f32 v[208:209], v[166:167], v[122:123], v[184:185]
	v_fmac_f32_dpp v206, v68, v160 row_shr:1 row_mask:0xf bank_mask:0xf
	v_fmac_f32_dpp v207, v69, v161 row_shr:1 row_mask:0xf bank_mask:0xf
	v_fmac_f32_dpp v208, v70, v162 row_shr:1 row_mask:0xf bank_mask:0xf
	v_fmac_f32_dpp v209, v71, v163 row_shr:1 row_mask:0xf bank_mask:0xf
	v_pk_fma_f32 v[206:207], v[190:191], v[226:227], v[206:207]
	v_pk_fma_f32 v[208:209], v[192:193], v[228:229], v[208:209]
	v_pk_fma_f32 v[206:207], v[100:101], v[178:179], v[206:207]
	v_pk_fma_f32 v[208:209], v[102:103], v[180:181], v[208:209]
	s_mov_b64 exec, s[76:77]
	v_add_u32_e32 v250, 0x5800, v252
	global_store_dwordx4 v250, v[202:205], s[80:81]
	v_add_u32_e32 v250, 0x8400, v252
	global_store_dwordx4 v250, v[206:209], s[80:81]
	s_mov_b64 exec, -1
	s_nop 4
	v_pk_mul_f32 v[210:211], v[202:203], s[90:91]
	v_pk_mul_f32 v[212:213], v[204:205], s[90:91]
	v_exp_f32_e32 v210, v210
	v_exp_f32_e32 v211, v211
	v_exp_f32_e32 v212, v212
	v_exp_f32_e32 v213, v213
	v_pk_add_f32 v[210:211], v[210:211], s[92:93]
	v_pk_add_f32 v[212:213], v[212:213], s[92:93]
	v_rcp_f32_e32 v210, v210
	v_rcp_f32_e32 v211, v211
	v_rcp_f32_e32 v212, v212
	v_rcp_f32_e32 v213, v213
	v_pk_mul_f32 v[202:203], v[202:203], v[210:211]
	v_pk_mul_f32 v[204:205], v[204:205], v[212:213]
	v_pk_mul_f32 v[202:203], v[202:203], v[206:207]
	v_pk_mul_f32 v[204:205], v[204:205], v[208:209]
	v_cvt_pk_bf16_f32 v236, v202, v203
	v_cvt_pk_bf16_f32 v237, v204, v205
	v_pk_fma_f32 v[202:203], v[124:125], v[108:109], v[132:133]
	v_pk_fma_f32 v[204:205], v[126:127], v[110:111], v[134:135]
	v_pk_fma_f32 v[202:203], v[140:141], v[116:117], v[202:203]
	v_pk_fma_f32 v[204:205], v[142:143], v[118:119], v[204:205]
	v_pk_fma_f32 v[202:203], v[92:93], v[128:129], v[202:203]
	v_pk_fma_f32 v[204:205], v[94:95], v[130:131], v[204:205]
	v_pk_fma_f32 v[206:207], v[164:165], v[100:101], v[182:183]
	v_pk_fma_f32 v[208:209], v[166:167], v[102:103], v[184:185]
	v_pk_fma_f32 v[206:207], v[120:121], v[160:161], v[206:207]
	v_pk_fma_f32 v[208:209], v[122:123], v[162:163], v[208:209]
	v_pk_fma_f32 v[206:207], v[84:85], v[178:179], v[206:207]
	v_pk_fma_f32 v[208:209], v[86:87], v[180:181], v[208:209]
	v_pk_mul_f32 v[210:211], v[202:203], s[90:91]
	v_pk_mul_f32 v[212:213], v[204:205], s[90:91]
	v_exp_f32_e32 v210, v210
	v_exp_f32_e32 v211, v211
	v_exp_f32_e32 v212, v212
	v_exp_f32_e32 v213, v213
	v_pk_add_f32 v[210:211], v[210:211], s[92:93]
	v_pk_add_f32 v[212:213], v[212:213], s[92:93]
	v_rcp_f32_e32 v210, v210
	v_rcp_f32_e32 v211, v211
	v_rcp_f32_e32 v212, v212
	v_rcp_f32_e32 v213, v213
	v_pk_mul_f32 v[202:203], v[202:203], v[210:211]
	v_pk_mul_f32 v[204:205], v[204:205], v[212:213]
	v_pk_mul_f32 v[202:203], v[202:203], v[206:207]
	v_pk_mul_f32 v[204:205], v[204:205], v[208:209]
	v_cvt_pk_bf16_f32 v238, v202, v203
	v_cvt_pk_bf16_f32 v239, v204, v205
	v_pk_fma_f32 v[202:203], v[124:125], v[92:93], v[132:133]
	v_pk_fma_f32 v[204:205], v[126:127], v[94:95], v[134:135]
	v_pk_fma_f32 v[202:203], v[108:109], v[116:117], v[202:203]
	v_pk_fma_f32 v[204:205], v[110:111], v[118:119], v[204:205]
	v_pk_fma_f32 v[202:203], v[76:77], v[128:129], v[202:203]
	v_pk_fma_f32 v[204:205], v[78:79], v[130:131], v[204:205]
	v_pk_fma_f32 v[206:207], v[164:165], v[84:85], v[182:183]
	v_pk_fma_f32 v[208:209], v[166:167], v[86:87], v[184:185]
	v_pk_fma_f32 v[206:207], v[100:101], v[160:161], v[206:207]
	v_pk_fma_f32 v[208:209], v[102:103], v[162:163], v[208:209]
	v_pk_fma_f32 v[206:207], v[68:69], v[178:179], v[206:207]
	v_pk_fma_f32 v[208:209], v[70:71], v[180:181], v[208:209]
	v_pk_mul_f32 v[210:211], v[202:203], s[90:91]
	v_pk_mul_f32 v[212:213], v[204:205], s[90:91]
	v_exp_f32_e32 v210, v210
	v_exp_f32_e32 v211, v211
	v_exp_f32_e32 v212, v212
	v_exp_f32_e32 v213, v213
	v_pk_add_f32 v[210:211], v[210:211], s[92:93]
	v_pk_add_f32 v[212:213], v[212:213], s[92:93]
	v_rcp_f32_e32 v210, v210
	v_rcp_f32_e32 v211, v211
	v_rcp_f32_e32 v212, v212
	v_rcp_f32_e32 v213, v213
	v_pk_mul_f32 v[202:203], v[202:203], v[210:211]
	v_pk_mul_f32 v[204:205], v[204:205], v[212:213]
	v_pk_mul_f32 v[202:203], v[202:203], v[206:207]
	v_pk_mul_f32 v[204:205], v[204:205], v[208:209]
	v_cvt_pk_bf16_f32 v240, v202, v203
	v_cvt_pk_bf16_f32 v241, v204, v205
	v_pk_fma_f32 v[202:203], v[124:125], v[76:77], v[132:133]
	v_pk_fma_f32 v[204:205], v[126:127], v[78:79], v[134:135]
	v_pk_fma_f32 v[202:203], v[92:93], v[116:117], v[202:203]
	v_pk_fma_f32 v[204:205], v[94:95], v[118:119], v[204:205]
	v_fmac_f32_dpp v202, v140, v128 row_shl:1 row_mask:0xf bank_mask:0xf
	v_fmac_f32_dpp v203, v141, v129 row_shl:1 row_mask:0xf bank_mask:0xf
	v_fmac_f32_dpp v204, v142, v130 row_shl:1 row_mask:0xf bank_mask:0xf
	v_fmac_f32_dpp v205, v143, v131 row_shl:1 row_mask:0xf bank_mask:0xf
	v_pk_fma_f32 v[202:203], v[186:187], v[222:223], v[202:203]
	v_pk_fma_f32 v[204:205], v[188:189], v[224:225], v[204:205]
	v_pk_fma_f32 v[206:207], v[164:165], v[68:69], v[182:183]
	v_pk_fma_f32 v[208:209], v[166:167], v[70:71], v[184:185]
	v_pk_fma_f32 v[206:207], v[84:85], v[160:161], v[206:207]
	v_pk_fma_f32 v[208:209], v[86:87], v[162:163], v[208:209]
	v_fmac_f32_dpp v206, v120, v178 row_shl:1 row_mask:0xf bank_mask:0xf
	v_fmac_f32_dpp v207, v121, v179 row_shl:1 row_mask:0xf bank_mask:0xf
	v_fmac_f32_dpp v208, v122, v180 row_shl:1 row_mask:0xf bank_mask:0xf
	v_fmac_f32_dpp v209, v123, v181 row_shl:1 row_mask:0xf bank_mask:0xf
	v_pk_fma_f32 v[206:207], v[190:191], v[232:233], v[206:207]
	v_pk_fma_f32 v[208:209], v[192:193], v[234:235], v[208:209]
	v_pk_mul_f32 v[210:211], v[202:203], s[90:91]
	v_pk_mul_f32 v[212:213], v[204:205], s[90:91]
	v_exp_f32_e32 v210, v210
	v_exp_f32_e32 v211, v211
	v_exp_f32_e32 v212, v212
	v_exp_f32_e32 v213, v213
	v_pk_add_f32 v[210:211], v[210:211], s[92:93]
	v_pk_add_f32 v[212:213], v[212:213], s[92:93]
	v_rcp_f32_e32 v210, v210
	v_rcp_f32_e32 v211, v211
	v_rcp_f32_e32 v212, v212
	v_rcp_f32_e32 v213, v213
	v_pk_mul_f32 v[202:203], v[202:203], v[210:211]
	v_pk_mul_f32 v[204:205], v[204:205], v[212:213]
	v_pk_mul_f32 v[202:203], v[202:203], v[206:207]
	v_pk_mul_f32 v[204:205], v[204:205], v[208:209]
	v_cvt_pk_bf16_f32 v242, v202, v203
	v_cvt_pk_bf16_f32 v243, v204, v205
	v_pk_fma_f32 v[202:203], v[124:125], v[60:61], v[132:133]
	v_pk_fma_f32 v[204:205], v[126:127], v[62:63], v[134:135]
	v_fmac_f32_dpp v202, v12, v116 row_shr:1 row_mask:0xf bank_mask:0xf
	v_fmac_f32_dpp v203, v13, v117 row_shr:1 row_mask:0xf bank_mask:0xf
	v_fmac_f32_dpp v204, v14, v118 row_shr:1 row_mask:0xf bank_mask:0xf
	v_fmac_f32_dpp v205, v15, v119 row_shr:1 row_mask:0xf bank_mask:0xf
	v_pk_fma_f32 v[202:203], v[194:195], v[218:219], v[202:203]
	v_pk_fma_f32 v[204:205], v[196:197], v[220:221], v[204:205]
	v_pk_fma_f32 v[202:203], v[44:45], v[128:129], v[202:203]
	v_pk_fma_f32 v[204:205], v[46:47], v[130:131], v[204:205]
	v_pk_fma_f32 v[206:207], v[164:165], v[52:53], v[182:183]
	v_pk_fma_f32 v[208:209], v[166:167], v[54:55], v[184:185]
	v_fmac_f32_dpp v206, v4, v160 row_shr:1 row_mask:0xf bank_mask:0xf
	v_fmac_f32_dpp v207, v5, v161 row_shr:1 row_mask:0xf bank_mask:0xf
	v_fmac_f32_dpp v208, v6, v162 row_shr:1 row_mask:0xf bank_mask:0xf
	v_fmac_f32_dpp v209, v7, v163 row_shr:1 row_mask:0xf bank_mask:0xf
	v_pk_fma_f32 v[206:207], v[198:199], v[226:227], v[206:207]
	v_pk_fma_f32 v[208:209], v[200:201], v[228:229], v[208:209]
	v_pk_fma_f32 v[206:207], v[36:37], v[178:179], v[206:207]
	v_pk_fma_f32 v[208:209], v[38:39], v[180:181], v[208:209]
	v_pk_mul_f32 v[210:211], v[202:203], s[90:91]
	v_pk_mul_f32 v[212:213], v[204:205], s[90:91]
	v_exp_f32_e32 v210, v210
	v_exp_f32_e32 v211, v211
	v_exp_f32_e32 v212, v212
	v_exp_f32_e32 v213, v213
	v_pk_add_f32 v[210:211], v[210:211], s[92:93]
	v_pk_add_f32 v[212:213], v[212:213], s[92:93]
	v_rcp_f32_e32 v210, v210
	v_rcp_f32_e32 v211, v211
	v_rcp_f32_e32 v212, v212
	v_rcp_f32_e32 v213, v213
	v_pk_mul_f32 v[202:203], v[202:203], v[210:211]
	v_pk_mul_f32 v[204:205], v[204:205], v[212:213]
	v_pk_mul_f32 v[202:203], v[202:203], v[206:207]
	v_pk_mul_f32 v[204:205], v[204:205], v[208:209]
	v_cvt_pk_bf16_f32 v244, v202, v203
	v_cvt_pk_bf16_f32 v245, v204, v205
	v_pk_fma_f32 v[202:203], v[124:125], v[44:45], v[132:133]
	v_pk_fma_f32 v[204:205], v[126:127], v[46:47], v[134:135]
	v_pk_fma_f32 v[202:203], v[60:61], v[116:117], v[202:203]
	v_pk_fma_f32 v[204:205], v[62:63], v[118:119], v[204:205]
	v_pk_fma_f32 v[202:203], v[28:29], v[128:129], v[202:203]
	v_pk_fma_f32 v[204:205], v[30:31], v[130:131], v[204:205]
	v_pk_fma_f32 v[206:207], v[164:165], v[36:37], v[182:183]
	v_pk_fma_f32 v[208:209], v[166:167], v[38:39], v[184:185]
	v_pk_fma_f32 v[206:207], v[52:53], v[160:161], v[206:207]
	v_pk_fma_f32 v[208:209], v[54:55], v[162:163], v[208:209]
	v_pk_fma_f32 v[206:207], v[20:21], v[178:179], v[206:207]
	v_pk_fma_f32 v[208:209], v[22:23], v[180:181], v[208:209]
	v_pk_mul_f32 v[210:211], v[202:203], s[90:91]
	v_pk_mul_f32 v[212:213], v[204:205], s[90:91]
	v_exp_f32_e32 v210, v210
	v_exp_f32_e32 v211, v211
	v_exp_f32_e32 v212, v212
	v_exp_f32_e32 v213, v213
	v_pk_add_f32 v[210:211], v[210:211], s[92:93]
	v_pk_add_f32 v[212:213], v[212:213], s[92:93]
	v_rcp_f32_e32 v210, v210
	v_rcp_f32_e32 v211, v211
	v_rcp_f32_e32 v212, v212
	v_rcp_f32_e32 v213, v213
	v_pk_mul_f32 v[202:203], v[202:203], v[210:211]
	v_pk_mul_f32 v[204:205], v[204:205], v[212:213]
	v_pk_mul_f32 v[202:203], v[202:203], v[206:207]
	v_pk_mul_f32 v[204:205], v[204:205], v[208:209]
	v_cvt_pk_bf16_f32 v246, v202, v203
	v_cvt_pk_bf16_f32 v247, v204, v205
	v_pk_fma_f32 v[202:203], v[124:125], v[28:29], v[132:133]
	v_pk_fma_f32 v[204:205], v[126:127], v[30:31], v[134:135]
	v_pk_fma_f32 v[202:203], v[44:45], v[116:117], v[202:203]
	v_pk_fma_f32 v[204:205], v[46:47], v[118:119], v[204:205]
	v_pk_fma_f32 v[202:203], v[12:13], v[128:129], v[202:203]
	v_pk_fma_f32 v[204:205], v[14:15], v[130:131], v[204:205]
	v_pk_fma_f32 v[206:207], v[164:165], v[20:21], v[182:183]
	v_pk_fma_f32 v[208:209], v[166:167], v[22:23], v[184:185]
	v_pk_fma_f32 v[206:207], v[36:37], v[160:161], v[206:207]
	v_pk_fma_f32 v[208:209], v[38:39], v[162:163], v[208:209]
	v_pk_fma_f32 v[206:207], v[4:5], v[178:179], v[206:207]
	v_pk_fma_f32 v[208:209], v[6:7], v[180:181], v[208:209]
	v_pk_mul_f32 v[210:211], v[202:203], s[90:91]
	v_pk_mul_f32 v[212:213], v[204:205], s[90:91]
	v_exp_f32_e32 v210, v210
	v_exp_f32_e32 v211, v211
	v_exp_f32_e32 v212, v212
	v_exp_f32_e32 v213, v213
	v_pk_add_f32 v[210:211], v[210:211], s[92:93]
	v_pk_add_f32 v[212:213], v[212:213], s[92:93]
	v_rcp_f32_e32 v210, v210
	v_rcp_f32_e32 v211, v211
	v_rcp_f32_e32 v212, v212
	v_rcp_f32_e32 v213, v213
	v_pk_mul_f32 v[202:203], v[202:203], v[210:211]
	v_pk_mul_f32 v[204:205], v[204:205], v[212:213]
	v_pk_mul_f32 v[202:203], v[202:203], v[206:207]
	v_pk_mul_f32 v[204:205], v[204:205], v[208:209]
	v_cvt_pk_bf16_f32 v248, v202, v203
	v_cvt_pk_bf16_f32 v249, v204, v205
	v_pk_fma_f32 v[202:203], v[124:125], v[12:13], v[132:133]
	v_pk_fma_f32 v[204:205], v[126:127], v[14:15], v[134:135]
	v_pk_fma_f32 v[202:203], v[28:29], v[116:117], v[202:203]
	v_pk_fma_f32 v[204:205], v[30:31], v[118:119], v[204:205]
	v_fmac_f32_dpp v202, v60, v128 row_shl:1 row_mask:0xf bank_mask:0xf
	v_fmac_f32_dpp v203, v61, v129 row_shl:1 row_mask:0xf bank_mask:0xf
	v_fmac_f32_dpp v204, v62, v130 row_shl:1 row_mask:0xf bank_mask:0xf
	v_fmac_f32_dpp v205, v63, v131 row_shl:1 row_mask:0xf bank_mask:0xf
	v_pk_fma_f32 v[202:203], v[194:195], v[222:223], v[202:203]
	v_pk_fma_f32 v[204:205], v[196:197], v[224:225], v[204:205]
	v_pk_fma_f32 v[206:207], v[164:165], v[4:5], v[182:183]
	v_pk_fma_f32 v[208:209], v[166:167], v[6:7], v[184:185]
	v_pk_fma_f32 v[206:207], v[20:21], v[160:161], v[206:207]
	v_pk_fma_f32 v[208:209], v[22:23], v[162:163], v[208:209]
	v_fmac_f32_dpp v206, v52, v178 row_shl:1 row_mask:0xf bank_mask:0xf
	v_fmac_f32_dpp v207, v53, v179 row_shl:1 row_mask:0xf bank_mask:0xf
	v_fmac_f32_dpp v208, v54, v180 row_shl:1 row_mask:0xf bank_mask:0xf
	v_fmac_f32_dpp v209, v55, v181 row_shl:1 row_mask:0xf bank_mask:0xf
	v_pk_fma_f32 v[206:207], v[198:199], v[232:233], v[206:207]
	v_pk_fma_f32 v[208:209], v[200:201], v[234:235], v[208:209]
	s_mov_b64 exec, s[78:79]
	v_add_u32_e32 v250, 0x10800, v252
	global_store_dwordx4 v250, v[202:205], s[80:81]
	v_add_u32_e32 v250, 0x13400, v252
	global_store_dwordx4 v250, v[206:209], s[80:81]
	s_mov_b64 exec, -1
	s_nop 4
	v_pk_mul_f32 v[210:211], v[202:203], s[90:91]
	v_pk_mul_f32 v[212:213], v[204:205], s[90:91]
	v_exp_f32_e32 v210, v210
	v_exp_f32_e32 v211, v211
	v_exp_f32_e32 v212, v212
	v_exp_f32_e32 v213, v213
	v_pk_add_f32 v[210:211], v[210:211], s[92:93]
	v_pk_add_f32 v[212:213], v[212:213], s[92:93]
	v_rcp_f32_e32 v210, v210
	v_rcp_f32_e32 v211, v211
	v_rcp_f32_e32 v212, v212
	v_rcp_f32_e32 v213, v213
	v_pk_mul_f32 v[202:203], v[202:203], v[210:211]
	v_pk_mul_f32 v[204:205], v[204:205], v[212:213]
	v_pk_mul_f32 v[202:203], v[202:203], v[206:207]
	v_pk_mul_f32 v[204:205], v[204:205], v[208:209]
	v_cvt_pk_bf16_f32 v250, v202, v203
	v_cvt_pk_bf16_f32 v251, v204, v205
	ds_read_b128 v[116:119], v177 offset:2064
	ds_read_b128 v[124:127], v177 offset:2576
	ds_read_b128 v[128:131], v177 offset:4112
	ds_read_b128 v[132:135], v177 offset:5136
	ds_read_b128 v[160:163], v177 offset:3088
	ds_read_b128 v[164:167], v177 offset:3600
	ds_read_b128 v[178:181], v177 offset:4624
	ds_read_b128 v[182:185], v177 offset:5648
	v_mov_b32_e32 v140, v236
	v_mov_b32_e32 v141, v237
	v_mov_b32_e32 v108, v238
	v_mov_b32_e32 v109, v239
	v_mov_b32_e32 v92, v240
	v_mov_b32_e32 v93, v241
	v_mov_b32_e32 v76, v242
	v_mov_b32_e32 v77, v243
	v_mov_b32_e32 v60, v244
	v_mov_b32_e32 v61, v245
	v_mov_b32_e32 v44, v246
	v_mov_b32_e32 v45, v247
	v_mov_b32_e32 v28, v248
	v_mov_b32_e32 v29, v249
	v_mov_b32_e32 v12, v250
	v_mov_b32_e32 v13, v251
	ds_read_b128 v[186:189], v231 offset:16
	ds_read_b128 v[190:193], v231 offset:528
	ds_read_b128 v[194:197], v231 offset:2064
	ds_read_b128 v[198:201], v231 offset:2576
	s_waitcnt lgkmcnt(4)
	v_cndmask_b32_e64 v218, 0, v116, s[2:3]
	v_cndmask_b32_e64 v222, 0, v128, s[28:29]
	v_cndmask_b32_e64 v219, 0, v117, s[2:3]
	v_cndmask_b32_e64 v223, 0, v129, s[28:29]
	v_cndmask_b32_e64 v220, 0, v118, s[2:3]
	v_cndmask_b32_e64 v224, 0, v130, s[28:29]
	v_cndmask_b32_e64 v221, 0, v119, s[2:3]
	v_cndmask_b32_e64 v225, 0, v131, s[28:29]
	v_cndmask_b32_e64 v226, 0, v160, s[2:3]
	v_cndmask_b32_e64 v232, 0, v178, s[28:29]
	v_cndmask_b32_e64 v227, 0, v161, s[2:3]
	v_cndmask_b32_e64 v233, 0, v179, s[28:29]
	v_cndmask_b32_e64 v228, 0, v162, s[2:3]
	v_cndmask_b32_e64 v234, 0, v180, s[28:29]
	v_cndmask_b32_e64 v229, 0, v163, s[2:3]
	v_cndmask_b32_e64 v235, 0, v181, s[28:29]
	s_waitcnt lgkmcnt(0)
	s_nop 1
	v_pk_fma_f32 v[202:203], v[124:125], v[136:137], v[132:133]
	v_pk_fma_f32 v[204:205], v[126:127], v[138:139], v[134:135]
	v_fmac_f32_dpp v202, v72, v116 row_shr:1 row_mask:0xf bank_mask:0xf
	v_fmac_f32_dpp v203, v73, v117 row_shr:1 row_mask:0xf bank_mask:0xf
	v_fmac_f32_dpp v204, v74, v118 row_shr:1 row_mask:0xf bank_mask:0xf
	v_fmac_f32_dpp v205, v75, v119 row_shr:1 row_mask:0xf bank_mask:0xf
	v_pk_fma_f32 v[202:203], v[186:187], v[218:219], v[202:203]
	v_pk_fma_f32 v[204:205], v[188:189], v[220:221], v[204:205]
	v_pk_fma_f32 v[202:203], v[104:105], v[128:129], v[202:203]
	v_pk_fma_f32 v[204:205], v[106:107], v[130:131], v[204:205]
	v_pk_fma_f32 v[206:207], v[164:165], v[112:113], v[182:183]
	v_pk_fma_f32 v[208:209], v[166:167], v[114:115], v[184:185]
	v_fmac_f32_dpp v206, v64, v160 row_shr:1 row_mask:0xf bank_mask:0xf
	v_fmac_f32_dpp v207, v65, v161 row_shr:1 row_mask:0xf bank_mask:0xf
	v_fmac_f32_dpp v208, v66, v162 row_shr:1 row_mask:0xf bank_mask:0xf
	v_fmac_f32_dpp v209, v67, v163 row_shr:1 row_mask:0xf bank_mask:0xf
	v_pk_fma_f32 v[206:207], v[190:191], v[226:227], v[206:207]
	v_pk_fma_f32 v[208:209], v[192:193], v[228:229], v[208:209]
	v_pk_fma_f32 v[206:207], v[96:97], v[178:179], v[206:207]
	v_pk_fma_f32 v[208:209], v[98:99], v[180:181], v[208:209]
	s_mov_b64 exec, s[76:77]
	v_add_u32_e32 v250, 0x5800, v252
	global_store_dwordx4 v250, v[202:205], s[80:81] offset:16
	v_add_u32_e32 v250, 0x8400, v252
	global_store_dwordx4 v250, v[206:209], s[80:81] offset:16
	s_mov_b64 exec, -1
	s_nop 4
	v_pk_mul_f32 v[210:211], v[202:203], s[90:91]
	v_pk_mul_f32 v[212:213], v[204:205], s[90:91]
	v_exp_f32_e32 v210, v210
	v_exp_f32_e32 v211, v211
	v_exp_f32_e32 v212, v212
	v_exp_f32_e32 v213, v213
	v_pk_add_f32 v[210:211], v[210:211], s[92:93]
	v_pk_add_f32 v[212:213], v[212:213], s[92:93]
	v_rcp_f32_e32 v210, v210
	v_rcp_f32_e32 v211, v211
	v_rcp_f32_e32 v212, v212
	v_rcp_f32_e32 v213, v213
	v_pk_mul_f32 v[202:203], v[202:203], v[210:211]
	v_pk_mul_f32 v[204:205], v[204:205], v[212:213]
	v_pk_mul_f32 v[202:203], v[202:203], v[206:207]
	v_pk_mul_f32 v[204:205], v[204:205], v[208:209]
	v_cvt_pk_bf16_f32 v142, v202, v203
	v_cvt_pk_bf16_f32 v143, v204, v205
	v_pk_fma_f32 v[202:203], v[124:125], v[104:105], v[132:133]
	v_pk_fma_f32 v[204:205], v[126:127], v[106:107], v[134:135]
	v_pk_fma_f32 v[202:203], v[136:137], v[116:117], v[202:203]
	v_pk_fma_f32 v[204:205], v[138:139], v[118:119], v[204:205]
	v_pk_fma_f32 v[202:203], v[88:89], v[128:129], v[202:203]
	v_pk_fma_f32 v[204:205], v[90:91], v[130:131], v[204:205]
	v_pk_fma_f32 v[206:207], v[164:165], v[96:97], v[182:183]
	v_pk_fma_f32 v[208:209], v[166:167], v[98:99], v[184:185]
	v_pk_fma_f32 v[206:207], v[112:113], v[160:161], v[206:207]
	v_pk_fma_f32 v[208:209], v[114:115], v[162:163], v[208:209]
	v_pk_fma_f32 v[206:207], v[80:81], v[178:179], v[206:207]
	v_pk_fma_f32 v[208:209], v[82:83], v[180:181], v[208:209]
	v_pk_mul_f32 v[210:211], v[202:203], s[90:91]
	v_pk_mul_f32 v[212:213], v[204:205], s[90:91]
	v_exp_f32_e32 v210, v210
	v_exp_f32_e32 v211, v211
	v_exp_f32_e32 v212, v212
	v_exp_f32_e32 v213, v213
	v_pk_add_f32 v[210:211], v[210:211], s[92:93]
	v_pk_add_f32 v[212:213], v[212:213], s[92:93]
	v_rcp_f32_e32 v210, v210
	v_rcp_f32_e32 v211, v211
	v_rcp_f32_e32 v212, v212
	v_rcp_f32_e32 v213, v213
	v_pk_mul_f32 v[202:203], v[202:203], v[210:211]
	v_pk_mul_f32 v[204:205], v[204:205], v[212:213]
	v_pk_mul_f32 v[202:203], v[202:203], v[206:207]
	v_pk_mul_f32 v[204:205], v[204:205], v[208:209]
	v_cvt_pk_bf16_f32 v110, v202, v203
	v_cvt_pk_bf16_f32 v111, v204, v205
	v_pk_fma_f32 v[202:203], v[124:125], v[88:89], v[132:133]
	v_pk_fma_f32 v[204:205], v[126:127], v[90:91], v[134:135]
	v_pk_fma_f32 v[202:203], v[104:105], v[116:117], v[202:203]
	v_pk_fma_f32 v[204:205], v[106:107], v[118:119], v[204:205]
	v_pk_fma_f32 v[202:203], v[72:73], v[128:129], v[202:203]
	v_pk_fma_f32 v[204:205], v[74:75], v[130:131], v[204:205]
	v_pk_fma_f32 v[206:207], v[164:165], v[80:81], v[182:183]
	v_pk_fma_f32 v[208:209], v[166:167], v[82:83], v[184:185]
	v_pk_fma_f32 v[206:207], v[96:97], v[160:161], v[206:207]
	v_pk_fma_f32 v[208:209], v[98:99], v[162:163], v[208:209]
	v_pk_fma_f32 v[206:207], v[64:65], v[178:179], v[206:207]
	v_pk_fma_f32 v[208:209], v[66:67], v[180:181], v[208:209]
	v_pk_mul_f32 v[210:211], v[202:203], s[90:91]
	v_pk_mul_f32 v[212:213], v[204:205], s[90:91]
	v_exp_f32_e32 v210, v210
	v_exp_f32_e32 v211, v211
	v_exp_f32_e32 v212, v212
	v_exp_f32_e32 v213, v213
	v_pk_add_f32 v[210:211], v[210:211], s[92:93]
	v_pk_add_f32 v[212:213], v[212:213], s[92:93]
	v_rcp_f32_e32 v210, v210
	v_rcp_f32_e32 v211, v211
	v_rcp_f32_e32 v212, v212
	v_rcp_f32_e32 v213, v213
	v_pk_mul_f32 v[202:203], v[202:203], v[210:211]
	v_pk_mul_f32 v[204:205], v[204:205], v[212:213]
	v_pk_mul_f32 v[202:203], v[202:203], v[206:207]
	v_pk_mul_f32 v[204:205], v[204:205], v[208:209]
	v_cvt_pk_bf16_f32 v94, v202, v203
	v_cvt_pk_bf16_f32 v95, v204, v205
	v_pk_fma_f32 v[202:203], v[124:125], v[72:73], v[132:133]
	v_pk_fma_f32 v[204:205], v[126:127], v[74:75], v[134:135]
	v_pk_fma_f32 v[202:203], v[88:89], v[116:117], v[202:203]
	v_pk_fma_f32 v[204:205], v[90:91], v[118:119], v[204:205]
	v_fmac_f32_dpp v202, v136, v128 row_shl:1 row_mask:0xf bank_mask:0xf
	v_fmac_f32_dpp v203, v137, v129 row_shl:1 row_mask:0xf bank_mask:0xf
	v_fmac_f32_dpp v204, v138, v130 row_shl:1 row_mask:0xf bank_mask:0xf
	v_fmac_f32_dpp v205, v139, v131 row_shl:1 row_mask:0xf bank_mask:0xf
	v_pk_fma_f32 v[202:203], v[186:187], v[222:223], v[202:203]
	v_pk_fma_f32 v[204:205], v[188:189], v[224:225], v[204:205]
	v_pk_fma_f32 v[206:207], v[164:165], v[64:65], v[182:183]
	v_pk_fma_f32 v[208:209], v[166:167], v[66:67], v[184:185]
	v_pk_fma_f32 v[206:207], v[80:81], v[160:161], v[206:207]
	v_pk_fma_f32 v[208:209], v[82:83], v[162:163], v[208:209]
	v_fmac_f32_dpp v206, v112, v178 row_shl:1 row_mask:0xf bank_mask:0xf
	v_fmac_f32_dpp v207, v113, v179 row_shl:1 row_mask:0xf bank_mask:0xf
	v_fmac_f32_dpp v208, v114, v180 row_shl:1 row_mask:0xf bank_mask:0xf
	v_fmac_f32_dpp v209, v115, v181 row_shl:1 row_mask:0xf bank_mask:0xf
	v_pk_fma_f32 v[206:207], v[190:191], v[232:233], v[206:207]
	v_pk_fma_f32 v[208:209], v[192:193], v[234:235], v[208:209]
	v_pk_mul_f32 v[210:211], v[202:203], s[90:91]
	v_pk_mul_f32 v[212:213], v[204:205], s[90:91]
	v_exp_f32_e32 v210, v210
	v_exp_f32_e32 v211, v211
	v_exp_f32_e32 v212, v212
	v_exp_f32_e32 v213, v213
	v_pk_add_f32 v[210:211], v[210:211], s[92:93]
	v_pk_add_f32 v[212:213], v[212:213], s[92:93]
	v_rcp_f32_e32 v210, v210
	v_rcp_f32_e32 v211, v211
	v_rcp_f32_e32 v212, v212
	v_rcp_f32_e32 v213, v213
	v_pk_mul_f32 v[202:203], v[202:203], v[210:211]
	v_pk_mul_f32 v[204:205], v[204:205], v[212:213]
	v_pk_mul_f32 v[202:203], v[202:203], v[206:207]
	v_pk_mul_f32 v[204:205], v[204:205], v[208:209]
	v_cvt_pk_bf16_f32 v78, v202, v203
	v_cvt_pk_bf16_f32 v79, v204, v205
	v_pk_fma_f32 v[202:203], v[124:125], v[56:57], v[132:133]
	v_pk_fma_f32 v[204:205], v[126:127], v[58:59], v[134:135]
	v_fmac_f32_dpp v202, v8, v116 row_shr:1 row_mask:0xf bank_mask:0xf
	v_fmac_f32_dpp v203, v9, v117 row_shr:1 row_mask:0xf bank_mask:0xf
	v_fmac_f32_dpp v204, v10, v118 row_shr:1 row_mask:0xf bank_mask:0xf
	v_fmac_f32_dpp v205, v11, v119 row_shr:1 row_mask:0xf bank_mask:0xf
	v_pk_fma_f32 v[202:203], v[194:195], v[218:219], v[202:203]
	v_pk_fma_f32 v[204:205], v[196:197], v[220:221], v[204:205]
	v_pk_fma_f32 v[202:203], v[40:41], v[128:129], v[202:203]
	v_pk_fma_f32 v[204:205], v[42:43], v[130:131], v[204:205]
	v_pk_fma_f32 v[206:207], v[164:165], v[48:49], v[182:183]
	v_pk_fma_f32 v[208:209], v[166:167], v[50:51], v[184:185]
	v_fmac_f32_dpp v206, v0, v160 row_shr:1 row_mask:0xf bank_mask:0xf
	v_fmac_f32_dpp v207, v1, v161 row_shr:1 row_mask:0xf bank_mask:0xf
	v_fmac_f32_dpp v208, v2, v162 row_shr:1 row_mask:0xf bank_mask:0xf
	v_fmac_f32_dpp v209, v3, v163 row_shr:1 row_mask:0xf bank_mask:0xf
	v_pk_fma_f32 v[206:207], v[198:199], v[226:227], v[206:207]
	v_pk_fma_f32 v[208:209], v[200:201], v[228:229], v[208:209]
	v_pk_fma_f32 v[206:207], v[32:33], v[178:179], v[206:207]
	v_pk_fma_f32 v[208:209], v[34:35], v[180:181], v[208:209]
	v_pk_mul_f32 v[210:211], v[202:203], s[90:91]
	v_pk_mul_f32 v[212:213], v[204:205], s[90:91]
	v_exp_f32_e32 v210, v210
	v_exp_f32_e32 v211, v211
	v_exp_f32_e32 v212, v212
	v_exp_f32_e32 v213, v213
	v_pk_add_f32 v[210:211], v[210:211], s[92:93]
	v_pk_add_f32 v[212:213], v[212:213], s[92:93]
	v_rcp_f32_e32 v210, v210
	v_rcp_f32_e32 v211, v211
	v_rcp_f32_e32 v212, v212
	v_rcp_f32_e32 v213, v213
	v_pk_mul_f32 v[202:203], v[202:203], v[210:211]
	v_pk_mul_f32 v[204:205], v[204:205], v[212:213]
	v_pk_mul_f32 v[202:203], v[202:203], v[206:207]
	v_pk_mul_f32 v[204:205], v[204:205], v[208:209]
	v_cvt_pk_bf16_f32 v62, v202, v203
	v_cvt_pk_bf16_f32 v63, v204, v205
	v_pk_fma_f32 v[202:203], v[124:125], v[40:41], v[132:133]
	v_pk_fma_f32 v[204:205], v[126:127], v[42:43], v[134:135]
	v_pk_fma_f32 v[202:203], v[56:57], v[116:117], v[202:203]
	v_pk_fma_f32 v[204:205], v[58:59], v[118:119], v[204:205]
	v_pk_fma_f32 v[202:203], v[24:25], v[128:129], v[202:203]
	v_pk_fma_f32 v[204:205], v[26:27], v[130:131], v[204:205]
	v_pk_fma_f32 v[206:207], v[164:165], v[32:33], v[182:183]
	v_pk_fma_f32 v[208:209], v[166:167], v[34:35], v[184:185]
	v_pk_fma_f32 v[206:207], v[48:49], v[160:161], v[206:207]
	v_pk_fma_f32 v[208:209], v[50:51], v[162:163], v[208:209]
	v_pk_fma_f32 v[206:207], v[16:17], v[178:179], v[206:207]
	v_pk_fma_f32 v[208:209], v[18:19], v[180:181], v[208:209]
	v_pk_mul_f32 v[210:211], v[202:203], s[90:91]
	v_pk_mul_f32 v[212:213], v[204:205], s[90:91]
	v_exp_f32_e32 v210, v210
	v_exp_f32_e32 v211, v211
	v_exp_f32_e32 v212, v212
	v_exp_f32_e32 v213, v213
	v_pk_add_f32 v[210:211], v[210:211], s[92:93]
	v_pk_add_f32 v[212:213], v[212:213], s[92:93]
	v_rcp_f32_e32 v210, v210
	v_rcp_f32_e32 v211, v211
	v_rcp_f32_e32 v212, v212
	v_rcp_f32_e32 v213, v213
	v_pk_mul_f32 v[202:203], v[202:203], v[210:211]
	v_pk_mul_f32 v[204:205], v[204:205], v[212:213]
	v_pk_mul_f32 v[202:203], v[202:203], v[206:207]
	v_pk_mul_f32 v[204:205], v[204:205], v[208:209]
	v_cvt_pk_bf16_f32 v46, v202, v203
	v_cvt_pk_bf16_f32 v47, v204, v205
	v_pk_fma_f32 v[202:203], v[124:125], v[24:25], v[132:133]
	v_pk_fma_f32 v[204:205], v[126:127], v[26:27], v[134:135]
	v_pk_fma_f32 v[202:203], v[40:41], v[116:117], v[202:203]
	v_pk_fma_f32 v[204:205], v[42:43], v[118:119], v[204:205]
	v_pk_fma_f32 v[202:203], v[8:9], v[128:129], v[202:203]
	v_pk_fma_f32 v[204:205], v[10:11], v[130:131], v[204:205]
	v_pk_fma_f32 v[206:207], v[164:165], v[16:17], v[182:183]
	v_pk_fma_f32 v[208:209], v[166:167], v[18:19], v[184:185]
	v_pk_fma_f32 v[206:207], v[32:33], v[160:161], v[206:207]
	v_pk_fma_f32 v[208:209], v[34:35], v[162:163], v[208:209]
	v_pk_fma_f32 v[206:207], v[0:1], v[178:179], v[206:207]
	v_pk_fma_f32 v[208:209], v[2:3], v[180:181], v[208:209]
	v_pk_mul_f32 v[210:211], v[202:203], s[90:91]
	v_pk_mul_f32 v[212:213], v[204:205], s[90:91]
	v_exp_f32_e32 v210, v210
	v_exp_f32_e32 v211, v211
	v_exp_f32_e32 v212, v212
	v_exp_f32_e32 v213, v213
	v_pk_add_f32 v[210:211], v[210:211], s[92:93]
	v_pk_add_f32 v[212:213], v[212:213], s[92:93]
	v_rcp_f32_e32 v210, v210
	v_rcp_f32_e32 v211, v211
	v_rcp_f32_e32 v212, v212
	v_rcp_f32_e32 v213, v213
	v_pk_mul_f32 v[202:203], v[202:203], v[210:211]
	v_pk_mul_f32 v[204:205], v[204:205], v[212:213]
	v_pk_mul_f32 v[202:203], v[202:203], v[206:207]
	v_pk_mul_f32 v[204:205], v[204:205], v[208:209]
	v_cvt_pk_bf16_f32 v30, v202, v203
	v_cvt_pk_bf16_f32 v31, v204, v205
	v_pk_fma_f32 v[202:203], v[124:125], v[8:9], v[132:133]
	v_pk_fma_f32 v[204:205], v[126:127], v[10:11], v[134:135]
	v_pk_fma_f32 v[202:203], v[24:25], v[116:117], v[202:203]
	v_pk_fma_f32 v[204:205], v[26:27], v[118:119], v[204:205]
	v_fmac_f32_dpp v202, v56, v128 row_shl:1 row_mask:0xf bank_mask:0xf
	v_fmac_f32_dpp v203, v57, v129 row_shl:1 row_mask:0xf bank_mask:0xf
	v_fmac_f32_dpp v204, v58, v130 row_shl:1 row_mask:0xf bank_mask:0xf
	v_fmac_f32_dpp v205, v59, v131 row_shl:1 row_mask:0xf bank_mask:0xf
	v_pk_fma_f32 v[202:203], v[194:195], v[222:223], v[202:203]
	v_pk_fma_f32 v[204:205], v[196:197], v[224:225], v[204:205]
	v_pk_fma_f32 v[206:207], v[164:165], v[0:1], v[182:183]
	v_pk_fma_f32 v[208:209], v[166:167], v[2:3], v[184:185]
	v_pk_fma_f32 v[206:207], v[16:17], v[160:161], v[206:207]
	v_pk_fma_f32 v[208:209], v[18:19], v[162:163], v[208:209]
	v_fmac_f32_dpp v206, v48, v178 row_shl:1 row_mask:0xf bank_mask:0xf
	v_fmac_f32_dpp v207, v49, v179 row_shl:1 row_mask:0xf bank_mask:0xf
	v_fmac_f32_dpp v208, v50, v180 row_shl:1 row_mask:0xf bank_mask:0xf
	v_fmac_f32_dpp v209, v51, v181 row_shl:1 row_mask:0xf bank_mask:0xf
	v_pk_fma_f32 v[206:207], v[198:199], v[232:233], v[206:207]
	v_pk_fma_f32 v[208:209], v[200:201], v[234:235], v[208:209]
	s_mov_b64 exec, s[78:79]
	v_add_u32_e32 v250, 0x10800, v252
	global_store_dwordx4 v250, v[202:205], s[80:81] offset:16
	v_add_u32_e32 v250, 0x13400, v252
	global_store_dwordx4 v250, v[206:209], s[80:81] offset:16
	s_mov_b64 exec, -1
	s_nop 4
	v_pk_mul_f32 v[210:211], v[202:203], s[90:91]
	v_pk_mul_f32 v[212:213], v[204:205], s[90:91]
	v_exp_f32_e32 v210, v210
	v_exp_f32_e32 v211, v211
	v_exp_f32_e32 v212, v212
	v_exp_f32_e32 v213, v213
	v_pk_add_f32 v[210:211], v[210:211], s[92:93]
	v_pk_add_f32 v[212:213], v[212:213], s[92:93]
	v_rcp_f32_e32 v210, v210
	v_rcp_f32_e32 v211, v211
	v_rcp_f32_e32 v212, v212
	v_rcp_f32_e32 v213, v213
	v_pk_mul_f32 v[202:203], v[202:203], v[210:211]
	v_pk_mul_f32 v[204:205], v[204:205], v[212:213]
	v_pk_mul_f32 v[202:203], v[202:203], v[206:207]
	v_pk_mul_f32 v[204:205], v[204:205], v[208:209]
	v_cvt_pk_bf16_f32 v14, v202, v203
	v_cvt_pk_bf16_f32 v15, v204, v205
	global_store_dwordx4 v168, v[140:143], s[4:5]
	v_add_u32_e32 v250, 0x1600, v168
	global_store_dwordx4 v250, v[108:111], s[4:5]
	s_nop 0
	v_add_u32_e32 v250, 0x2c00, v168
	global_store_dwordx4 v250, v[92:95], s[4:5]
	s_nop 0
	v_add_u32_e32 v250, 0x4200, v168
	global_store_dwordx4 v250, v[76:79], s[4:5]
	s_nop 0
	v_add_u32_e32 v250, 0xb0000, v168
	global_store_dwordx4 v250, v[60:63], s[4:5]
	s_nop 0
	v_add_u32_e32 v250, 0xb1600, v168
	global_store_dwordx4 v250, v[44:47], s[4:5]
	s_nop 0
	v_add_u32_e32 v250, 0xb2c00, v168
	global_store_dwordx4 v250, v[28:31], s[4:5]
	s_nop 0
	v_add_u32_e32 v250, 0xb4200, v168
	global_store_dwordx4 v250, v[12:15], s[4:5]
	s_nop 0
	s_and_b64 s[2:3], s[6:7], exec
	s_cbranch_scc0 .LepD_nonext
	s_xor_b32 s101, s101, 1
	s_or_b32 s101, s101, 2
	s_and_b32 s55, s101, 1
	s_mulk_i32 s55, 0x1800
	s_add_i32 s55, s55, 0x22c00
	v_readfirstlane_b32 s57, v230
	s_cmp_lt_u32 s57, 64
	s_cbranch_scc0 .LepD_nfe
	s_add_i32 s4, s56, 0
	s_ashr_i32 s4, s4, 2
	s_add_i32 s4, s4, 1
	s_cmp_gt_i32 s56, -1
	s_cselect_b32 s4, s4, 0
	s_mul_hi_i32 s5, s4, 0x5800
	s_mulk_i32 s4, 0x5800
	v_readlane_b32 s57, v254, 49
	v_readlane_b32 s99, v254, 50
	s_nop 0
	s_add_u32 s4, s57, s4
	s_addc_u32 s5, s99, s5
	v_readlane_b32 s2, v254, 5
	v_readlane_b32 s3, v254, 6
	v_readlane_b32 s28, v254, 7
	v_readlane_b32 s29, v254, 8
	s_nop 0
	v_and_b32_e32 v238, 63, v230
	v_lshrrev_b32_e32 v239, 5, v238
	v_and_b32_e32 v240, 31, v238
	v_lshlrev_b32_e32 v240, 4, v240
	s_lshl_b32 s57, s54, 9
	v_add_u32_e32 v240, s57, v240
	v_mul_u32_u24_e32 v241, 0x2c00, v239
	v_mul_u32_u24_e32 v242, 0x5800, v239
	v_add_u32_e32 v241, v241, v240
	v_add_u32_e32 v242, v242, v240
	v_lshlrev_b32_e32 v243, 4, v238
	s_lshl_b32 s57, s56, 10
	v_add_u32_e32 v243, s57, v243
	s_mov_b32 m0, s55
	s_nop 0
	global_load_lds_dwordx4 v243, s[12:13]
	s_add_i32 m0, s55, 1024
	s_nop 0
	global_load_lds_dwordx4 v241, s[4:5]
	s_add_i32 m0, s55, 2048
	s_nop 0
	global_load_lds_dwordx4 v242, s[2:3]
	v_add_u32_e32 v243, 0x2c00, v242
	s_add_i32 m0, s55, 3072
	s_nop 0
	global_load_lds_dwordx4 v243, s[2:3]
	v_add_u32_e32 v243, 0xb000, v241
	s_add_i32 m0, s55, 4096
	s_nop 0
	global_load_lds_dwordx4 v243, s[2:3]
	s_add_i32 m0, s55, 5120
	s_nop 0
	global_load_lds_dwordx4 v241, s[28:29]

.LepA_fast:
	s_mov_b32 s40, 0xbfb8aa3b
	s_mov_b32 s41, 0xbfb8aa3b
	s_mov_b32 s54, 1.0
	s_mov_b32 s55, 1.0
	s_and_b32 s27, s12, 1
	v_and_b32_e32 v237, 15, v164
	v_and_b32_e32 v236, 64, v164
	v_lshl_add_u32 v236, v237, 2, v236
	v_mul_u32_u24_e32 v171, 0x1600, v236
	v_lshl_add_u32 v171, v166, 1, v171
	v_lshl_add_u32 v236, v236, 2, s32
	v_lshl_add_u32 v229, v166, 2, s32
	ds_read_b128 v[208:211], v236
	ds_read_b128 v[212:215], v236 offset:512
	ds_read_b128 v[200:203], v229 offset:1024
	ds_read_b128 v[204:207], v229 offset:1040
	ds_read_b128 v[216:219], v229 offset:1536
	ds_read_b128 v[220:223], v229 offset:1552
	ds_read_b128 v[128:131], v229 offset:2048
	ds_read_b128 v[132:135], v229 offset:2560
	ds_read_b128 v[136:139], v229 offset:4096
	ds_read_b128 v[140:143], v229 offset:5120
	ds_read_b128 v[160:163], v229 offset:3072
	ds_read_b128 v[172:175], v229 offset:3584
	ds_read_b128 v[176:179], v229 offset:4608
	ds_read_b128 v[180:183], v229 offset:5632
	s_mul_i32 s4, s8, 0x160000
	s_lshl_b32 s79, s9, 8
	s_add_i32 s4, s4, s79
	s_add_i32 s4, s4, 0x9300000
	s_add_u32 s4, s4, s70
	s_addc_u32 s5, s71, 0
	s_mov_b32 s79, 0x20800
	v_lshl_add_u32 v228, v166, 2, s79
	v_cmp_eq_u32_e64 s[36:37], 0, v237
	v_cmp_eq_u32_e64 s[38:39], 15, v237
	v_and_b32_e32 v231, 8, v237
	v_lshlrev_b32_e32 v231, 9, v231
	s_lshl_b32 s79, s27, 10
	v_add3_u32 v231, v231, v228, s79
	s_waitcnt lgkmcnt(12)
	v_fmamk_f32 v208, v208, 0x3a800000, v170
	v_fmamk_f32 v209, v209, 0x3a800000, v170
	v_fmamk_f32 v210, v210, 0x3a800000, v170
	v_fmamk_f32 v211, v211, 0x3a800000, v170
	v_fmamk_f32 v212, v212, 0x3a800000, v170
	v_fmamk_f32 v213, v213, 0x3a800000, v170
	v_fmamk_f32 v214, v214, 0x3a800000, v170
	v_fmamk_f32 v215, v215, 0x3a800000, v170
	s_mov_b32 s79, 0x800000
	v_mul_f32_e32 v224, 0x4b800000, v208
	v_mul_f32_e32 v225, 0x4b800000, v209
	v_mul_f32_e32 v226, 0x4b800000, v210
	v_mul_f32_e32 v227, 0x4b800000, v211
	v_mul_f32_e32 v232, 0x4b800000, v212
	v_mul_f32_e32 v233, 0x4b800000, v213
	v_mul_f32_e32 v234, 0x4b800000, v214
	v_mul_f32_e32 v235, 0x4b800000, v215
	v_cmp_gt_f32_e32 vcc, s79, v208
	s_nop 1
	v_cndmask_b32_e32 v208, v208, v224, vcc
	v_rsq_f32_e32 v208, v208
	s_nop 0
	v_mul_f32_e32 v224, 0x45800000, v208
	v_cndmask_b32_e32 v208, v208, v224, vcc
	v_cmp_gt_f32_e32 vcc, s79, v209
	s_nop 1
	v_cndmask_b32_e32 v209, v209, v225, vcc
	v_rsq_f32_e32 v209, v209
	s_nop 0
	v_mul_f32_e32 v225, 0x45800000, v209
	v_cndmask_b32_e32 v209, v209, v225, vcc
	v_cmp_gt_f32_e32 vcc, s79, v210
	s_nop 1
	v_cndmask_b32_e32 v210, v210, v226, vcc
	v_rsq_f32_e32 v210, v210
	s_nop 0
	v_mul_f32_e32 v226, 0x45800000, v210
	v_cndmask_b32_e32 v210, v210, v226, vcc
	v_cmp_gt_f32_e32 vcc, s79, v211
	s_nop 1
	v_cndmask_b32_e32 v211, v211, v227, vcc
	v_rsq_f32_e32 v211, v211
	s_nop 0
	v_mul_f32_e32 v227, 0x45800000, v211
	v_cndmask_b32_e32 v211, v211, v227, vcc
	v_cmp_gt_f32_e32 vcc, s79, v212
	s_nop 1
	v_cndmask_b32_e32 v212, v212, v232, vcc
	v_rsq_f32_e32 v212, v212
	s_nop 0
	v_mul_f32_e32 v232, 0x45800000, v212
	v_cndmask_b32_e32 v212, v212, v232, vcc
	v_cmp_gt_f32_e32 vcc, s79, v213
	s_nop 1
	v_cndmask_b32_e32 v213, v213, v233, vcc
	v_rsq_f32_e32 v213, v213
	s_nop 0
	v_mul_f32_e32 v233, 0x45800000, v213
	v_cndmask_b32_e32 v213, v213, v233, vcc
	v_cmp_gt_f32_e32 vcc, s79, v214
	s_nop 1
	v_cndmask_b32_e32 v214, v214, v234, vcc
	v_rsq_f32_e32 v214, v214
	s_nop 0
	v_mul_f32_e32 v234, 0x45800000, v214
	v_cndmask_b32_e32 v214, v214, v234, vcc
	v_cmp_gt_f32_e32 vcc, s79, v215
	s_nop 1
	v_cndmask_b32_e32 v215, v215, v235, vcc
	v_rsq_f32_e32 v215, v215
	s_nop 0
	v_mul_f32_e32 v235, 0x45800000, v215
	v_cndmask_b32_e32 v215, v215, v235, vcc
	s_waitcnt lgkmcnt(8)
	v_pk_fma_f32 v[124:125], v[124:125], v[208:209], v[200:201] op_sel:[0,0,0] op_sel_hi:[1,0,1]
	v_pk_fma_f32 v[126:127], v[126:127], v[208:209], v[202:203] op_sel:[0,0,0] op_sel_hi:[1,0,1]
	v_pk_fma_f32 v[120:121], v[120:121], v[208:209], v[204:205] op_sel:[0,0,0] op_sel_hi:[1,0,1]
	v_pk_fma_f32 v[122:123], v[122:123], v[208:209], v[206:207] op_sel:[0,0,0] op_sel_hi:[1,0,1]
	v_pk_fma_f32 v[108:109], v[108:109], v[208:209], v[216:217] op_sel:[0,0,0] op_sel_hi:[1,0,1]
	v_pk_fma_f32 v[110:111], v[110:111], v[208:209], v[218:219] op_sel:[0,0,0] op_sel_hi:[1,0,1]
	v_pk_fma_f32 v[104:105], v[104:105], v[208:209], v[220:221] op_sel:[0,0,0] op_sel_hi:[1,0,1]
	v_pk_fma_f32 v[106:107], v[106:107], v[208:209], v[222:223] op_sel:[0,0,0] op_sel_hi:[1,0,1]
	v_pk_fma_f32 v[116:117], v[116:117], v[208:209], v[200:201] op_sel:[0,1,0] op_sel_hi:[1,1,1]
	v_pk_fma_f32 v[118:119], v[118:119], v[208:209], v[202:203] op_sel:[0,1,0] op_sel_hi:[1,1,1]
	v_pk_fma_f32 v[112:113], v[112:113], v[208:209], v[204:205] op_sel:[0,1,0] op_sel_hi:[1,1,1]
	v_pk_fma_f32 v[114:115], v[114:115], v[208:209], v[206:207] op_sel:[0,1,0] op_sel_hi:[1,1,1]
	v_pk_fma_f32 v[100:101], v[100:101], v[208:209], v[216:217] op_sel:[0,1,0] op_sel_hi:[1,1,1]
	v_pk_fma_f32 v[102:103], v[102:103], v[208:209], v[218:219] op_sel:[0,1,0] op_sel_hi:[1,1,1]
	v_pk_fma_f32 v[92:93], v[92:93], v[208:209], v[220:221] op_sel:[0,1,0] op_sel_hi:[1,1,1]
	v_pk_fma_f32 v[94:95], v[94:95], v[208:209], v[222:223] op_sel:[0,1,0] op_sel_hi:[1,1,1]
	v_pk_fma_f32 v[96:97], v[96:97], v[210:211], v[200:201] op_sel:[0,0,0] op_sel_hi:[1,0,1]
	v_pk_fma_f32 v[98:99], v[98:99], v[210:211], v[202:203] op_sel:[0,0,0] op_sel_hi:[1,0,1]
	v_pk_fma_f32 v[88:89], v[88:89], v[210:211], v[204:205] op_sel:[0,0,0] op_sel_hi:[1,0,1]
	v_pk_fma_f32 v[90:91], v[90:91], v[210:211], v[206:207] op_sel:[0,0,0] op_sel_hi:[1,0,1]
	v_pk_fma_f32 v[84:85], v[84:85], v[210:211], v[216:217] op_sel:[0,0,0] op_sel_hi:[1,0,1]
	v_pk_fma_f32 v[86:87], v[86:87], v[210:211], v[218:219] op_sel:[0,0,0] op_sel_hi:[1,0,1]
	v_pk_fma_f32 v[76:77], v[76:77], v[210:211], v[220:221] op_sel:[0,0,0] op_sel_hi:[1,0,1]
	v_pk_fma_f32 v[78:79], v[78:79], v[210:211], v[222:223] op_sel:[0,0,0] op_sel_hi:[1,0,1]
	v_pk_fma_f32 v[80:81], v[80:81], v[210:211], v[200:201] op_sel:[0,1,0] op_sel_hi:[1,1,1]
	v_pk_fma_f32 v[82:83], v[82:83], v[210:211], v[202:203] op_sel:[0,1,0] op_sel_hi:[1,1,1]
	v_pk_fma_f32 v[72:73], v[72:73], v[210:211], v[204:205] op_sel:[0,1,0] op_sel_hi:[1,1,1]
	v_pk_fma_f32 v[74:75], v[74:75], v[210:211], v[206:207] op_sel:[0,1,0] op_sel_hi:[1,1,1]
	v_pk_fma_f32 v[68:69], v[68:69], v[210:211], v[216:217] op_sel:[0,1,0] op_sel_hi:[1,1,1]
	v_pk_fma_f32 v[70:71], v[70:71], v[210:211], v[218:219] op_sel:[0,1,0] op_sel_hi:[1,1,1]
	v_pk_fma_f32 v[64:65], v[64:65], v[210:211], v[220:221] op_sel:[0,1,0] op_sel_hi:[1,1,1]
	v_pk_fma_f32 v[66:67], v[66:67], v[210:211], v[222:223] op_sel:[0,1,0] op_sel_hi:[1,1,1]
	v_pk_fma_f32 v[60:61], v[60:61], v[212:213], v[200:201] op_sel:[0,0,0] op_sel_hi:[1,0,1]
	v_pk_fma_f32 v[62:63], v[62:63], v[212:213], v[202:203] op_sel:[0,0,0] op_sel_hi:[1,0,1]
	v_pk_fma_f32 v[56:57], v[56:57], v[212:213], v[204:205] op_sel:[0,0,0] op_sel_hi:[1,0,1]
	v_pk_fma_f32 v[58:59], v[58:59], v[212:213], v[206:207] op_sel:[0,0,0] op_sel_hi:[1,0,1]
	v_pk_fma_f32 v[52:53], v[52:53], v[212:213], v[216:217] op_sel:[0,0,0] op_sel_hi:[1,0,1]
	v_pk_fma_f32 v[54:55], v[54:55], v[212:213], v[218:219] op_sel:[0,0,0] op_sel_hi:[1,0,1]
	v_pk_fma_f32 v[44:45], v[44:45], v[212:213], v[220:221] op_sel:[0,0,0] op_sel_hi:[1,0,1]
	v_pk_fma_f32 v[46:47], v[46:47], v[212:213], v[222:223] op_sel:[0,0,0] op_sel_hi:[1,0,1]
	v_pk_fma_f32 v[48:49], v[48:49], v[212:213], v[200:201] op_sel:[0,1,0] op_sel_hi:[1,1,1]
	v_pk_fma_f32 v[50:51], v[50:51], v[212:213], v[202:203] op_sel:[0,1,0] op_sel_hi:[1,1,1]
	v_pk_fma_f32 v[40:41], v[40:41], v[212:213], v[204:205] op_sel:[0,1,0] op_sel_hi:[1,1,1]
	v_pk_fma_f32 v[42:43], v[42:43], v[212:213], v[206:207] op_sel:[0,1,0] op_sel_hi:[1,1,1]
	v_pk_fma_f32 v[36:37], v[36:37], v[212:213], v[216:217] op_sel:[0,1,0] op_sel_hi:[1,1,1]
	v_pk_fma_f32 v[38:39], v[38:39], v[212:213], v[218:219] op_sel:[0,1,0] op_sel_hi:[1,1,1]
	v_pk_fma_f32 v[28:29], v[28:29], v[212:213], v[220:221] op_sel:[0,1,0] op_sel_hi:[1,1,1]
	v_pk_fma_f32 v[30:31], v[30:31], v[212:213], v[222:223] op_sel:[0,1,0] op_sel_hi:[1,1,1]
	v_pk_fma_f32 v[32:33], v[32:33], v[214:215], v[200:201] op_sel:[0,0,0] op_sel_hi:[1,0,1]
	v_pk_fma_f32 v[34:35], v[34:35], v[214:215], v[202:203] op_sel:[0,0,0] op_sel_hi:[1,0,1]
	v_pk_fma_f32 v[24:25], v[24:25], v[214:215], v[204:205] op_sel:[0,0,0] op_sel_hi:[1,0,1]
	v_pk_fma_f32 v[26:27], v[26:27], v[214:215], v[206:207] op_sel:[0,0,0] op_sel_hi:[1,0,1]
	v_pk_fma_f32 v[20:21], v[20:21], v[214:215], v[216:217] op_sel:[0,0,0] op_sel_hi:[1,0,1]
	v_pk_fma_f32 v[22:23], v[22:23], v[214:215], v[218:219] op_sel:[0,0,0] op_sel_hi:[1,0,1]
	v_pk_fma_f32 v[12:13], v[12:13], v[214:215], v[220:221] op_sel:[0,0,0] op_sel_hi:[1,0,1]
	v_pk_fma_f32 v[14:15], v[14:15], v[214:215], v[222:223] op_sel:[0,0,0] op_sel_hi:[1,0,1]
	v_pk_fma_f32 v[16:17], v[16:17], v[214:215], v[200:201] op_sel:[0,1,0] op_sel_hi:[1,1,1]
	v_pk_fma_f32 v[18:19], v[18:19], v[214:215], v[202:203] op_sel:[0,1,0] op_sel_hi:[1,1,1]
	v_pk_fma_f32 v[8:9], v[8:9], v[214:215], v[204:205] op_sel:[0,1,0] op_sel_hi:[1,1,1]
	v_pk_fma_f32 v[10:11], v[10:11], v[214:215], v[206:207] op_sel:[0,1,0] op_sel_hi:[1,1,1]
	v_pk_fma_f32 v[4:5], v[4:5], v[214:215], v[216:217] op_sel:[0,1,0] op_sel_hi:[1,1,1]
	v_pk_fma_f32 v[6:7], v[6:7], v[214:215], v[218:219] op_sel:[0,1,0] op_sel_hi:[1,1,1]
	v_pk_fma_f32 v[0:1], v[0:1], v[214:215], v[220:221] op_sel:[0,1,0] op_sel_hi:[1,1,1]
	v_pk_fma_f32 v[2:3], v[2:3], v[214:215], v[222:223] op_sel:[0,1,0] op_sel_hi:[1,1,1]
	v_mov_b32_e32 v212, 0
	v_mov_b32_e32 v213, 0
	v_mov_b32_e32 v214, 0
	v_mov_b32_e32 v215, 0
	s_lshl_b32 s96, s27, 12
	s_sub_i32 s96, 0x2000, s96
	s_mul_i32 s94, s27, 0x1400
	s_add_i32 s94, s94, 0xc00
	s_lshl_b32 s79, s27, 10
	s_add_i32 s95, s79, 5120
	s_add_i32 s92, s79, 1024
	s_mov_b64 exec, s[36:37]
	v_add_u32_e32 v250, s96, v228
	ds_write_b128 v250, v[124:127] offset:0
	ds_write_b128 v250, v[120:123] offset:16
	ds_write_b128 v250, v[108:111] offset:512
	ds_write_b128 v250, v[104:107] offset:528
	v_add_u32_e32 v250, s95, v228
	ds_write_b128 v250, v[60:63] offset:0
	ds_write_b128 v250, v[56:59] offset:16
	ds_write_b128 v250, v[52:55] offset:512
	ds_write_b128 v250, v[44:47] offset:528
	ds_write_b128 v228, v[212:215] offset:0
	ds_write_b128 v228, v[212:215] offset:16
	ds_write_b128 v228, v[212:215] offset:512
	ds_write_b128 v228, v[212:215] offset:528
	s_mov_b64 exec, s[38:39]
	v_add_u32_e32 v251, s92, v228
	ds_write_b128 v251, v[80:83] offset:0
	ds_write_b128 v251, v[72:75] offset:16
	ds_write_b128 v251, v[68:71] offset:512
	ds_write_b128 v251, v[64:67] offset:528
	v_add_u32_e32 v251, s94, v228
	ds_write_b128 v251, v[16:19] offset:0
	ds_write_b128 v251, v[8:11] offset:16
	ds_write_b128 v251, v[4:7] offset:512
	ds_write_b128 v251, v[0:3] offset:528
	ds_write_b128 v228, v[212:215] offset:7168
	ds_write_b128 v228, v[212:215] offset:7184
	ds_write_b128 v228, v[212:215] offset:7680
	ds_write_b128 v228, v[212:215] offset:7696
	s_mov_b64 exec, -1
	s_waitcnt lgkmcnt(0)
	s_barrier
	ds_read_b128 v[184:187], v231 offset:0
	ds_read_b128 v[188:191], v231 offset:512
	ds_read_b128 v[192:195], v231 offset:2048
	ds_read_b128 v[196:199], v231 offset:2560
	s_nop 0
	v_cndmask_b32_e64 v216, 0, v128, s[36:37]
	v_cndmask_b32_e64 v220, 0, v136, s[38:39]
	v_cndmask_b32_e64 v217, 0, v129, s[36:37]
	v_cndmask_b32_e64 v221, 0, v137, s[38:39]
	v_cndmask_b32_e64 v218, 0, v130, s[36:37]
	v_cndmask_b32_e64 v222, 0, v138, s[38:39]
	v_cndmask_b32_e64 v219, 0, v131, s[36:37]
	v_cndmask_b32_e64 v223, 0, v139, s[38:39]
	v_cndmask_b32_e64 v224, 0, v160, s[36:37]
	v_cndmask_b32_e64 v232, 0, v176, s[38:39]
	v_cndmask_b32_e64 v225, 0, v161, s[36:37]
	v_cndmask_b32_e64 v233, 0, v177, s[38:39]
	v_cndmask_b32_e64 v226, 0, v162, s[36:37]
	v_cndmask_b32_e64 v234, 0, v178, s[38:39]
	v_cndmask_b32_e64 v227, 0, v163, s[36:37]
	v_cndmask_b32_e64 v235, 0, v179, s[38:39]
	s_waitcnt lgkmcnt(0)
	s_nop 1
	v_pk_fma_f32 v[200:201], v[132:133], v[124:125], v[140:141]
	v_pk_fma_f32 v[202:203], v[134:135], v[126:127], v[142:143]
	v_fmac_f32_dpp v200, v80, v128 row_shr:1 row_mask:0xf bank_mask:0xf
	v_fmac_f32_dpp v201, v81, v129 row_shr:1 row_mask:0xf bank_mask:0xf
	v_fmac_f32_dpp v202, v82, v130 row_shr:1 row_mask:0xf bank_mask:0xf
	v_fmac_f32_dpp v203, v83, v131 row_shr:1 row_mask:0xf bank_mask:0xf
	v_pk_fma_f32 v[200:201], v[184:185], v[216:217], v[200:201]
	v_pk_fma_f32 v[202:203], v[186:187], v[218:219], v[202:203]
	v_pk_fma_f32 v[200:201], v[116:117], v[136:137], v[200:201]
	v_pk_fma_f32 v[202:203], v[118:119], v[138:139], v[202:203]
	v_pk_fma_f32 v[204:205], v[172:173], v[108:109], v[180:181]
	v_pk_fma_f32 v[206:207], v[174:175], v[110:111], v[182:183]
	v_fmac_f32_dpp v204, v68, v160 row_shr:1 row_mask:0xf bank_mask:0xf
	v_fmac_f32_dpp v205, v69, v161 row_shr:1 row_mask:0xf bank_mask:0xf
	v_fmac_f32_dpp v206, v70, v162 row_shr:1 row_mask:0xf bank_mask:0xf
	v_fmac_f32_dpp v207, v71, v163 row_shr:1 row_mask:0xf bank_mask:0xf
	v_pk_fma_f32 v[204:205], v[188:189], v[224:225], v[204:205]
	v_pk_fma_f32 v[206:207], v[190:191], v[226:227], v[206:207]
	v_pk_fma_f32 v[204:205], v[100:101], v[176:177], v[204:205]
	v_pk_fma_f32 v[206:207], v[102:103], v[178:179], v[206:207]
	v_pk_mul_f32 v[208:209], v[200:201], s[40:41]
	v_pk_mul_f32 v[210:211], v[202:203], s[40:41]
	v_exp_f32_e32 v208, v208
	v_exp_f32_e32 v209, v209
	v_exp_f32_e32 v210, v210
	v_exp_f32_e32 v211, v211
	v_pk_add_f32 v[208:209], v[208:209], s[54:55]
	v_pk_add_f32 v[210:211], v[210:211], s[54:55]
	v_rcp_f32_e32 v208, v208
	v_rcp_f32_e32 v209, v209
	v_rcp_f32_e32 v210, v210
	v_rcp_f32_e32 v211, v211
	v_pk_mul_f32 v[200:201], v[200:201], v[208:209]
	v_pk_mul_f32 v[202:203], v[202:203], v[210:211]
	v_pk_mul_f32 v[200:201], v[200:201], v[204:205]
	v_pk_mul_f32 v[202:203], v[202:203], v[206:207]
	v_cvt_pk_bf16_f32 v236, v200, v201
	v_cvt_pk_bf16_f32 v237, v202, v203
	v_pk_fma_f32 v[200:201], v[132:133], v[116:117], v[140:141]
	v_pk_fma_f32 v[202:203], v[134:135], v[118:119], v[142:143]
	v_pk_fma_f32 v[200:201], v[124:125], v[128:129], v[200:201]
	v_pk_fma_f32 v[202:203], v[126:127], v[130:131], v[202:203]
	v_pk_fma_f32 v[200:201], v[96:97], v[136:137], v[200:201]
	v_pk_fma_f32 v[202:203], v[98:99], v[138:139], v[202:203]
	v_pk_fma_f32 v[204:205], v[172:173], v[100:101], v[180:181]
	v_pk_fma_f32 v[206:207], v[174:175], v[102:103], v[182:183]
	v_pk_fma_f32 v[204:205], v[108:109], v[160:161], v[204:205]
	v_pk_fma_f32 v[206:207], v[110:111], v[162:163], v[206:207]
	v_pk_fma_f32 v[204:205], v[84:85], v[176:177], v[204:205]
	v_pk_fma_f32 v[206:207], v[86:87], v[178:179], v[206:207]
	v_pk_mul_f32 v[208:209], v[200:201], s[40:41]
	v_pk_mul_f32 v[210:211], v[202:203], s[40:41]
	v_exp_f32_e32 v208, v208
	v_exp_f32_e32 v209, v209
	v_exp_f32_e32 v210, v210
	v_exp_f32_e32 v211, v211
	v_pk_add_f32 v[208:209], v[208:209], s[54:55]
	v_pk_add_f32 v[210:211], v[210:211], s[54:55]
	v_rcp_f32_e32 v208, v208
	v_rcp_f32_e32 v209, v209
	v_rcp_f32_e32 v210, v210
	v_rcp_f32_e32 v211, v211
	v_pk_mul_f32 v[200:201], v[200:201], v[208:209]
	v_pk_mul_f32 v[202:203], v[202:203], v[210:211]
	v_pk_mul_f32 v[200:201], v[200:201], v[204:205]
	v_pk_mul_f32 v[202:203], v[202:203], v[206:207]
	v_cvt_pk_bf16_f32 v238, v200, v201
	v_cvt_pk_bf16_f32 v239, v202, v203
	v_pk_fma_f32 v[200:201], v[132:133], v[96:97], v[140:141]
	v_pk_fma_f32 v[202:203], v[134:135], v[98:99], v[142:143]
	v_pk_fma_f32 v[200:201], v[116:117], v[128:129], v[200:201]
	v_pk_fma_f32 v[202:203], v[118:119], v[130:131], v[202:203]
	v_pk_fma_f32 v[200:201], v[80:81], v[136:137], v[200:201]
	v_pk_fma_f32 v[202:203], v[82:83], v[138:139], v[202:203]
	v_pk_fma_f32 v[204:205], v[172:173], v[84:85], v[180:181]
	v_pk_fma_f32 v[206:207], v[174:175], v[86:87], v[182:183]
	v_pk_fma_f32 v[204:205], v[100:101], v[160:161], v[204:205]
	v_pk_fma_f32 v[206:207], v[102:103], v[162:163], v[206:207]
	v_pk_fma_f32 v[204:205], v[68:69], v[176:177], v[204:205]
	v_pk_fma_f32 v[206:207], v[70:71], v[178:179], v[206:207]
	v_pk_mul_f32 v[208:209], v[200:201], s[40:41]
	v_pk_mul_f32 v[210:211], v[202:203], s[40:41]
	v_exp_f32_e32 v208, v208
	v_exp_f32_e32 v209, v209
	v_exp_f32_e32 v210, v210
	v_exp_f32_e32 v211, v211
	v_pk_add_f32 v[208:209], v[208:209], s[54:55]
	v_pk_add_f32 v[210:211], v[210:211], s[54:55]
	v_rcp_f32_e32 v208, v208
	v_rcp_f32_e32 v209, v209
	v_rcp_f32_e32 v210, v210
	v_rcp_f32_e32 v211, v211
	v_pk_mul_f32 v[200:201], v[200:201], v[208:209]
	v_pk_mul_f32 v[202:203], v[202:203], v[210:211]
	v_pk_mul_f32 v[200:201], v[200:201], v[204:205]
	v_pk_mul_f32 v[202:203], v[202:203], v[206:207]
	v_cvt_pk_bf16_f32 v240, v200, v201
	v_cvt_pk_bf16_f32 v241, v202, v203
	v_pk_fma_f32 v[200:201], v[132:133], v[80:81], v[140:141]
	v_pk_fma_f32 v[202:203], v[134:135], v[82:83], v[142:143]
	v_pk_fma_f32 v[200:201], v[96:97], v[128:129], v[200:201]
	v_pk_fma_f32 v[202:203], v[98:99], v[130:131], v[202:203]
	v_fmac_f32_dpp v200, v124, v136 row_shl:1 row_mask:0xf bank_mask:0xf
	v_fmac_f32_dpp v201, v125, v137 row_shl:1 row_mask:0xf bank_mask:0xf
	v_fmac_f32_dpp v202, v126, v138 row_shl:1 row_mask:0xf bank_mask:0xf
	v_fmac_f32_dpp v203, v127, v139 row_shl:1 row_mask:0xf bank_mask:0xf
	v_pk_fma_f32 v[200:201], v[184:185], v[220:221], v[200:201]
	v_pk_fma_f32 v[202:203], v[186:187], v[222:223], v[202:203]
	v_pk_fma_f32 v[204:205], v[172:173], v[68:69], v[180:181]
	v_pk_fma_f32 v[206:207], v[174:175], v[70:71], v[182:183]
	v_pk_fma_f32 v[204:205], v[84:85], v[160:161], v[204:205]
	v_pk_fma_f32 v[206:207], v[86:87], v[162:163], v[206:207]
	v_fmac_f32_dpp v204, v108, v176 row_shl:1 row_mask:0xf bank_mask:0xf
	v_fmac_f32_dpp v205, v109, v177 row_shl:1 row_mask:0xf bank_mask:0xf
	v_fmac_f32_dpp v206, v110, v178 row_shl:1 row_mask:0xf bank_mask:0xf
	v_fmac_f32_dpp v207, v111, v179 row_shl:1 row_mask:0xf bank_mask:0xf
	v_pk_fma_f32 v[204:205], v[188:189], v[232:233], v[204:205]
	v_pk_fma_f32 v[206:207], v[190:191], v[234:235], v[206:207]
	v_pk_mul_f32 v[208:209], v[200:201], s[40:41]
	v_pk_mul_f32 v[210:211], v[202:203], s[40:41]
	v_exp_f32_e32 v208, v208
	v_exp_f32_e32 v209, v209
	v_exp_f32_e32 v210, v210
	v_exp_f32_e32 v211, v211
	v_pk_add_f32 v[208:209], v[208:209], s[54:55]
	v_pk_add_f32 v[210:211], v[210:211], s[54:55]
	v_rcp_f32_e32 v208, v208
	v_rcp_f32_e32 v209, v209
	v_rcp_f32_e32 v210, v210
	v_rcp_f32_e32 v211, v211
	v_pk_mul_f32 v[200:201], v[200:201], v[208:209]
	v_pk_mul_f32 v[202:203], v[202:203], v[210:211]
	v_pk_mul_f32 v[200:201], v[200:201], v[204:205]
	v_pk_mul_f32 v[202:203], v[202:203], v[206:207]
	v_cvt_pk_bf16_f32 v242, v200, v201
	v_cvt_pk_bf16_f32 v243, v202, v203
	v_pk_fma_f32 v[200:201], v[132:133], v[60:61], v[140:141]
	v_pk_fma_f32 v[202:203], v[134:135], v[62:63], v[142:143]
	v_fmac_f32_dpp v200, v16, v128 row_shr:1 row_mask:0xf bank_mask:0xf
	v_fmac_f32_dpp v201, v17, v129 row_shr:1 row_mask:0xf bank_mask:0xf
	v_fmac_f32_dpp v202, v18, v130 row_shr:1 row_mask:0xf bank_mask:0xf
	v_fmac_f32_dpp v203, v19, v131 row_shr:1 row_mask:0xf bank_mask:0xf
	v_pk_fma_f32 v[200:201], v[192:193], v[216:217], v[200:201]
	v_pk_fma_f32 v[202:203], v[194:195], v[218:219], v[202:203]
	v_pk_fma_f32 v[200:201], v[48:49], v[136:137], v[200:201]
	v_pk_fma_f32 v[202:203], v[50:51], v[138:139], v[202:203]
	v_pk_fma_f32 v[204:205], v[172:173], v[52:53], v[180:181]
	v_pk_fma_f32 v[206:207], v[174:175], v[54:55], v[182:183]
	v_fmac_f32_dpp v204, v4, v160 row_shr:1 row_mask:0xf bank_mask:0xf
	v_fmac_f32_dpp v205, v5, v161 row_shr:1 row_mask:0xf bank_mask:0xf
	v_fmac_f32_dpp v206, v6, v162 row_shr:1 row_mask:0xf bank_mask:0xf
	v_fmac_f32_dpp v207, v7, v163 row_shr:1 row_mask:0xf bank_mask:0xf
	v_pk_fma_f32 v[204:205], v[196:197], v[224:225], v[204:205]
	v_pk_fma_f32 v[206:207], v[198:199], v[226:227], v[206:207]
	v_pk_fma_f32 v[204:205], v[36:37], v[176:177], v[204:205]
	v_pk_fma_f32 v[206:207], v[38:39], v[178:179], v[206:207]
	v_pk_mul_f32 v[208:209], v[200:201], s[40:41]
	v_pk_mul_f32 v[210:211], v[202:203], s[40:41]
	v_exp_f32_e32 v208, v208
	v_exp_f32_e32 v209, v209
	v_exp_f32_e32 v210, v210
	v_exp_f32_e32 v211, v211
	v_pk_add_f32 v[208:209], v[208:209], s[54:55]
	v_pk_add_f32 v[210:211], v[210:211], s[54:55]
	v_rcp_f32_e32 v208, v208
	v_rcp_f32_e32 v209, v209
	v_rcp_f32_e32 v210, v210
	v_rcp_f32_e32 v211, v211
	v_pk_mul_f32 v[200:201], v[200:201], v[208:209]
	v_pk_mul_f32 v[202:203], v[202:203], v[210:211]
	v_pk_mul_f32 v[200:201], v[200:201], v[204:205]
	v_pk_mul_f32 v[202:203], v[202:203], v[206:207]
	v_cvt_pk_bf16_f32 v244, v200, v201
	v_cvt_pk_bf16_f32 v245, v202, v203
	v_pk_fma_f32 v[200:201], v[132:133], v[48:49], v[140:141]
	v_pk_fma_f32 v[202:203], v[134:135], v[50:51], v[142:143]
	v_pk_fma_f32 v[200:201], v[60:61], v[128:129], v[200:201]
	v_pk_fma_f32 v[202:203], v[62:63], v[130:131], v[202:203]
	v_pk_fma_f32 v[200:201], v[32:33], v[136:137], v[200:201]
	v_pk_fma_f32 v[202:203], v[34:35], v[138:139], v[202:203]
	v_pk_fma_f32 v[204:205], v[172:173], v[36:37], v[180:181]
	v_pk_fma_f32 v[206:207], v[174:175], v[38:39], v[182:183]
	v_pk_fma_f32 v[204:205], v[52:53], v[160:161], v[204:205]
	v_pk_fma_f32 v[206:207], v[54:55], v[162:163], v[206:207]
	v_pk_fma_f32 v[204:205], v[20:21], v[176:177], v[204:205]
	v_pk_fma_f32 v[206:207], v[22:23], v[178:179], v[206:207]
	v_pk_mul_f32 v[208:209], v[200:201], s[40:41]
	v_pk_mul_f32 v[210:211], v[202:203], s[40:41]
	v_exp_f32_e32 v208, v208
	v_exp_f32_e32 v209, v209
	v_exp_f32_e32 v210, v210
	v_exp_f32_e32 v211, v211
	v_pk_add_f32 v[208:209], v[208:209], s[54:55]
	v_pk_add_f32 v[210:211], v[210:211], s[54:55]
	v_rcp_f32_e32 v208, v208
	v_rcp_f32_e32 v209, v209
	v_rcp_f32_e32 v210, v210
	v_rcp_f32_e32 v211, v211
	v_pk_mul_f32 v[200:201], v[200:201], v[208:209]
	v_pk_mul_f32 v[202:203], v[202:203], v[210:211]
	v_pk_mul_f32 v[200:201], v[200:201], v[204:205]
	v_pk_mul_f32 v[202:203], v[202:203], v[206:207]
	v_cvt_pk_bf16_f32 v246, v200, v201
	v_cvt_pk_bf16_f32 v247, v202, v203
	v_pk_fma_f32 v[200:201], v[132:133], v[32:33], v[140:141]
	v_pk_fma_f32 v[202:203], v[134:135], v[34:35], v[142:143]
	v_pk_fma_f32 v[200:201], v[48:49], v[128:129], v[200:201]
	v_pk_fma_f32 v[202:203], v[50:51], v[130:131], v[202:203]
	v_pk_fma_f32 v[200:201], v[16:17], v[136:137], v[200:201]
	v_pk_fma_f32 v[202:203], v[18:19], v[138:139], v[202:203]
	v_pk_fma_f32 v[204:205], v[172:173], v[20:21], v[180:181]
	v_pk_fma_f32 v[206:207], v[174:175], v[22:23], v[182:183]
	v_pk_fma_f32 v[204:205], v[36:37], v[160:161], v[204:205]
	v_pk_fma_f32 v[206:207], v[38:39], v[162:163], v[206:207]
	v_pk_fma_f32 v[204:205], v[4:5], v[176:177], v[204:205]
	v_pk_fma_f32 v[206:207], v[6:7], v[178:179], v[206:207]
	v_pk_mul_f32 v[208:209], v[200:201], s[40:41]
	v_pk_mul_f32 v[210:211], v[202:203], s[40:41]
	v_exp_f32_e32 v208, v208
	v_exp_f32_e32 v209, v209
	v_exp_f32_e32 v210, v210
	v_exp_f32_e32 v211, v211
	v_pk_add_f32 v[208:209], v[208:209], s[54:55]
	v_pk_add_f32 v[210:211], v[210:211], s[54:55]
	v_rcp_f32_e32 v208, v208
	v_rcp_f32_e32 v209, v209
	v_rcp_f32_e32 v210, v210
	v_rcp_f32_e32 v211, v211
	v_pk_mul_f32 v[200:201], v[200:201], v[208:209]
	v_pk_mul_f32 v[202:203], v[202:203], v[210:211]
	v_pk_mul_f32 v[200:201], v[200:201], v[204:205]
	v_pk_mul_f32 v[202:203], v[202:203], v[206:207]
	v_cvt_pk_bf16_f32 v248, v200, v201
	v_cvt_pk_bf16_f32 v249, v202, v203
	v_pk_fma_f32 v[200:201], v[132:133], v[16:17], v[140:141]
	v_pk_fma_f32 v[202:203], v[134:135], v[18:19], v[142:143]
	v_pk_fma_f32 v[200:201], v[32:33], v[128:129], v[200:201]
	v_pk_fma_f32 v[202:203], v[34:35], v[130:131], v[202:203]
	v_fmac_f32_dpp v200, v60, v136 row_shl:1 row_mask:0xf bank_mask:0xf
	v_fmac_f32_dpp v201, v61, v137 row_shl:1 row_mask:0xf bank_mask:0xf
	v_fmac_f32_dpp v202, v62, v138 row_shl:1 row_mask:0xf bank_mask:0xf
	v_fmac_f32_dpp v203, v63, v139 row_shl:1 row_mask:0xf bank_mask:0xf
	v_pk_fma_f32 v[200:201], v[192:193], v[220:221], v[200:201]
	v_pk_fma_f32 v[202:203], v[194:195], v[222:223], v[202:203]
	v_pk_fma_f32 v[204:205], v[172:173], v[4:5], v[180:181]
	v_pk_fma_f32 v[206:207], v[174:175], v[6:7], v[182:183]
	v_pk_fma_f32 v[204:205], v[20:21], v[160:161], v[204:205]
	v_pk_fma_f32 v[206:207], v[22:23], v[162:163], v[206:207]
	v_fmac_f32_dpp v204, v52, v176 row_shl:1 row_mask:0xf bank_mask:0xf
	v_fmac_f32_dpp v205, v53, v177 row_shl:1 row_mask:0xf bank_mask:0xf
	v_fmac_f32_dpp v206, v54, v178 row_shl:1 row_mask:0xf bank_mask:0xf
	v_fmac_f32_dpp v207, v55, v179 row_shl:1 row_mask:0xf bank_mask:0xf
	v_pk_fma_f32 v[204:205], v[196:197], v[232:233], v[204:205]
	v_pk_fma_f32 v[206:207], v[198:199], v[234:235], v[206:207]
	v_pk_mul_f32 v[208:209], v[200:201], s[40:41]
	v_pk_mul_f32 v[210:211], v[202:203], s[40:41]
	v_exp_f32_e32 v208, v208
	v_exp_f32_e32 v209, v209
	v_exp_f32_e32 v210, v210
	v_exp_f32_e32 v211, v211
	v_pk_add_f32 v[208:209], v[208:209], s[54:55]
	v_pk_add_f32 v[210:211], v[210:211], s[54:55]
	v_rcp_f32_e32 v208, v208
	v_rcp_f32_e32 v209, v209
	v_rcp_f32_e32 v210, v210
	v_rcp_f32_e32 v211, v211
	v_pk_mul_f32 v[200:201], v[200:201], v[208:209]
	v_pk_mul_f32 v[202:203], v[202:203], v[210:211]
	v_pk_mul_f32 v[200:201], v[200:201], v[204:205]
	v_pk_mul_f32 v[202:203], v[202:203], v[206:207]
	v_cvt_pk_bf16_f32 v250, v200, v201
	v_cvt_pk_bf16_f32 v251, v202, v203
	ds_read_b128 v[128:131], v229 offset:2064
	ds_read_b128 v[132:135], v229 offset:2576
	ds_read_b128 v[136:139], v229 offset:4112
	ds_read_b128 v[140:143], v229 offset:5136
	ds_read_b128 v[160:163], v229 offset:3088
	ds_read_b128 v[172:175], v229 offset:3600
	ds_read_b128 v[176:179], v229 offset:4624
	ds_read_b128 v[180:183], v229 offset:5648
	v_mov_b32_e32 v124, v236
	v_mov_b32_e32 v125, v237
	v_mov_b32_e32 v116, v238
	v_mov_b32_e32 v117, v239
	v_mov_b32_e32 v96, v240
	v_mov_b32_e32 v97, v241
	v_mov_b32_e32 v80, v242
	v_mov_b32_e32 v81, v243
	v_mov_b32_e32 v60, v244
	v_mov_b32_e32 v61, v245
	v_mov_b32_e32 v48, v246
	v_mov_b32_e32 v49, v247
	v_mov_b32_e32 v32, v248
	v_mov_b32_e32 v33, v249
	v_mov_b32_e32 v16, v250
	v_mov_b32_e32 v17, v251
	ds_read_b128 v[184:187], v231 offset:16
	ds_read_b128 v[188:191], v231 offset:528
	ds_read_b128 v[192:195], v231 offset:2064
	ds_read_b128 v[196:199], v231 offset:2576
	s_waitcnt lgkmcnt(4)
	v_cndmask_b32_e64 v216, 0, v128, s[36:37]
	v_cndmask_b32_e64 v220, 0, v136, s[38:39]
	v_cndmask_b32_e64 v217, 0, v129, s[36:37]
	v_cndmask_b32_e64 v221, 0, v137, s[38:39]
	v_cndmask_b32_e64 v218, 0, v130, s[36:37]
	v_cndmask_b32_e64 v222, 0, v138, s[38:39]
	v_cndmask_b32_e64 v219, 0, v131, s[36:37]
	v_cndmask_b32_e64 v223, 0, v139, s[38:39]
	v_cndmask_b32_e64 v224, 0, v160, s[36:37]
	v_cndmask_b32_e64 v232, 0, v176, s[38:39]
	v_cndmask_b32_e64 v225, 0, v161, s[36:37]
	v_cndmask_b32_e64 v233, 0, v177, s[38:39]
	v_cndmask_b32_e64 v226, 0, v162, s[36:37]
	v_cndmask_b32_e64 v234, 0, v178, s[38:39]
	v_cndmask_b32_e64 v227, 0, v163, s[36:37]
	v_cndmask_b32_e64 v235, 0, v179, s[38:39]
	s_waitcnt lgkmcnt(0)
	s_nop 1
	v_pk_fma_f32 v[200:201], v[132:133], v[120:121], v[140:141]
	v_pk_fma_f32 v[202:203], v[134:135], v[122:123], v[142:143]
	v_fmac_f32_dpp v200, v72, v128 row_shr:1 row_mask:0xf bank_mask:0xf
	v_fmac_f32_dpp v201, v73, v129 row_shr:1 row_mask:0xf bank_mask:0xf
	v_fmac_f32_dpp v202, v74, v130 row_shr:1 row_mask:0xf bank_mask:0xf
	v_fmac_f32_dpp v203, v75, v131 row_shr:1 row_mask:0xf bank_mask:0xf
	v_pk_fma_f32 v[200:201], v[184:185], v[216:217], v[200:201]
	v_pk_fma_f32 v[202:203], v[186:187], v[218:219], v[202:203]
	v_pk_fma_f32 v[200:201], v[112:113], v[136:137], v[200:201]
	v_pk_fma_f32 v[202:203], v[114:115], v[138:139], v[202:203]
	v_pk_fma_f32 v[204:205], v[172:173], v[104:105], v[180:181]
	v_pk_fma_f32 v[206:207], v[174:175], v[106:107], v[182:183]
	v_fmac_f32_dpp v204, v64, v160 row_shr:1 row_mask:0xf bank_mask:0xf
	v_fmac_f32_dpp v205, v65, v161 row_shr:1 row_mask:0xf bank_mask:0xf
	v_fmac_f32_dpp v206, v66, v162 row_shr:1 row_mask:0xf bank_mask:0xf
	v_fmac_f32_dpp v207, v67, v163 row_shr:1 row_mask:0xf bank_mask:0xf
	v_pk_fma_f32 v[204:205], v[188:189], v[224:225], v[204:205]
	v_pk_fma_f32 v[206:207], v[190:191], v[226:227], v[206:207]
	v_pk_fma_f32 v[204:205], v[92:93], v[176:177], v[204:205]
	v_pk_fma_f32 v[206:207], v[94:95], v[178:179], v[206:207]
	v_pk_mul_f32 v[208:209], v[200:201], s[40:41]
	v_pk_mul_f32 v[210:211], v[202:203], s[40:41]
	v_exp_f32_e32 v208, v208
	v_exp_f32_e32 v209, v209
	v_exp_f32_e32 v210, v210
	v_exp_f32_e32 v211, v211
	v_pk_add_f32 v[208:209], v[208:209], s[54:55]
	v_pk_add_f32 v[210:211], v[210:211], s[54:55]
	v_rcp_f32_e32 v208, v208
	v_rcp_f32_e32 v209, v209
	v_rcp_f32_e32 v210, v210
	v_rcp_f32_e32 v211, v211
	v_pk_mul_f32 v[200:201], v[200:201], v[208:209]
	v_pk_mul_f32 v[202:203], v[202:203], v[210:211]
	v_pk_mul_f32 v[200:201], v[200:201], v[204:205]
	v_pk_mul_f32 v[202:203], v[202:203], v[206:207]
	v_cvt_pk_bf16_f32 v126, v200, v201
	v_cvt_pk_bf16_f32 v127, v202, v203
	v_pk_fma_f32 v[200:201], v[132:133], v[112:113], v[140:141]
	v_pk_fma_f32 v[202:203], v[134:135], v[114:115], v[142:143]
	v_pk_fma_f32 v[200:201], v[120:121], v[128:129], v[200:201]
	v_pk_fma_f32 v[202:203], v[122:123], v[130:131], v[202:203]
	v_pk_fma_f32 v[200:201], v[88:89], v[136:137], v[200:201]
	v_pk_fma_f32 v[202:203], v[90:91], v[138:139], v[202:203]
	v_pk_fma_f32 v[204:205], v[172:173], v[92:93], v[180:181]
	v_pk_fma_f32 v[206:207], v[174:175], v[94:95], v[182:183]
	v_pk_fma_f32 v[204:205], v[104:105], v[160:161], v[204:205]
	v_pk_fma_f32 v[206:207], v[106:107], v[162:163], v[206:207]
	v_pk_fma_f32 v[204:205], v[76:77], v[176:177], v[204:205]
	v_pk_fma_f32 v[206:207], v[78:79], v[178:179], v[206:207]
	v_pk_mul_f32 v[208:209], v[200:201], s[40:41]
	v_pk_mul_f32 v[210:211], v[202:203], s[40:41]
	v_exp_f32_e32 v208, v208
	v_exp_f32_e32 v209, v209
	v_exp_f32_e32 v210, v210
	v_exp_f32_e32 v211, v211
	v_pk_add_f32 v[208:209], v[208:209], s[54:55]
	v_pk_add_f32 v[210:211], v[210:211], s[54:55]
	v_rcp_f32_e32 v208, v208
	v_rcp_f32_e32 v209, v209
	v_rcp_f32_e32 v210, v210
	v_rcp_f32_e32 v211, v211
	v_pk_mul_f32 v[200:201], v[200:201], v[208:209]
	v_pk_mul_f32 v[202:203], v[202:203], v[210:211]
	v_pk_mul_f32 v[200:201], v[200:201], v[204:205]
	v_pk_mul_f32 v[202:203], v[202:203], v[206:207]
	v_cvt_pk_bf16_f32 v118, v200, v201
	v_cvt_pk_bf16_f32 v119, v202, v203
	v_pk_fma_f32 v[200:201], v[132:133], v[88:89], v[140:141]
	v_pk_fma_f32 v[202:203], v[134:135], v[90:91], v[142:143]
	v_pk_fma_f32 v[200:201], v[112:113], v[128:129], v[200:201]
	v_pk_fma_f32 v[202:203], v[114:115], v[130:131], v[202:203]
	v_pk_fma_f32 v[200:201], v[72:73], v[136:137], v[200:201]
	v_pk_fma_f32 v[202:203], v[74:75], v[138:139], v[202:203]
	v_pk_fma_f32 v[204:205], v[172:173], v[76:77], v[180:181]
	v_pk_fma_f32 v[206:207], v[174:175], v[78:79], v[182:183]
	v_pk_fma_f32 v[204:205], v[92:93], v[160:161], v[204:205]
	v_pk_fma_f32 v[206:207], v[94:95], v[162:163], v[206:207]
	v_pk_fma_f32 v[204:205], v[64:65], v[176:177], v[204:205]
	v_pk_fma_f32 v[206:207], v[66:67], v[178:179], v[206:207]
	v_pk_mul_f32 v[208:209], v[200:201], s[40:41]
	v_pk_mul_f32 v[210:211], v[202:203], s[40:41]
	v_exp_f32_e32 v208, v208
	v_exp_f32_e32 v209, v209
	v_exp_f32_e32 v210, v210
	v_exp_f32_e32 v211, v211
	v_pk_add_f32 v[208:209], v[208:209], s[54:55]
	v_pk_add_f32 v[210:211], v[210:211], s[54:55]
	v_rcp_f32_e32 v208, v208
	v_rcp_f32_e32 v209, v209
	v_rcp_f32_e32 v210, v210
	v_rcp_f32_e32 v211, v211
	v_pk_mul_f32 v[200:201], v[200:201], v[208:209]
	v_pk_mul_f32 v[202:203], v[202:203], v[210:211]
	v_pk_mul_f32 v[200:201], v[200:201], v[204:205]
	v_pk_mul_f32 v[202:203], v[202:203], v[206:207]
	v_cvt_pk_bf16_f32 v98, v200, v201
	v_cvt_pk_bf16_f32 v99, v202, v203
	v_pk_fma_f32 v[200:201], v[132:133], v[72:73], v[140:141]
	v_pk_fma_f32 v[202:203], v[134:135], v[74:75], v[142:143]
	v_pk_fma_f32 v[200:201], v[88:89], v[128:129], v[200:201]
	v_pk_fma_f32 v[202:203], v[90:91], v[130:131], v[202:203]
	v_fmac_f32_dpp v200, v120, v136 row_shl:1 row_mask:0xf bank_mask:0xf
	v_fmac_f32_dpp v201, v121, v137 row_shl:1 row_mask:0xf bank_mask:0xf
	v_fmac_f32_dpp v202, v122, v138 row_shl:1 row_mask:0xf bank_mask:0xf
	v_fmac_f32_dpp v203, v123, v139 row_shl:1 row_mask:0xf bank_mask:0xf
	v_pk_fma_f32 v[200:201], v[184:185], v[220:221], v[200:201]
	v_pk_fma_f32 v[202:203], v[186:187], v[222:223], v[202:203]
	v_pk_fma_f32 v[204:205], v[172:173], v[64:65], v[180:181]
	v_pk_fma_f32 v[206:207], v[174:175], v[66:67], v[182:183]
	v_pk_fma_f32 v[204:205], v[76:77], v[160:161], v[204:205]
	v_pk_fma_f32 v[206:207], v[78:79], v[162:163], v[206:207]
	v_fmac_f32_dpp v204, v104, v176 row_shl:1 row_mask:0xf bank_mask:0xf
	v_fmac_f32_dpp v205, v105, v177 row_shl:1 row_mask:0xf bank_mask:0xf
	v_fmac_f32_dpp v206, v106, v178 row_shl:1 row_mask:0xf bank_mask:0xf
	v_fmac_f32_dpp v207, v107, v179 row_shl:1 row_mask:0xf bank_mask:0xf
	v_pk_fma_f32 v[204:205], v[188:189], v[232:233], v[204:205]
	v_pk_fma_f32 v[206:207], v[190:191], v[234:235], v[206:207]
	v_pk_mul_f32 v[208:209], v[200:201], s[40:41]
	v_pk_mul_f32 v[210:211], v[202:203], s[40:41]
	v_exp_f32_e32 v208, v208
	v_exp_f32_e32 v209, v209
	v_exp_f32_e32 v210, v210
	v_exp_f32_e32 v211, v211
	v_pk_add_f32 v[208:209], v[208:209], s[54:55]
	v_pk_add_f32 v[210:211], v[210:211], s[54:55]
	v_rcp_f32_e32 v208, v208
	v_rcp_f32_e32 v209, v209
	v_rcp_f32_e32 v210, v210
	v_rcp_f32_e32 v211, v211
	v_pk_mul_f32 v[200:201], v[200:201], v[208:209]
	v_pk_mul_f32 v[202:203], v[202:203], v[210:211]
	v_pk_mul_f32 v[200:201], v[200:201], v[204:205]
	v_pk_mul_f32 v[202:203], v[202:203], v[206:207]
	v_cvt_pk_bf16_f32 v82, v200, v201
	v_cvt_pk_bf16_f32 v83, v202, v203
	v_pk_fma_f32 v[200:201], v[132:133], v[56:57], v[140:141]
	v_pk_fma_f32 v[202:203], v[134:135], v[58:59], v[142:143]
	v_fmac_f32_dpp v200, v8, v128 row_shr:1 row_mask:0xf bank_mask:0xf
	v_fmac_f32_dpp v201, v9, v129 row_shr:1 row_mask:0xf bank_mask:0xf
	v_fmac_f32_dpp v202, v10, v130 row_shr:1 row_mask:0xf bank_mask:0xf
	v_fmac_f32_dpp v203, v11, v131 row_shr:1 row_mask:0xf bank_mask:0xf
	v_pk_fma_f32 v[200:201], v[192:193], v[216:217], v[200:201]
	v_pk_fma_f32 v[202:203], v[194:195], v[218:219], v[202:203]
	v_pk_fma_f32 v[200:201], v[40:41], v[136:137], v[200:201]
	v_pk_fma_f32 v[202:203], v[42:43], v[138:139], v[202:203]
	v_pk_fma_f32 v[204:205], v[172:173], v[44:45], v[180:181]
	v_pk_fma_f32 v[206:207], v[174:175], v[46:47], v[182:183]
	v_fmac_f32_dpp v204, v0, v160 row_shr:1 row_mask:0xf bank_mask:0xf
	v_fmac_f32_dpp v205, v1, v161 row_shr:1 row_mask:0xf bank_mask:0xf
	v_fmac_f32_dpp v206, v2, v162 row_shr:1 row_mask:0xf bank_mask:0xf
	v_fmac_f32_dpp v207, v3, v163 row_shr:1 row_mask:0xf bank_mask:0xf
	v_pk_fma_f32 v[204:205], v[196:197], v[224:225], v[204:205]
	v_pk_fma_f32 v[206:207], v[198:199], v[226:227], v[206:207]
	v_pk_fma_f32 v[204:205], v[28:29], v[176:177], v[204:205]
	v_pk_fma_f32 v[206:207], v[30:31], v[178:179], v[206:207]
	v_pk_mul_f32 v[208:209], v[200:201], s[40:41]
	v_pk_mul_f32 v[210:211], v[202:203], s[40:41]
	v_exp_f32_e32 v208, v208
	v_exp_f32_e32 v209, v209
	v_exp_f32_e32 v210, v210
	v_exp_f32_e32 v211, v211
	v_pk_add_f32 v[208:209], v[208:209], s[54:55]
	v_pk_add_f32 v[210:211], v[210:211], s[54:55]
	v_rcp_f32_e32 v208, v208
	v_rcp_f32_e32 v209, v209
	v_rcp_f32_e32 v210, v210
	v_rcp_f32_e32 v211, v211
	v_pk_mul_f32 v[200:201], v[200:201], v[208:209]
	v_pk_mul_f32 v[202:203], v[202:203], v[210:211]
	v_pk_mul_f32 v[200:201], v[200:201], v[204:205]
	v_pk_mul_f32 v[202:203], v[202:203], v[206:207]
	v_cvt_pk_bf16_f32 v62, v200, v201
	v_cvt_pk_bf16_f32 v63, v202, v203
	v_pk_fma_f32 v[200:201], v[132:133], v[40:41], v[140:141]
	v_pk_fma_f32 v[202:203], v[134:135], v[42:43], v[142:143]
	v_pk_fma_f32 v[200:201], v[56:57], v[128:129], v[200:201]
	v_pk_fma_f32 v[202:203], v[58:59], v[130:131], v[202:203]
	v_pk_fma_f32 v[200:201], v[24:25], v[136:137], v[200:201]
	v_pk_fma_f32 v[202:203], v[26:27], v[138:139], v[202:203]
	v_pk_fma_f32 v[204:205], v[172:173], v[28:29], v[180:181]
	v_pk_fma_f32 v[206:207], v[174:175], v[30:31], v[182:183]
	v_pk_fma_f32 v[204:205], v[44:45], v[160:161], v[204:205]
	v_pk_fma_f32 v[206:207], v[46:47], v[162:163], v[206:207]
	v_pk_fma_f32 v[204:205], v[12:13], v[176:177], v[204:205]
	v_pk_fma_f32 v[206:207], v[14:15], v[178:179], v[206:207]
	v_pk_mul_f32 v[208:209], v[200:201], s[40:41]
	v_pk_mul_f32 v[210:211], v[202:203], s[40:41]
	v_exp_f32_e32 v208, v208
	v_exp_f32_e32 v209, v209
	v_exp_f32_e32 v210, v210
	v_exp_f32_e32 v211, v211
	v_pk_add_f32 v[208:209], v[208:209], s[54:55]
	v_pk_add_f32 v[210:211], v[210:211], s[54:55]
	v_rcp_f32_e32 v208, v208
	v_rcp_f32_e32 v209, v209
	v_rcp_f32_e32 v210, v210
	v_rcp_f32_e32 v211, v211
	v_pk_mul_f32 v[200:201], v[200:201], v[208:209]
	v_pk_mul_f32 v[202:203], v[202:203], v[210:211]
	v_pk_mul_f32 v[200:201], v[200:201], v[204:205]
	v_pk_mul_f32 v[202:203], v[202:203], v[206:207]
	v_cvt_pk_bf16_f32 v50, v200, v201
	v_cvt_pk_bf16_f32 v51, v202, v203
	v_pk_fma_f32 v[200:201], v[132:133], v[24:25], v[140:141]
	v_pk_fma_f32 v[202:203], v[134:135], v[26:27], v[142:143]
	v_pk_fma_f32 v[200:201], v[40:41], v[128:129], v[200:201]
	v_pk_fma_f32 v[202:203], v[42:43], v[130:131], v[202:203]
	v_pk_fma_f32 v[200:201], v[8:9], v[136:137], v[200:201]
	v_pk_fma_f32 v[202:203], v[10:11], v[138:139], v[202:203]
	v_pk_fma_f32 v[204:205], v[172:173], v[12:13], v[180:181]
	v_pk_fma_f32 v[206:207], v[174:175], v[14:15], v[182:183]
	v_pk_fma_f32 v[204:205], v[28:29], v[160:161], v[204:205]
	v_pk_fma_f32 v[206:207], v[30:31], v[162:163], v[206:207]
	v_pk_fma_f32 v[204:205], v[0:1], v[176:177], v[204:205]
	v_pk_fma_f32 v[206:207], v[2:3], v[178:179], v[206:207]
	v_pk_mul_f32 v[208:209], v[200:201], s[40:41]
	v_pk_mul_f32 v[210:211], v[202:203], s[40:41]
	v_exp_f32_e32 v208, v208
	v_exp_f32_e32 v209, v209
	v_exp_f32_e32 v210, v210
	v_exp_f32_e32 v211, v211
	v_pk_add_f32 v[208:209], v[208:209], s[54:55]
	v_pk_add_f32 v[210:211], v[210:211], s[54:55]
	v_rcp_f32_e32 v208, v208
	v_rcp_f32_e32 v209, v209
	v_rcp_f32_e32 v210, v210
	v_rcp_f32_e32 v211, v211
	v_pk_mul_f32 v[200:201], v[200:201], v[208:209]
	v_pk_mul_f32 v[202:203], v[202:203], v[210:211]
	v_pk_mul_f32 v[200:201], v[200:201], v[204:205]
	v_pk_mul_f32 v[202:203], v[202:203], v[206:207]
	v_cvt_pk_bf16_f32 v34, v200, v201
	v_cvt_pk_bf16_f32 v35, v202, v203
	v_pk_fma_f32 v[200:201], v[132:133], v[8:9], v[140:141]
	v_pk_fma_f32 v[202:203], v[134:135], v[10:11], v[142:143]
	v_pk_fma_f32 v[200:201], v[24:25], v[128:129], v[200:201]
	v_pk_fma_f32 v[202:203], v[26:27], v[130:131], v[202:203]
	v_fmac_f32_dpp v200, v56, v136 row_shl:1 row_mask:0xf bank_mask:0xf
	v_fmac_f32_dpp v201, v57, v137 row_shl:1 row_mask:0xf bank_mask:0xf
	v_fmac_f32_dpp v202, v58, v138 row_shl:1 row_mask:0xf bank_mask:0xf
	v_fmac_f32_dpp v203, v59, v139 row_shl:1 row_mask:0xf bank_mask:0xf
	v_pk_fma_f32 v[200:201], v[192:193], v[220:221], v[200:201]
	v_pk_fma_f32 v[202:203], v[194:195], v[222:223], v[202:203]
	v_pk_fma_f32 v[204:205], v[172:173], v[0:1], v[180:181]
	v_pk_fma_f32 v[206:207], v[174:175], v[2:3], v[182:183]
	v_pk_fma_f32 v[204:205], v[12:13], v[160:161], v[204:205]
	v_pk_fma_f32 v[206:207], v[14:15], v[162:163], v[206:207]
	v_fmac_f32_dpp v204, v44, v176 row_shl:1 row_mask:0xf bank_mask:0xf
	v_fmac_f32_dpp v205, v45, v177 row_shl:1 row_mask:0xf bank_mask:0xf
	v_fmac_f32_dpp v206, v46, v178 row_shl:1 row_mask:0xf bank_mask:0xf
	v_fmac_f32_dpp v207, v47, v179 row_shl:1 row_mask:0xf bank_mask:0xf
	v_pk_fma_f32 v[204:205], v[196:197], v[232:233], v[204:205]
	v_pk_fma_f32 v[206:207], v[198:199], v[234:235], v[206:207]
	v_pk_mul_f32 v[208:209], v[200:201], s[40:41]
	v_pk_mul_f32 v[210:211], v[202:203], s[40:41]
	v_exp_f32_e32 v208, v208
	v_exp_f32_e32 v209, v209
	v_exp_f32_e32 v210, v210
	v_exp_f32_e32 v211, v211
	v_pk_add_f32 v[208:209], v[208:209], s[54:55]
	v_pk_add_f32 v[210:211], v[210:211], s[54:55]
	v_rcp_f32_e32 v208, v208
	v_rcp_f32_e32 v209, v209
	v_rcp_f32_e32 v210, v210
	v_rcp_f32_e32 v211, v211
	v_pk_mul_f32 v[200:201], v[200:201], v[208:209]
	v_pk_mul_f32 v[202:203], v[202:203], v[210:211]
	v_pk_mul_f32 v[200:201], v[200:201], v[204:205]
	v_pk_mul_f32 v[202:203], v[202:203], v[206:207]
	v_cvt_pk_bf16_f32 v18, v200, v201
	v_cvt_pk_bf16_f32 v19, v202, v203
	global_store_dwordx4 v171, v[124:127], s[4:5]
	v_add_u32_e32 v250, 0x1600, v171
	global_store_dwordx4 v250, v[116:119], s[4:5]
	s_nop 0
	v_add_u32_e32 v250, 0x2c00, v171
	global_store_dwordx4 v250, v[96:99], s[4:5]
	s_nop 0
	v_add_u32_e32 v250, 0x4200, v171
	global_store_dwordx4 v250, v[80:83], s[4:5]
	s_nop 0
	v_add_u32_e32 v250, 0xb0000, v171
	global_store_dwordx4 v250, v[60:63], s[4:5]
	s_nop 0
	v_add_u32_e32 v250, 0xb1600, v171
	global_store_dwordx4 v250, v[48:51], s[4:5]
	s_nop 0
	v_add_u32_e32 v250, 0xb2c00, v171
	global_store_dwordx4 v250, v[32:35], s[4:5]
	s_nop 0
	v_add_u32_e32 v250, 0xb4200, v171
	global_store_dwordx4 v250, v[16:19], s[4:5]
	s_nop 0
	s_and_b64 s[36:37], s[6:7], exec
	s_cbranch_scc0 .LepA_nonext
	s_xor_b32 s101, s101, 1
	s_or_b32 s101, s101, 2
	s_and_b32 s32, s101, 1
	s_mulk_i32 s32, 0x1800
	s_add_i32 s32, s32, 0x22c00
	v_readfirstlane_b32 s79, v230
	s_cmp_lt_u32 s79, 64
	s_cbranch_scc0 .LepA_nfe
	s_add_i32 s4, s26, -32
	s_ashr_i32 s4, s4, 2
	s_add_i32 s4, s4, 1
	s_cmp_gt_i32 s26, 31
	s_cselect_b32 s4, s4, 0
	s_mul_hi_i32 s5, s4, 0x5800
	s_mulk_i32 s4, 0x5800
	s_add_u32 s4, s33, s4
	s_addc_u32 s5, s50, s5
	v_readlane_b32 s36, v254, 5
	v_readlane_b32 s37, v254, 6
	v_readlane_b32 s38, v254, 7
	v_readlane_b32 s39, v254, 8
	s_nop 0
	s_add_u32 s36, s36, 0x10800
	s_addc_u32 s37, s37, 0
	s_add_u32 s38, s38, 0x5800
	s_addc_u32 s39, s39, 0
	v_and_b32_e32 v238, 63, v230
	v_lshrrev_b32_e32 v239, 5, v238
	v_and_b32_e32 v240, 31, v238
	v_lshlrev_b32_e32 v240, 4, v240
	s_lshl_b32 s79, s24, 9
	v_add_u32_e32 v240, s79, v240
	v_mul_u32_u24_e32 v241, 0x2c00, v239
	v_mul_u32_u24_e32 v242, 0x5800, v239
	v_add_u32_e32 v241, v241, v240
	v_add_u32_e32 v242, v242, v240
	v_lshlrev_b32_e32 v243, 4, v238
	s_lshl_b32 s79, s26, 10
	v_add_u32_e32 v243, s79, v243
	s_mov_b32 m0, s32
	s_nop 0
	global_load_lds_dwordx4 v243, s[10:11]
	s_add_i32 m0, s32, 1024
	s_nop 0
	global_load_lds_dwordx4 v241, s[4:5]
	s_add_i32 m0, s32, 2048
	s_nop 0
	global_load_lds_dwordx4 v242, s[36:37]
	v_add_u32_e32 v243, 0x2c00, v242
	s_add_i32 m0, s32, 3072
	s_nop 0
	global_load_lds_dwordx4 v243, s[36:37]
	v_add_u32_e32 v243, 0xb000, v241
	s_add_i32 m0, s32, 4096
	s_nop 0
	global_load_lds_dwordx4 v243, s[36:37]
	s_add_i32 m0, s32, 5120
	s_nop 0
	global_load_lds_dwordx4 v241, s[38:39]

.LepC_fast:
	s_mov_b32 s58, 0xbfb8aa3b
	s_mov_b32 s59, 0xbfb8aa3b
	s_mov_b32 s60, 1.0
	s_mov_b32 s61, 1.0
	s_and_b32 s23, s8, 1
	v_and_b32_e32 v237, 15, v164
	v_and_b32_e32 v236, 64, v164
	v_lshl_add_u32 v236, v237, 2, v236
	v_mul_u32_u24_e32 v171, 0x1600, v236
	v_lshl_add_u32 v171, v166, 1, v171
	v_lshl_add_u32 v236, v236, 2, s32
	v_lshl_add_u32 v229, v166, 2, s32
	ds_read_b128 v[208:211], v236
	ds_read_b128 v[212:215], v236 offset:512
	ds_read_b128 v[200:203], v229 offset:1024
	ds_read_b128 v[204:207], v229 offset:1040
	ds_read_b128 v[216:219], v229 offset:1536
	ds_read_b128 v[220:223], v229 offset:1552
	ds_read_b128 v[128:131], v229 offset:2048
	ds_read_b128 v[132:135], v229 offset:2560
	ds_read_b128 v[136:139], v229 offset:4096
	ds_read_b128 v[140:143], v229 offset:5120
	ds_read_b128 v[160:163], v229 offset:3072
	ds_read_b128 v[172:175], v229 offset:3584
	ds_read_b128 v[176:179], v229 offset:4608
	ds_read_b128 v[180:183], v229 offset:5632
	s_mul_i32 s30, s6, 0x160000
	s_lshl_b32 s79, s7, 8
	s_add_i32 s30, s30, s79
	s_add_i32 s30, s30, 0xbf00000
	s_add_u32 s30, s30, s70
	s_addc_u32 s31, s71, 0
	s_mov_b32 s79, 0x20800
	v_lshl_add_u32 v228, v166, 2, s79
	v_cmp_eq_u32_e64 s[34:35], 0, v237
	v_cmp_eq_u32_e64 s[36:37], 15, v237
	v_and_b32_e32 v231, 8, v237
	v_lshlrev_b32_e32 v231, 9, v231
	s_lshl_b32 s79, s23, 10
	v_add3_u32 v231, v231, v228, s79
	s_waitcnt lgkmcnt(12)
	v_fmamk_f32 v208, v208, 0x3a800000, v170
	v_fmamk_f32 v209, v209, 0x3a800000, v170
	v_fmamk_f32 v210, v210, 0x3a800000, v170
	v_fmamk_f32 v211, v211, 0x3a800000, v170
	v_fmamk_f32 v212, v212, 0x3a800000, v170
	v_fmamk_f32 v213, v213, 0x3a800000, v170
	v_fmamk_f32 v214, v214, 0x3a800000, v170
	v_fmamk_f32 v215, v215, 0x3a800000, v170
	s_mov_b32 s79, 0x800000
	v_mul_f32_e32 v224, 0x4b800000, v208
	v_mul_f32_e32 v225, 0x4b800000, v209
	v_mul_f32_e32 v226, 0x4b800000, v210
	v_mul_f32_e32 v227, 0x4b800000, v211
	v_mul_f32_e32 v232, 0x4b800000, v212
	v_mul_f32_e32 v233, 0x4b800000, v213
	v_mul_f32_e32 v234, 0x4b800000, v214
	v_mul_f32_e32 v235, 0x4b800000, v215
	v_cmp_gt_f32_e32 vcc, s79, v208
	s_nop 1
	v_cndmask_b32_e32 v208, v208, v224, vcc
	v_rsq_f32_e32 v208, v208
	s_nop 0
	v_mul_f32_e32 v224, 0x45800000, v208
	v_cndmask_b32_e32 v208, v208, v224, vcc
	v_cmp_gt_f32_e32 vcc, s79, v209
	s_nop 1
	v_cndmask_b32_e32 v209, v209, v225, vcc
	v_rsq_f32_e32 v209, v209
	s_nop 0
	v_mul_f32_e32 v225, 0x45800000, v209
	v_cndmask_b32_e32 v209, v209, v225, vcc
	v_cmp_gt_f32_e32 vcc, s79, v210
	s_nop 1
	v_cndmask_b32_e32 v210, v210, v226, vcc
	v_rsq_f32_e32 v210, v210
	s_nop 0
	v_mul_f32_e32 v226, 0x45800000, v210
	v_cndmask_b32_e32 v210, v210, v226, vcc
	v_cmp_gt_f32_e32 vcc, s79, v211
	s_nop 1
	v_cndmask_b32_e32 v211, v211, v227, vcc
	v_rsq_f32_e32 v211, v211
	s_nop 0
	v_mul_f32_e32 v227, 0x45800000, v211
	v_cndmask_b32_e32 v211, v211, v227, vcc
	v_cmp_gt_f32_e32 vcc, s79, v212
	s_nop 1
	v_cndmask_b32_e32 v212, v212, v232, vcc
	v_rsq_f32_e32 v212, v212
	s_nop 0
	v_mul_f32_e32 v232, 0x45800000, v212
	v_cndmask_b32_e32 v212, v212, v232, vcc
	v_cmp_gt_f32_e32 vcc, s79, v213
	s_nop 1
	v_cndmask_b32_e32 v213, v213, v233, vcc
	v_rsq_f32_e32 v213, v213
	s_nop 0
	v_mul_f32_e32 v233, 0x45800000, v213
	v_cndmask_b32_e32 v213, v213, v233, vcc
	v_cmp_gt_f32_e32 vcc, s79, v214
	s_nop 1
	v_cndmask_b32_e32 v214, v214, v234, vcc
	v_rsq_f32_e32 v214, v214
	s_nop 0
	v_mul_f32_e32 v234, 0x45800000, v214
	v_cndmask_b32_e32 v214, v214, v234, vcc
	v_cmp_gt_f32_e32 vcc, s79, v215
	s_nop 1
	v_cndmask_b32_e32 v215, v215, v235, vcc
	v_rsq_f32_e32 v215, v215
	s_nop 0
	v_mul_f32_e32 v235, 0x45800000, v215
	v_cndmask_b32_e32 v215, v215, v235, vcc
	s_waitcnt lgkmcnt(8)
	v_pk_fma_f32 v[124:125], v[124:125], v[208:209], v[200:201] op_sel:[0,0,0] op_sel_hi:[1,0,1]
	v_pk_fma_f32 v[126:127], v[126:127], v[208:209], v[202:203] op_sel:[0,0,0] op_sel_hi:[1,0,1]
	v_pk_fma_f32 v[120:121], v[120:121], v[208:209], v[204:205] op_sel:[0,0,0] op_sel_hi:[1,0,1]
	v_pk_fma_f32 v[122:123], v[122:123], v[208:209], v[206:207] op_sel:[0,0,0] op_sel_hi:[1,0,1]
	v_pk_fma_f32 v[108:109], v[108:109], v[208:209], v[216:217] op_sel:[0,0,0] op_sel_hi:[1,0,1]
	v_pk_fma_f32 v[110:111], v[110:111], v[208:209], v[218:219] op_sel:[0,0,0] op_sel_hi:[1,0,1]
	v_pk_fma_f32 v[104:105], v[104:105], v[208:209], v[220:221] op_sel:[0,0,0] op_sel_hi:[1,0,1]
	v_pk_fma_f32 v[106:107], v[106:107], v[208:209], v[222:223] op_sel:[0,0,0] op_sel_hi:[1,0,1]
	v_pk_fma_f32 v[116:117], v[116:117], v[208:209], v[200:201] op_sel:[0,1,0] op_sel_hi:[1,1,1]
	v_pk_fma_f32 v[118:119], v[118:119], v[208:209], v[202:203] op_sel:[0,1,0] op_sel_hi:[1,1,1]
	v_pk_fma_f32 v[112:113], v[112:113], v[208:209], v[204:205] op_sel:[0,1,0] op_sel_hi:[1,1,1]
	v_pk_fma_f32 v[114:115], v[114:115], v[208:209], v[206:207] op_sel:[0,1,0] op_sel_hi:[1,1,1]
	v_pk_fma_f32 v[100:101], v[100:101], v[208:209], v[216:217] op_sel:[0,1,0] op_sel_hi:[1,1,1]
	v_pk_fma_f32 v[102:103], v[102:103], v[208:209], v[218:219] op_sel:[0,1,0] op_sel_hi:[1,1,1]
	v_pk_fma_f32 v[92:93], v[92:93], v[208:209], v[220:221] op_sel:[0,1,0] op_sel_hi:[1,1,1]
	v_pk_fma_f32 v[94:95], v[94:95], v[208:209], v[222:223] op_sel:[0,1,0] op_sel_hi:[1,1,1]
	v_pk_fma_f32 v[96:97], v[96:97], v[210:211], v[200:201] op_sel:[0,0,0] op_sel_hi:[1,0,1]
	v_pk_fma_f32 v[98:99], v[98:99], v[210:211], v[202:203] op_sel:[0,0,0] op_sel_hi:[1,0,1]
	v_pk_fma_f32 v[88:89], v[88:89], v[210:211], v[204:205] op_sel:[0,0,0] op_sel_hi:[1,0,1]
	v_pk_fma_f32 v[90:91], v[90:91], v[210:211], v[206:207] op_sel:[0,0,0] op_sel_hi:[1,0,1]
	v_pk_fma_f32 v[84:85], v[84:85], v[210:211], v[216:217] op_sel:[0,0,0] op_sel_hi:[1,0,1]
	v_pk_fma_f32 v[86:87], v[86:87], v[210:211], v[218:219] op_sel:[0,0,0] op_sel_hi:[1,0,1]
	v_pk_fma_f32 v[76:77], v[76:77], v[210:211], v[220:221] op_sel:[0,0,0] op_sel_hi:[1,0,1]
	v_pk_fma_f32 v[78:79], v[78:79], v[210:211], v[222:223] op_sel:[0,0,0] op_sel_hi:[1,0,1]
	v_pk_fma_f32 v[80:81], v[80:81], v[210:211], v[200:201] op_sel:[0,1,0] op_sel_hi:[1,1,1]
	v_pk_fma_f32 v[82:83], v[82:83], v[210:211], v[202:203] op_sel:[0,1,0] op_sel_hi:[1,1,1]
	v_pk_fma_f32 v[72:73], v[72:73], v[210:211], v[204:205] op_sel:[0,1,0] op_sel_hi:[1,1,1]
	v_pk_fma_f32 v[74:75], v[74:75], v[210:211], v[206:207] op_sel:[0,1,0] op_sel_hi:[1,1,1]
	v_pk_fma_f32 v[68:69], v[68:69], v[210:211], v[216:217] op_sel:[0,1,0] op_sel_hi:[1,1,1]
	v_pk_fma_f32 v[70:71], v[70:71], v[210:211], v[218:219] op_sel:[0,1,0] op_sel_hi:[1,1,1]
	v_pk_fma_f32 v[64:65], v[64:65], v[210:211], v[220:221] op_sel:[0,1,0] op_sel_hi:[1,1,1]
	v_pk_fma_f32 v[66:67], v[66:67], v[210:211], v[222:223] op_sel:[0,1,0] op_sel_hi:[1,1,1]
	v_pk_fma_f32 v[60:61], v[60:61], v[212:213], v[200:201] op_sel:[0,0,0] op_sel_hi:[1,0,1]
	v_pk_fma_f32 v[62:63], v[62:63], v[212:213], v[202:203] op_sel:[0,0,0] op_sel_hi:[1,0,1]
	v_pk_fma_f32 v[56:57], v[56:57], v[212:213], v[204:205] op_sel:[0,0,0] op_sel_hi:[1,0,1]
	v_pk_fma_f32 v[58:59], v[58:59], v[212:213], v[206:207] op_sel:[0,0,0] op_sel_hi:[1,0,1]
	v_pk_fma_f32 v[52:53], v[52:53], v[212:213], v[216:217] op_sel:[0,0,0] op_sel_hi:[1,0,1]
	v_pk_fma_f32 v[54:55], v[54:55], v[212:213], v[218:219] op_sel:[0,0,0] op_sel_hi:[1,0,1]
	v_pk_fma_f32 v[44:45], v[44:45], v[212:213], v[220:221] op_sel:[0,0,0] op_sel_hi:[1,0,1]
	v_pk_fma_f32 v[46:47], v[46:47], v[212:213], v[222:223] op_sel:[0,0,0] op_sel_hi:[1,0,1]
	v_pk_fma_f32 v[48:49], v[48:49], v[212:213], v[200:201] op_sel:[0,1,0] op_sel_hi:[1,1,1]
	v_pk_fma_f32 v[50:51], v[50:51], v[212:213], v[202:203] op_sel:[0,1,0] op_sel_hi:[1,1,1]
	v_pk_fma_f32 v[40:41], v[40:41], v[212:213], v[204:205] op_sel:[0,1,0] op_sel_hi:[1,1,1]
	v_pk_fma_f32 v[42:43], v[42:43], v[212:213], v[206:207] op_sel:[0,1,0] op_sel_hi:[1,1,1]
	v_pk_fma_f32 v[36:37], v[36:37], v[212:213], v[216:217] op_sel:[0,1,0] op_sel_hi:[1,1,1]
	v_pk_fma_f32 v[38:39], v[38:39], v[212:213], v[218:219] op_sel:[0,1,0] op_sel_hi:[1,1,1]
	v_pk_fma_f32 v[28:29], v[28:29], v[212:213], v[220:221] op_sel:[0,1,0] op_sel_hi:[1,1,1]
	v_pk_fma_f32 v[30:31], v[30:31], v[212:213], v[222:223] op_sel:[0,1,0] op_sel_hi:[1,1,1]
	v_pk_fma_f32 v[32:33], v[32:33], v[214:215], v[200:201] op_sel:[0,0,0] op_sel_hi:[1,0,1]
	v_pk_fma_f32 v[34:35], v[34:35], v[214:215], v[202:203] op_sel:[0,0,0] op_sel_hi:[1,0,1]
	v_pk_fma_f32 v[24:25], v[24:25], v[214:215], v[204:205] op_sel:[0,0,0] op_sel_hi:[1,0,1]
	v_pk_fma_f32 v[26:27], v[26:27], v[214:215], v[206:207] op_sel:[0,0,0] op_sel_hi:[1,0,1]
	v_pk_fma_f32 v[20:21], v[20:21], v[214:215], v[216:217] op_sel:[0,0,0] op_sel_hi:[1,0,1]
	v_pk_fma_f32 v[22:23], v[22:23], v[214:215], v[218:219] op_sel:[0,0,0] op_sel_hi:[1,0,1]
	v_pk_fma_f32 v[12:13], v[12:13], v[214:215], v[220:221] op_sel:[0,0,0] op_sel_hi:[1,0,1]
	v_pk_fma_f32 v[14:15], v[14:15], v[214:215], v[222:223] op_sel:[0,0,0] op_sel_hi:[1,0,1]
	v_pk_fma_f32 v[16:17], v[16:17], v[214:215], v[200:201] op_sel:[0,1,0] op_sel_hi:[1,1,1]
	v_pk_fma_f32 v[18:19], v[18:19], v[214:215], v[202:203] op_sel:[0,1,0] op_sel_hi:[1,1,1]
	v_pk_fma_f32 v[8:9], v[8:9], v[214:215], v[204:205] op_sel:[0,1,0] op_sel_hi:[1,1,1]
	v_pk_fma_f32 v[10:11], v[10:11], v[214:215], v[206:207] op_sel:[0,1,0] op_sel_hi:[1,1,1]
	v_pk_fma_f32 v[4:5], v[4:5], v[214:215], v[216:217] op_sel:[0,1,0] op_sel_hi:[1,1,1]
	v_pk_fma_f32 v[6:7], v[6:7], v[214:215], v[218:219] op_sel:[0,1,0] op_sel_hi:[1,1,1]
	v_pk_fma_f32 v[0:1], v[0:1], v[214:215], v[220:221] op_sel:[0,1,0] op_sel_hi:[1,1,1]
	v_pk_fma_f32 v[2:3], v[2:3], v[214:215], v[222:223] op_sel:[0,1,0] op_sel_hi:[1,1,1]
	v_mov_b32_e32 v212, 0
	v_mov_b32_e32 v213, 0
	v_mov_b32_e32 v214, 0
	v_mov_b32_e32 v215, 0
	s_lshl_b32 s96, s23, 12
	s_sub_i32 s96, 0x2000, s96
	s_mul_i32 s94, s23, 0x1400
	s_add_i32 s94, s94, 0xc00
	s_lshl_b32 s79, s23, 10
	s_add_i32 s95, s79, 5120
	s_add_i32 s92, s79, 1024
	s_mov_b64 exec, s[34:35]
	v_add_u32_e32 v250, s96, v228
	ds_write_b128 v250, v[124:127] offset:0
	ds_write_b128 v250, v[120:123] offset:16
	ds_write_b128 v250, v[108:111] offset:512
	ds_write_b128 v250, v[104:107] offset:528
	v_add_u32_e32 v250, s95, v228
	ds_write_b128 v250, v[60:63] offset:0
	ds_write_b128 v250, v[56:59] offset:16
	ds_write_b128 v250, v[52:55] offset:512
	ds_write_b128 v250, v[44:47] offset:528
	ds_write_b128 v228, v[212:215] offset:0
	ds_write_b128 v228, v[212:215] offset:16
	ds_write_b128 v228, v[212:215] offset:512
	ds_write_b128 v228, v[212:215] offset:528
	s_mov_b64 exec, s[36:37]
	v_add_u32_e32 v251, s92, v228
	ds_write_b128 v251, v[80:83] offset:0
	ds_write_b128 v251, v[72:75] offset:16
	ds_write_b128 v251, v[68:71] offset:512
	ds_write_b128 v251, v[64:67] offset:528
	v_add_u32_e32 v251, s94, v228
	ds_write_b128 v251, v[16:19] offset:0
	ds_write_b128 v251, v[8:11] offset:16
	ds_write_b128 v251, v[4:7] offset:512
	ds_write_b128 v251, v[0:3] offset:528
	ds_write_b128 v228, v[212:215] offset:7168
	ds_write_b128 v228, v[212:215] offset:7184
	ds_write_b128 v228, v[212:215] offset:7680
	ds_write_b128 v228, v[212:215] offset:7696
	s_mov_b64 exec, -1
	s_cmp_eq_u32 s23, 0
	s_cselect_b64 s[52:53], s[34:35], 0
	s_cselect_b64 s[54:55], 0, s[36:37]
	s_mul_i32 s56, s6, 0x16000
	s_add_u32 s56, s56, 0x5b00000
	s_add_u32 s56, s56, s70
	s_addc_u32 s57, s71, 0
	v_lshl_or_b32 v252, s7, 7, v166
	v_lshlrev_b32_e32 v252, 2, v252
	s_mov_b64 exec, s[52:53]
	global_store_dwordx4 v252, v[124:127], s[56:57]
	global_store_dwordx4 v252, v[120:123], s[56:57] offset:16
	v_add_u32_e32 v250, 0x2c00, v252
	global_store_dwordx4 v250, v[108:111], s[56:57]
	global_store_dwordx4 v250, v[104:107], s[56:57] offset:16
	s_mov_b64 exec, s[54:55]
	v_add_u32_e32 v250, 0xb000, v252
	global_store_dwordx4 v250, v[16:19], s[56:57]
	global_store_dwordx4 v250, v[8:11], s[56:57] offset:16
	v_add_u32_e32 v250, 0xdc00, v252
	global_store_dwordx4 v250, v[4:7], s[56:57]
	global_store_dwordx4 v250, v[0:3], s[56:57] offset:16
	s_mov_b64 exec, -1
	s_waitcnt lgkmcnt(0)
	s_barrier
	ds_read_b128 v[184:187], v231 offset:0
	ds_read_b128 v[188:191], v231 offset:512
	ds_read_b128 v[192:195], v231 offset:2048
	ds_read_b128 v[196:199], v231 offset:2560
	s_nop 0
	v_cndmask_b32_e64 v216, 0, v128, s[34:35]
	v_cndmask_b32_e64 v220, 0, v136, s[36:37]
	v_cndmask_b32_e64 v217, 0, v129, s[34:35]
	v_cndmask_b32_e64 v221, 0, v137, s[36:37]
	v_cndmask_b32_e64 v218, 0, v130, s[34:35]
	v_cndmask_b32_e64 v222, 0, v138, s[36:37]
	v_cndmask_b32_e64 v219, 0, v131, s[34:35]
	v_cndmask_b32_e64 v223, 0, v139, s[36:37]
	v_cndmask_b32_e64 v224, 0, v160, s[34:35]
	v_cndmask_b32_e64 v232, 0, v176, s[36:37]
	v_cndmask_b32_e64 v225, 0, v161, s[34:35]
	v_cndmask_b32_e64 v233, 0, v177, s[36:37]
	v_cndmask_b32_e64 v226, 0, v162, s[34:35]
	v_cndmask_b32_e64 v234, 0, v178, s[36:37]
	v_cndmask_b32_e64 v227, 0, v163, s[34:35]
	v_cndmask_b32_e64 v235, 0, v179, s[36:37]
	s_waitcnt lgkmcnt(0)
	s_nop 1
	v_pk_fma_f32 v[200:201], v[132:133], v[124:125], v[140:141]
	v_pk_fma_f32 v[202:203], v[134:135], v[126:127], v[142:143]
	v_fmac_f32_dpp v200, v80, v128 row_shr:1 row_mask:0xf bank_mask:0xf
	v_fmac_f32_dpp v201, v81, v129 row_shr:1 row_mask:0xf bank_mask:0xf
	v_fmac_f32_dpp v202, v82, v130 row_shr:1 row_mask:0xf bank_mask:0xf
	v_fmac_f32_dpp v203, v83, v131 row_shr:1 row_mask:0xf bank_mask:0xf
	v_pk_fma_f32 v[200:201], v[184:185], v[216:217], v[200:201]
	v_pk_fma_f32 v[202:203], v[186:187], v[218:219], v[202:203]
	v_pk_fma_f32 v[200:201], v[116:117], v[136:137], v[200:201]
	v_pk_fma_f32 v[202:203], v[118:119], v[138:139], v[202:203]
	v_pk_fma_f32 v[204:205], v[172:173], v[108:109], v[180:181]
	v_pk_fma_f32 v[206:207], v[174:175], v[110:111], v[182:183]
	v_fmac_f32_dpp v204, v68, v160 row_shr:1 row_mask:0xf bank_mask:0xf
	v_fmac_f32_dpp v205, v69, v161 row_shr:1 row_mask:0xf bank_mask:0xf
	v_fmac_f32_dpp v206, v70, v162 row_shr:1 row_mask:0xf bank_mask:0xf
	v_fmac_f32_dpp v207, v71, v163 row_shr:1 row_mask:0xf bank_mask:0xf
	v_pk_fma_f32 v[204:205], v[188:189], v[224:225], v[204:205]
	v_pk_fma_f32 v[206:207], v[190:191], v[226:227], v[206:207]
	v_pk_fma_f32 v[204:205], v[100:101], v[176:177], v[204:205]
	v_pk_fma_f32 v[206:207], v[102:103], v[178:179], v[206:207]
	s_mov_b64 exec, s[52:53]
	v_add_u32_e32 v250, 0x5800, v252
	global_store_dwordx4 v250, v[200:203], s[56:57]
	v_add_u32_e32 v250, 0x8400, v252
	global_store_dwordx4 v250, v[204:207], s[56:57]
	s_mov_b64 exec, -1
	s_nop 4
	v_pk_mul_f32 v[208:209], v[200:201], s[58:59]
	v_pk_mul_f32 v[210:211], v[202:203], s[58:59]
	v_exp_f32_e32 v208, v208
	v_exp_f32_e32 v209, v209
	v_exp_f32_e32 v210, v210
	v_exp_f32_e32 v211, v211
	v_pk_add_f32 v[208:209], v[208:209], s[60:61]
	v_pk_add_f32 v[210:211], v[210:211], s[60:61]
	v_rcp_f32_e32 v208, v208
	v_rcp_f32_e32 v209, v209
	v_rcp_f32_e32 v210, v210
	v_rcp_f32_e32 v211, v211
	v_pk_mul_f32 v[200:201], v[200:201], v[208:209]
	v_pk_mul_f32 v[202:203], v[202:203], v[210:211]
	v_pk_mul_f32 v[200:201], v[200:201], v[204:205]
	v_pk_mul_f32 v[202:203], v[202:203], v[206:207]
	v_cvt_pk_bf16_f32 v236, v200, v201
	v_cvt_pk_bf16_f32 v237, v202, v203
	v_pk_fma_f32 v[200:201], v[132:133], v[116:117], v[140:141]
	v_pk_fma_f32 v[202:203], v[134:135], v[118:119], v[142:143]
	v_pk_fma_f32 v[200:201], v[124:125], v[128:129], v[200:201]
	v_pk_fma_f32 v[202:203], v[126:127], v[130:131], v[202:203]
	v_pk_fma_f32 v[200:201], v[96:97], v[136:137], v[200:201]
	v_pk_fma_f32 v[202:203], v[98:99], v[138:139], v[202:203]
	v_pk_fma_f32 v[204:205], v[172:173], v[100:101], v[180:181]
	v_pk_fma_f32 v[206:207], v[174:175], v[102:103], v[182:183]
	v_pk_fma_f32 v[204:205], v[108:109], v[160:161], v[204:205]
	v_pk_fma_f32 v[206:207], v[110:111], v[162:163], v[206:207]
	v_pk_fma_f32 v[204:205], v[84:85], v[176:177], v[204:205]
	v_pk_fma_f32 v[206:207], v[86:87], v[178:179], v[206:207]
	v_pk_mul_f32 v[208:209], v[200:201], s[58:59]
	v_pk_mul_f32 v[210:211], v[202:203], s[58:59]
	v_exp_f32_e32 v208, v208
	v_exp_f32_e32 v209, v209
	v_exp_f32_e32 v210, v210
	v_exp_f32_e32 v211, v211
	v_pk_add_f32 v[208:209], v[208:209], s[60:61]
	v_pk_add_f32 v[210:211], v[210:211], s[60:61]
	v_rcp_f32_e32 v208, v208
	v_rcp_f32_e32 v209, v209
	v_rcp_f32_e32 v210, v210
	v_rcp_f32_e32 v211, v211
	v_pk_mul_f32 v[200:201], v[200:201], v[208:209]
	v_pk_mul_f32 v[202:203], v[202:203], v[210:211]
	v_pk_mul_f32 v[200:201], v[200:201], v[204:205]
	v_pk_mul_f32 v[202:203], v[202:203], v[206:207]
	v_cvt_pk_bf16_f32 v238, v200, v201
	v_cvt_pk_bf16_f32 v239, v202, v203
	v_pk_fma_f32 v[200:201], v[132:133], v[96:97], v[140:141]
	v_pk_fma_f32 v[202:203], v[134:135], v[98:99], v[142:143]
	v_pk_fma_f32 v[200:201], v[116:117], v[128:129], v[200:201]
	v_pk_fma_f32 v[202:203], v[118:119], v[130:131], v[202:203]
	v_pk_fma_f32 v[200:201], v[80:81], v[136:137], v[200:201]
	v_pk_fma_f32 v[202:203], v[82:83], v[138:139], v[202:203]
	v_pk_fma_f32 v[204:205], v[172:173], v[84:85], v[180:181]
	v_pk_fma_f32 v[206:207], v[174:175], v[86:87], v[182:183]
	v_pk_fma_f32 v[204:205], v[100:101], v[160:161], v[204:205]
	v_pk_fma_f32 v[206:207], v[102:103], v[162:163], v[206:207]
	v_pk_fma_f32 v[204:205], v[68:69], v[176:177], v[204:205]
	v_pk_fma_f32 v[206:207], v[70:71], v[178:179], v[206:207]
	v_pk_mul_f32 v[208:209], v[200:201], s[58:59]
	v_pk_mul_f32 v[210:211], v[202:203], s[58:59]
	v_exp_f32_e32 v208, v208
	v_exp_f32_e32 v209, v209
	v_exp_f32_e32 v210, v210
	v_exp_f32_e32 v211, v211
	v_pk_add_f32 v[208:209], v[208:209], s[60:61]
	v_pk_add_f32 v[210:211], v[210:211], s[60:61]
	v_rcp_f32_e32 v208, v208
	v_rcp_f32_e32 v209, v209
	v_rcp_f32_e32 v210, v210
	v_rcp_f32_e32 v211, v211
	v_pk_mul_f32 v[200:201], v[200:201], v[208:209]
	v_pk_mul_f32 v[202:203], v[202:203], v[210:211]
	v_pk_mul_f32 v[200:201], v[200:201], v[204:205]
	v_pk_mul_f32 v[202:203], v[202:203], v[206:207]
	v_cvt_pk_bf16_f32 v240, v200, v201
	v_cvt_pk_bf16_f32 v241, v202, v203
	v_pk_fma_f32 v[200:201], v[132:133], v[80:81], v[140:141]
	v_pk_fma_f32 v[202:203], v[134:135], v[82:83], v[142:143]
	v_pk_fma_f32 v[200:201], v[96:97], v[128:129], v[200:201]
	v_pk_fma_f32 v[202:203], v[98:99], v[130:131], v[202:203]
	v_fmac_f32_dpp v200, v124, v136 row_shl:1 row_mask:0xf bank_mask:0xf
	v_fmac_f32_dpp v201, v125, v137 row_shl:1 row_mask:0xf bank_mask:0xf
	v_fmac_f32_dpp v202, v126, v138 row_shl:1 row_mask:0xf bank_mask:0xf
	v_fmac_f32_dpp v203, v127, v139 row_shl:1 row_mask:0xf bank_mask:0xf
	v_pk_fma_f32 v[200:201], v[184:185], v[220:221], v[200:201]
	v_pk_fma_f32 v[202:203], v[186:187], v[222:223], v[202:203]
	v_pk_fma_f32 v[204:205], v[172:173], v[68:69], v[180:181]
	v_pk_fma_f32 v[206:207], v[174:175], v[70:71], v[182:183]
	v_pk_fma_f32 v[204:205], v[84:85], v[160:161], v[204:205]
	v_pk_fma_f32 v[206:207], v[86:87], v[162:163], v[206:207]
	v_fmac_f32_dpp v204, v108, v176 row_shl:1 row_mask:0xf bank_mask:0xf
	v_fmac_f32_dpp v205, v109, v177 row_shl:1 row_mask:0xf bank_mask:0xf
	v_fmac_f32_dpp v206, v110, v178 row_shl:1 row_mask:0xf bank_mask:0xf
	v_fmac_f32_dpp v207, v111, v179 row_shl:1 row_mask:0xf bank_mask:0xf
	v_pk_fma_f32 v[204:205], v[188:189], v[232:233], v[204:205]
	v_pk_fma_f32 v[206:207], v[190:191], v[234:235], v[206:207]
	v_pk_mul_f32 v[208:209], v[200:201], s[58:59]
	v_pk_mul_f32 v[210:211], v[202:203], s[58:59]
	v_exp_f32_e32 v208, v208
	v_exp_f32_e32 v209, v209
	v_exp_f32_e32 v210, v210
	v_exp_f32_e32 v211, v211
	v_pk_add_f32 v[208:209], v[208:209], s[60:61]
	v_pk_add_f32 v[210:211], v[210:211], s[60:61]
	v_rcp_f32_e32 v208, v208
	v_rcp_f32_e32 v209, v209
	v_rcp_f32_e32 v210, v210
	v_rcp_f32_e32 v211, v211
	v_pk_mul_f32 v[200:201], v[200:201], v[208:209]
	v_pk_mul_f32 v[202:203], v[202:203], v[210:211]
	v_pk_mul_f32 v[200:201], v[200:201], v[204:205]
	v_pk_mul_f32 v[202:203], v[202:203], v[206:207]
	v_cvt_pk_bf16_f32 v242, v200, v201
	v_cvt_pk_bf16_f32 v243, v202, v203
	v_pk_fma_f32 v[200:201], v[132:133], v[60:61], v[140:141]
	v_pk_fma_f32 v[202:203], v[134:135], v[62:63], v[142:143]
	v_fmac_f32_dpp v200, v16, v128 row_shr:1 row_mask:0xf bank_mask:0xf
	v_fmac_f32_dpp v201, v17, v129 row_shr:1 row_mask:0xf bank_mask:0xf
	v_fmac_f32_dpp v202, v18, v130 row_shr:1 row_mask:0xf bank_mask:0xf
	v_fmac_f32_dpp v203, v19, v131 row_shr:1 row_mask:0xf bank_mask:0xf
	v_pk_fma_f32 v[200:201], v[192:193], v[216:217], v[200:201]
	v_pk_fma_f32 v[202:203], v[194:195], v[218:219], v[202:203]
	v_pk_fma_f32 v[200:201], v[48:49], v[136:137], v[200:201]
	v_pk_fma_f32 v[202:203], v[50:51], v[138:139], v[202:203]
	v_pk_fma_f32 v[204:205], v[172:173], v[52:53], v[180:181]
	v_pk_fma_f32 v[206:207], v[174:175], v[54:55], v[182:183]
	v_fmac_f32_dpp v204, v4, v160 row_shr:1 row_mask:0xf bank_mask:0xf
	v_fmac_f32_dpp v205, v5, v161 row_shr:1 row_mask:0xf bank_mask:0xf
	v_fmac_f32_dpp v206, v6, v162 row_shr:1 row_mask:0xf bank_mask:0xf
	v_fmac_f32_dpp v207, v7, v163 row_shr:1 row_mask:0xf bank_mask:0xf
	v_pk_fma_f32 v[204:205], v[196:197], v[224:225], v[204:205]
	v_pk_fma_f32 v[206:207], v[198:199], v[226:227], v[206:207]
	v_pk_fma_f32 v[204:205], v[36:37], v[176:177], v[204:205]
	v_pk_fma_f32 v[206:207], v[38:39], v[178:179], v[206:207]
	v_pk_mul_f32 v[208:209], v[200:201], s[58:59]
	v_pk_mul_f32 v[210:211], v[202:203], s[58:59]
	v_exp_f32_e32 v208, v208
	v_exp_f32_e32 v209, v209
	v_exp_f32_e32 v210, v210
	v_exp_f32_e32 v211, v211
	v_pk_add_f32 v[208:209], v[208:209], s[60:61]
	v_pk_add_f32 v[210:211], v[210:211], s[60:61]
	v_rcp_f32_e32 v208, v208
	v_rcp_f32_e32 v209, v209
	v_rcp_f32_e32 v210, v210
	v_rcp_f32_e32 v211, v211
	v_pk_mul_f32 v[200:201], v[200:201], v[208:209]
	v_pk_mul_f32 v[202:203], v[202:203], v[210:211]
	v_pk_mul_f32 v[200:201], v[200:201], v[204:205]
	v_pk_mul_f32 v[202:203], v[202:203], v[206:207]
	v_cvt_pk_bf16_f32 v244, v200, v201
	v_cvt_pk_bf16_f32 v245, v202, v203
	v_pk_fma_f32 v[200:201], v[132:133], v[48:49], v[140:141]
	v_pk_fma_f32 v[202:203], v[134:135], v[50:51], v[142:143]
	v_pk_fma_f32 v[200:201], v[60:61], v[128:129], v[200:201]
	v_pk_fma_f32 v[202:203], v[62:63], v[130:131], v[202:203]
	v_pk_fma_f32 v[200:201], v[32:33], v[136:137], v[200:201]
	v_pk_fma_f32 v[202:203], v[34:35], v[138:139], v[202:203]
	v_pk_fma_f32 v[204:205], v[172:173], v[36:37], v[180:181]
	v_pk_fma_f32 v[206:207], v[174:175], v[38:39], v[182:183]
	v_pk_fma_f32 v[204:205], v[52:53], v[160:161], v[204:205]
	v_pk_fma_f32 v[206:207], v[54:55], v[162:163], v[206:207]
	v_pk_fma_f32 v[204:205], v[20:21], v[176:177], v[204:205]
	v_pk_fma_f32 v[206:207], v[22:23], v[178:179], v[206:207]
	v_pk_mul_f32 v[208:209], v[200:201], s[58:59]
	v_pk_mul_f32 v[210:211], v[202:203], s[58:59]
	v_exp_f32_e32 v208, v208
	v_exp_f32_e32 v209, v209
	v_exp_f32_e32 v210, v210
	v_exp_f32_e32 v211, v211
	v_pk_add_f32 v[208:209], v[208:209], s[60:61]
	v_pk_add_f32 v[210:211], v[210:211], s[60:61]
	v_rcp_f32_e32 v208, v208
	v_rcp_f32_e32 v209, v209
	v_rcp_f32_e32 v210, v210
	v_rcp_f32_e32 v211, v211
	v_pk_mul_f32 v[200:201], v[200:201], v[208:209]
	v_pk_mul_f32 v[202:203], v[202:203], v[210:211]
	v_pk_mul_f32 v[200:201], v[200:201], v[204:205]
	v_pk_mul_f32 v[202:203], v[202:203], v[206:207]
	v_cvt_pk_bf16_f32 v246, v200, v201
	v_cvt_pk_bf16_f32 v247, v202, v203
	v_pk_fma_f32 v[200:201], v[132:133], v[32:33], v[140:141]
	v_pk_fma_f32 v[202:203], v[134:135], v[34:35], v[142:143]
	v_pk_fma_f32 v[200:201], v[48:49], v[128:129], v[200:201]
	v_pk_fma_f32 v[202:203], v[50:51], v[130:131], v[202:203]
	v_pk_fma_f32 v[200:201], v[16:17], v[136:137], v[200:201]
	v_pk_fma_f32 v[202:203], v[18:19], v[138:139], v[202:203]
	v_pk_fma_f32 v[204:205], v[172:173], v[20:21], v[180:181]
	v_pk_fma_f32 v[206:207], v[174:175], v[22:23], v[182:183]
	v_pk_fma_f32 v[204:205], v[36:37], v[160:161], v[204:205]
	v_pk_fma_f32 v[206:207], v[38:39], v[162:163], v[206:207]
	v_pk_fma_f32 v[204:205], v[4:5], v[176:177], v[204:205]
	v_pk_fma_f32 v[206:207], v[6:7], v[178:179], v[206:207]
	v_pk_mul_f32 v[208:209], v[200:201], s[58:59]
	v_pk_mul_f32 v[210:211], v[202:203], s[58:59]
	v_exp_f32_e32 v208, v208
	v_exp_f32_e32 v209, v209
	v_exp_f32_e32 v210, v210
	v_exp_f32_e32 v211, v211
	v_pk_add_f32 v[208:209], v[208:209], s[60:61]
	v_pk_add_f32 v[210:211], v[210:211], s[60:61]
	v_rcp_f32_e32 v208, v208
	v_rcp_f32_e32 v209, v209
	v_rcp_f32_e32 v210, v210
	v_rcp_f32_e32 v211, v211
	v_pk_mul_f32 v[200:201], v[200:201], v[208:209]
	v_pk_mul_f32 v[202:203], v[202:203], v[210:211]
	v_pk_mul_f32 v[200:201], v[200:201], v[204:205]
	v_pk_mul_f32 v[202:203], v[202:203], v[206:207]
	v_cvt_pk_bf16_f32 v248, v200, v201
	v_cvt_pk_bf16_f32 v249, v202, v203
	v_pk_fma_f32 v[200:201], v[132:133], v[16:17], v[140:141]
	v_pk_fma_f32 v[202:203], v[134:135], v[18:19], v[142:143]
	v_pk_fma_f32 v[200:201], v[32:33], v[128:129], v[200:201]
	v_pk_fma_f32 v[202:203], v[34:35], v[130:131], v[202:203]
	v_fmac_f32_dpp v200, v60, v136 row_shl:1 row_mask:0xf bank_mask:0xf
	v_fmac_f32_dpp v201, v61, v137 row_shl:1 row_mask:0xf bank_mask:0xf
	v_fmac_f32_dpp v202, v62, v138 row_shl:1 row_mask:0xf bank_mask:0xf
	v_fmac_f32_dpp v203, v63, v139 row_shl:1 row_mask:0xf bank_mask:0xf
	v_pk_fma_f32 v[200:201], v[192:193], v[220:221], v[200:201]
	v_pk_fma_f32 v[202:203], v[194:195], v[222:223], v[202:203]
	v_pk_fma_f32 v[204:205], v[172:173], v[4:5], v[180:181]
	v_pk_fma_f32 v[206:207], v[174:175], v[6:7], v[182:183]
	v_pk_fma_f32 v[204:205], v[20:21], v[160:161], v[204:205]
	v_pk_fma_f32 v[206:207], v[22:23], v[162:163], v[206:207]
	v_fmac_f32_dpp v204, v52, v176 row_shl:1 row_mask:0xf bank_mask:0xf
	v_fmac_f32_dpp v205, v53, v177 row_shl:1 row_mask:0xf bank_mask:0xf
	v_fmac_f32_dpp v206, v54, v178 row_shl:1 row_mask:0xf bank_mask:0xf
	v_fmac_f32_dpp v207, v55, v179 row_shl:1 row_mask:0xf bank_mask:0xf
	v_pk_fma_f32 v[204:205], v[196:197], v[232:233], v[204:205]
	v_pk_fma_f32 v[206:207], v[198:199], v[234:235], v[206:207]
	s_mov_b64 exec, s[54:55]
	v_add_u32_e32 v250, 0x10800, v252
	global_store_dwordx4 v250, v[200:203], s[56:57]
	v_add_u32_e32 v250, 0x13400, v252
	global_store_dwordx4 v250, v[204:207], s[56:57]
	s_mov_b64 exec, -1
	s_nop 4
	v_pk_mul_f32 v[208:209], v[200:201], s[58:59]
	v_pk_mul_f32 v[210:211], v[202:203], s[58:59]
	v_exp_f32_e32 v208, v208
	v_exp_f32_e32 v209, v209
	v_exp_f32_e32 v210, v210
	v_exp_f32_e32 v211, v211
	v_pk_add_f32 v[208:209], v[208:209], s[60:61]
	v_pk_add_f32 v[210:211], v[210:211], s[60:61]
	v_rcp_f32_e32 v208, v208
	v_rcp_f32_e32 v209, v209
	v_rcp_f32_e32 v210, v210
	v_rcp_f32_e32 v211, v211
	v_pk_mul_f32 v[200:201], v[200:201], v[208:209]
	v_pk_mul_f32 v[202:203], v[202:203], v[210:211]
	v_pk_mul_f32 v[200:201], v[200:201], v[204:205]
	v_pk_mul_f32 v[202:203], v[202:203], v[206:207]
	v_cvt_pk_bf16_f32 v250, v200, v201
	v_cvt_pk_bf16_f32 v251, v202, v203
	ds_read_b128 v[128:131], v229 offset:2064
	ds_read_b128 v[132:135], v229 offset:2576
	ds_read_b128 v[136:139], v229 offset:4112
	ds_read_b128 v[140:143], v229 offset:5136
	ds_read_b128 v[160:163], v229 offset:3088
	ds_read_b128 v[172:175], v229 offset:3600
	ds_read_b128 v[176:179], v229 offset:4624
	ds_read_b128 v[180:183], v229 offset:5648
	v_mov_b32_e32 v124, v236
	v_mov_b32_e32 v125, v237
	v_mov_b32_e32 v116, v238
	v_mov_b32_e32 v117, v239
	v_mov_b32_e32 v96, v240
	v_mov_b32_e32 v97, v241
	v_mov_b32_e32 v80, v242
	v_mov_b32_e32 v81, v243
	v_mov_b32_e32 v60, v244
	v_mov_b32_e32 v61, v245
	v_mov_b32_e32 v48, v246
	v_mov_b32_e32 v49, v247
	v_mov_b32_e32 v32, v248
	v_mov_b32_e32 v33, v249
	v_mov_b32_e32 v16, v250
	v_mov_b32_e32 v17, v251
	ds_read_b128 v[184:187], v231 offset:16
	ds_read_b128 v[188:191], v231 offset:528
	ds_read_b128 v[192:195], v231 offset:2064
	ds_read_b128 v[196:199], v231 offset:2576
	s_waitcnt lgkmcnt(4)
	v_cndmask_b32_e64 v216, 0, v128, s[34:35]
	v_cndmask_b32_e64 v220, 0, v136, s[36:37]
	v_cndmask_b32_e64 v217, 0, v129, s[34:35]
	v_cndmask_b32_e64 v221, 0, v137, s[36:37]
	v_cndmask_b32_e64 v218, 0, v130, s[34:35]
	v_cndmask_b32_e64 v222, 0, v138, s[36:37]
	v_cndmask_b32_e64 v219, 0, v131, s[34:35]
	v_cndmask_b32_e64 v223, 0, v139, s[36:37]
	v_cndmask_b32_e64 v224, 0, v160, s[34:35]
	v_cndmask_b32_e64 v232, 0, v176, s[36:37]
	v_cndmask_b32_e64 v225, 0, v161, s[34:35]
	v_cndmask_b32_e64 v233, 0, v177, s[36:37]
	v_cndmask_b32_e64 v226, 0, v162, s[34:35]
	v_cndmask_b32_e64 v234, 0, v178, s[36:37]
	v_cndmask_b32_e64 v227, 0, v163, s[34:35]
	v_cndmask_b32_e64 v235, 0, v179, s[36:37]
	s_waitcnt lgkmcnt(0)
	s_nop 1
	v_pk_fma_f32 v[200:201], v[132:133], v[120:121], v[140:141]
	v_pk_fma_f32 v[202:203], v[134:135], v[122:123], v[142:143]
	v_fmac_f32_dpp v200, v72, v128 row_shr:1 row_mask:0xf bank_mask:0xf
	v_fmac_f32_dpp v201, v73, v129 row_shr:1 row_mask:0xf bank_mask:0xf
	v_fmac_f32_dpp v202, v74, v130 row_shr:1 row_mask:0xf bank_mask:0xf
	v_fmac_f32_dpp v203, v75, v131 row_shr:1 row_mask:0xf bank_mask:0xf
	v_pk_fma_f32 v[200:201], v[184:185], v[216:217], v[200:201]
	v_pk_fma_f32 v[202:203], v[186:187], v[218:219], v[202:203]
	v_pk_fma_f32 v[200:201], v[112:113], v[136:137], v[200:201]
	v_pk_fma_f32 v[202:203], v[114:115], v[138:139], v[202:203]
	v_pk_fma_f32 v[204:205], v[172:173], v[104:105], v[180:181]
	v_pk_fma_f32 v[206:207], v[174:175], v[106:107], v[182:183]
	v_fmac_f32_dpp v204, v64, v160 row_shr:1 row_mask:0xf bank_mask:0xf
	v_fmac_f32_dpp v205, v65, v161 row_shr:1 row_mask:0xf bank_mask:0xf
	v_fmac_f32_dpp v206, v66, v162 row_shr:1 row_mask:0xf bank_mask:0xf
	v_fmac_f32_dpp v207, v67, v163 row_shr:1 row_mask:0xf bank_mask:0xf
	v_pk_fma_f32 v[204:205], v[188:189], v[224:225], v[204:205]
	v_pk_fma_f32 v[206:207], v[190:191], v[226:227], v[206:207]
	v_pk_fma_f32 v[204:205], v[92:93], v[176:177], v[204:205]
	v_pk_fma_f32 v[206:207], v[94:95], v[178:179], v[206:207]
	s_mov_b64 exec, s[52:53]
	v_add_u32_e32 v250, 0x5800, v252
	global_store_dwordx4 v250, v[200:203], s[56:57] offset:16
	v_add_u32_e32 v250, 0x8400, v252
	global_store_dwordx4 v250, v[204:207], s[56:57] offset:16
	s_mov_b64 exec, -1
	s_nop 4
	v_pk_mul_f32 v[208:209], v[200:201], s[58:59]
	v_pk_mul_f32 v[210:211], v[202:203], s[58:59]
	v_exp_f32_e32 v208, v208
	v_exp_f32_e32 v209, v209
	v_exp_f32_e32 v210, v210
	v_exp_f32_e32 v211, v211
	v_pk_add_f32 v[208:209], v[208:209], s[60:61]
	v_pk_add_f32 v[210:211], v[210:211], s[60:61]
	v_rcp_f32_e32 v208, v208
	v_rcp_f32_e32 v209, v209
	v_rcp_f32_e32 v210, v210
	v_rcp_f32_e32 v211, v211
	v_pk_mul_f32 v[200:201], v[200:201], v[208:209]
	v_pk_mul_f32 v[202:203], v[202:203], v[210:211]
	v_pk_mul_f32 v[200:201], v[200:201], v[204:205]
	v_pk_mul_f32 v[202:203], v[202:203], v[206:207]
	v_cvt_pk_bf16_f32 v126, v200, v201
	v_cvt_pk_bf16_f32 v127, v202, v203
	v_pk_fma_f32 v[200:201], v[132:133], v[112:113], v[140:141]
	v_pk_fma_f32 v[202:203], v[134:135], v[114:115], v[142:143]
	v_pk_fma_f32 v[200:201], v[120:121], v[128:129], v[200:201]
	v_pk_fma_f32 v[202:203], v[122:123], v[130:131], v[202:203]
	v_pk_fma_f32 v[200:201], v[88:89], v[136:137], v[200:201]
	v_pk_fma_f32 v[202:203], v[90:91], v[138:139], v[202:203]
	v_pk_fma_f32 v[204:205], v[172:173], v[92:93], v[180:181]
	v_pk_fma_f32 v[206:207], v[174:175], v[94:95], v[182:183]
	v_pk_fma_f32 v[204:205], v[104:105], v[160:161], v[204:205]
	v_pk_fma_f32 v[206:207], v[106:107], v[162:163], v[206:207]
	v_pk_fma_f32 v[204:205], v[76:77], v[176:177], v[204:205]
	v_pk_fma_f32 v[206:207], v[78:79], v[178:179], v[206:207]
	v_pk_mul_f32 v[208:209], v[200:201], s[58:59]
	v_pk_mul_f32 v[210:211], v[202:203], s[58:59]
	v_exp_f32_e32 v208, v208
	v_exp_f32_e32 v209, v209
	v_exp_f32_e32 v210, v210
	v_exp_f32_e32 v211, v211
	v_pk_add_f32 v[208:209], v[208:209], s[60:61]
	v_pk_add_f32 v[210:211], v[210:211], s[60:61]
	v_rcp_f32_e32 v208, v208
	v_rcp_f32_e32 v209, v209
	v_rcp_f32_e32 v210, v210
	v_rcp_f32_e32 v211, v211
	v_pk_mul_f32 v[200:201], v[200:201], v[208:209]
	v_pk_mul_f32 v[202:203], v[202:203], v[210:211]
	v_pk_mul_f32 v[200:201], v[200:201], v[204:205]
	v_pk_mul_f32 v[202:203], v[202:203], v[206:207]
	v_cvt_pk_bf16_f32 v118, v200, v201
	v_cvt_pk_bf16_f32 v119, v202, v203
	v_pk_fma_f32 v[200:201], v[132:133], v[88:89], v[140:141]
	v_pk_fma_f32 v[202:203], v[134:135], v[90:91], v[142:143]
	v_pk_fma_f32 v[200:201], v[112:113], v[128:129], v[200:201]
	v_pk_fma_f32 v[202:203], v[114:115], v[130:131], v[202:203]
	v_pk_fma_f32 v[200:201], v[72:73], v[136:137], v[200:201]
	v_pk_fma_f32 v[202:203], v[74:75], v[138:139], v[202:203]
	v_pk_fma_f32 v[204:205], v[172:173], v[76:77], v[180:181]
	v_pk_fma_f32 v[206:207], v[174:175], v[78:79], v[182:183]
	v_pk_fma_f32 v[204:205], v[92:93], v[160:161], v[204:205]
	v_pk_fma_f32 v[206:207], v[94:95], v[162:163], v[206:207]
	v_pk_fma_f32 v[204:205], v[64:65], v[176:177], v[204:205]
	v_pk_fma_f32 v[206:207], v[66:67], v[178:179], v[206:207]
	v_pk_mul_f32 v[208:209], v[200:201], s[58:59]
	v_pk_mul_f32 v[210:211], v[202:203], s[58:59]
	v_exp_f32_e32 v208, v208
	v_exp_f32_e32 v209, v209
	v_exp_f32_e32 v210, v210
	v_exp_f32_e32 v211, v211
	v_pk_add_f32 v[208:209], v[208:209], s[60:61]
	v_pk_add_f32 v[210:211], v[210:211], s[60:61]
	v_rcp_f32_e32 v208, v208
	v_rcp_f32_e32 v209, v209
	v_rcp_f32_e32 v210, v210
	v_rcp_f32_e32 v211, v211
	v_pk_mul_f32 v[200:201], v[200:201], v[208:209]
	v_pk_mul_f32 v[202:203], v[202:203], v[210:211]
	v_pk_mul_f32 v[200:201], v[200:201], v[204:205]
	v_pk_mul_f32 v[202:203], v[202:203], v[206:207]
	v_cvt_pk_bf16_f32 v98, v200, v201
	v_cvt_pk_bf16_f32 v99, v202, v203
	v_pk_fma_f32 v[200:201], v[132:133], v[72:73], v[140:141]
	v_pk_fma_f32 v[202:203], v[134:135], v[74:75], v[142:143]
	v_pk_fma_f32 v[200:201], v[88:89], v[128:129], v[200:201]
	v_pk_fma_f32 v[202:203], v[90:91], v[130:131], v[202:203]
	v_fmac_f32_dpp v200, v120, v136 row_shl:1 row_mask:0xf bank_mask:0xf
	v_fmac_f32_dpp v201, v121, v137 row_shl:1 row_mask:0xf bank_mask:0xf
	v_fmac_f32_dpp v202, v122, v138 row_shl:1 row_mask:0xf bank_mask:0xf
	v_fmac_f32_dpp v203, v123, v139 row_shl:1 row_mask:0xf bank_mask:0xf
	v_pk_fma_f32 v[200:201], v[184:185], v[220:221], v[200:201]
	v_pk_fma_f32 v[202:203], v[186:187], v[222:223], v[202:203]
	v_pk_fma_f32 v[204:205], v[172:173], v[64:65], v[180:181]
	v_pk_fma_f32 v[206:207], v[174:175], v[66:67], v[182:183]
	v_pk_fma_f32 v[204:205], v[76:77], v[160:161], v[204:205]
	v_pk_fma_f32 v[206:207], v[78:79], v[162:163], v[206:207]
	v_fmac_f32_dpp v204, v104, v176 row_shl:1 row_mask:0xf bank_mask:0xf
	v_fmac_f32_dpp v205, v105, v177 row_shl:1 row_mask:0xf bank_mask:0xf
	v_fmac_f32_dpp v206, v106, v178 row_shl:1 row_mask:0xf bank_mask:0xf
	v_fmac_f32_dpp v207, v107, v179 row_shl:1 row_mask:0xf bank_mask:0xf
	v_pk_fma_f32 v[204:205], v[188:189], v[232:233], v[204:205]
	v_pk_fma_f32 v[206:207], v[190:191], v[234:235], v[206:207]
	v_pk_mul_f32 v[208:209], v[200:201], s[58:59]
	v_pk_mul_f32 v[210:211], v[202:203], s[58:59]
	v_exp_f32_e32 v208, v208
	v_exp_f32_e32 v209, v209
	v_exp_f32_e32 v210, v210
	v_exp_f32_e32 v211, v211
	v_pk_add_f32 v[208:209], v[208:209], s[60:61]
	v_pk_add_f32 v[210:211], v[210:211], s[60:61]
	v_rcp_f32_e32 v208, v208
	v_rcp_f32_e32 v209, v209
	v_rcp_f32_e32 v210, v210
	v_rcp_f32_e32 v211, v211
	v_pk_mul_f32 v[200:201], v[200:201], v[208:209]
	v_pk_mul_f32 v[202:203], v[202:203], v[210:211]
	v_pk_mul_f32 v[200:201], v[200:201], v[204:205]
	v_pk_mul_f32 v[202:203], v[202:203], v[206:207]
	v_cvt_pk_bf16_f32 v82, v200, v201
	v_cvt_pk_bf16_f32 v83, v202, v203
	v_pk_fma_f32 v[200:201], v[132:133], v[56:57], v[140:141]
	v_pk_fma_f32 v[202:203], v[134:135], v[58:59], v[142:143]
	v_fmac_f32_dpp v200, v8, v128 row_shr:1 row_mask:0xf bank_mask:0xf
	v_fmac_f32_dpp v201, v9, v129 row_shr:1 row_mask:0xf bank_mask:0xf
	v_fmac_f32_dpp v202, v10, v130 row_shr:1 row_mask:0xf bank_mask:0xf
	v_fmac_f32_dpp v203, v11, v131 row_shr:1 row_mask:0xf bank_mask:0xf
	v_pk_fma_f32 v[200:201], v[192:193], v[216:217], v[200:201]
	v_pk_fma_f32 v[202:203], v[194:195], v[218:219], v[202:203]
	v_pk_fma_f32 v[200:201], v[40:41], v[136:137], v[200:201]
	v_pk_fma_f32 v[202:203], v[42:43], v[138:139], v[202:203]
	v_pk_fma_f32 v[204:205], v[172:173], v[44:45], v[180:181]
	v_pk_fma_f32 v[206:207], v[174:175], v[46:47], v[182:183]
	v_fmac_f32_dpp v204, v0, v160 row_shr:1 row_mask:0xf bank_mask:0xf
	v_fmac_f32_dpp v205, v1, v161 row_shr:1 row_mask:0xf bank_mask:0xf
	v_fmac_f32_dpp v206, v2, v162 row_shr:1 row_mask:0xf bank_mask:0xf
	v_fmac_f32_dpp v207, v3, v163 row_shr:1 row_mask:0xf bank_mask:0xf
	v_pk_fma_f32 v[204:205], v[196:197], v[224:225], v[204:205]
	v_pk_fma_f32 v[206:207], v[198:199], v[226:227], v[206:207]
	v_pk_fma_f32 v[204:205], v[28:29], v[176:177], v[204:205]
	v_pk_fma_f32 v[206:207], v[30:31], v[178:179], v[206:207]
	v_pk_mul_f32 v[208:209], v[200:201], s[58:59]
	v_pk_mul_f32 v[210:211], v[202:203], s[58:59]
	v_exp_f32_e32 v208, v208
	v_exp_f32_e32 v209, v209
	v_exp_f32_e32 v210, v210
	v_exp_f32_e32 v211, v211
	v_pk_add_f32 v[208:209], v[208:209], s[60:61]
	v_pk_add_f32 v[210:211], v[210:211], s[60:61]
	v_rcp_f32_e32 v208, v208
	v_rcp_f32_e32 v209, v209
	v_rcp_f32_e32 v210, v210
	v_rcp_f32_e32 v211, v211
	v_pk_mul_f32 v[200:201], v[200:201], v[208:209]
	v_pk_mul_f32 v[202:203], v[202:203], v[210:211]
	v_pk_mul_f32 v[200:201], v[200:201], v[204:205]
	v_pk_mul_f32 v[202:203], v[202:203], v[206:207]
	v_cvt_pk_bf16_f32 v62, v200, v201
	v_cvt_pk_bf16_f32 v63, v202, v203
	v_pk_fma_f32 v[200:201], v[132:133], v[40:41], v[140:141]
	v_pk_fma_f32 v[202:203], v[134:135], v[42:43], v[142:143]
	v_pk_fma_f32 v[200:201], v[56:57], v[128:129], v[200:201]
	v_pk_fma_f32 v[202:203], v[58:59], v[130:131], v[202:203]
	v_pk_fma_f32 v[200:201], v[24:25], v[136:137], v[200:201]
	v_pk_fma_f32 v[202:203], v[26:27], v[138:139], v[202:203]
	v_pk_fma_f32 v[204:205], v[172:173], v[28:29], v[180:181]
	v_pk_fma_f32 v[206:207], v[174:175], v[30:31], v[182:183]
	v_pk_fma_f32 v[204:205], v[44:45], v[160:161], v[204:205]
	v_pk_fma_f32 v[206:207], v[46:47], v[162:163], v[206:207]
	v_pk_fma_f32 v[204:205], v[12:13], v[176:177], v[204:205]
	v_pk_fma_f32 v[206:207], v[14:15], v[178:179], v[206:207]
	v_pk_mul_f32 v[208:209], v[200:201], s[58:59]
	v_pk_mul_f32 v[210:211], v[202:203], s[58:59]
	v_exp_f32_e32 v208, v208
	v_exp_f32_e32 v209, v209
	v_exp_f32_e32 v210, v210
	v_exp_f32_e32 v211, v211
	v_pk_add_f32 v[208:209], v[208:209], s[60:61]
	v_pk_add_f32 v[210:211], v[210:211], s[60:61]
	v_rcp_f32_e32 v208, v208
	v_rcp_f32_e32 v209, v209
	v_rcp_f32_e32 v210, v210
	v_rcp_f32_e32 v211, v211
	v_pk_mul_f32 v[200:201], v[200:201], v[208:209]
	v_pk_mul_f32 v[202:203], v[202:203], v[210:211]
	v_pk_mul_f32 v[200:201], v[200:201], v[204:205]
	v_pk_mul_f32 v[202:203], v[202:203], v[206:207]
	v_cvt_pk_bf16_f32 v50, v200, v201
	v_cvt_pk_bf16_f32 v51, v202, v203
	v_pk_fma_f32 v[200:201], v[132:133], v[24:25], v[140:141]
	v_pk_fma_f32 v[202:203], v[134:135], v[26:27], v[142:143]
	v_pk_fma_f32 v[200:201], v[40:41], v[128:129], v[200:201]
	v_pk_fma_f32 v[202:203], v[42:43], v[130:131], v[202:203]
	v_pk_fma_f32 v[200:201], v[8:9], v[136:137], v[200:201]
	v_pk_fma_f32 v[202:203], v[10:11], v[138:139], v[202:203]
	v_pk_fma_f32 v[204:205], v[172:173], v[12:13], v[180:181]
	v_pk_fma_f32 v[206:207], v[174:175], v[14:15], v[182:183]
	v_pk_fma_f32 v[204:205], v[28:29], v[160:161], v[204:205]
	v_pk_fma_f32 v[206:207], v[30:31], v[162:163], v[206:207]
	v_pk_fma_f32 v[204:205], v[0:1], v[176:177], v[204:205]
	v_pk_fma_f32 v[206:207], v[2:3], v[178:179], v[206:207]
	v_pk_mul_f32 v[208:209], v[200:201], s[58:59]
	v_pk_mul_f32 v[210:211], v[202:203], s[58:59]
	v_exp_f32_e32 v208, v208
	v_exp_f32_e32 v209, v209
	v_exp_f32_e32 v210, v210
	v_exp_f32_e32 v211, v211
	v_pk_add_f32 v[208:209], v[208:209], s[60:61]
	v_pk_add_f32 v[210:211], v[210:211], s[60:61]
	v_rcp_f32_e32 v208, v208
	v_rcp_f32_e32 v209, v209
	v_rcp_f32_e32 v210, v210
	v_rcp_f32_e32 v211, v211
	v_pk_mul_f32 v[200:201], v[200:201], v[208:209]
	v_pk_mul_f32 v[202:203], v[202:203], v[210:211]
	v_pk_mul_f32 v[200:201], v[200:201], v[204:205]
	v_pk_mul_f32 v[202:203], v[202:203], v[206:207]
	v_cvt_pk_bf16_f32 v34, v200, v201
	v_cvt_pk_bf16_f32 v35, v202, v203
	v_pk_fma_f32 v[200:201], v[132:133], v[8:9], v[140:141]
	v_pk_fma_f32 v[202:203], v[134:135], v[10:11], v[142:143]
	v_pk_fma_f32 v[200:201], v[24:25], v[128:129], v[200:201]
	v_pk_fma_f32 v[202:203], v[26:27], v[130:131], v[202:203]
	v_fmac_f32_dpp v200, v56, v136 row_shl:1 row_mask:0xf bank_mask:0xf
	v_fmac_f32_dpp v201, v57, v137 row_shl:1 row_mask:0xf bank_mask:0xf
	v_fmac_f32_dpp v202, v58, v138 row_shl:1 row_mask:0xf bank_mask:0xf
	v_fmac_f32_dpp v203, v59, v139 row_shl:1 row_mask:0xf bank_mask:0xf
	v_pk_fma_f32 v[200:201], v[192:193], v[220:221], v[200:201]
	v_pk_fma_f32 v[202:203], v[194:195], v[222:223], v[202:203]
	v_pk_fma_f32 v[204:205], v[172:173], v[0:1], v[180:181]
	v_pk_fma_f32 v[206:207], v[174:175], v[2:3], v[182:183]
	v_pk_fma_f32 v[204:205], v[12:13], v[160:161], v[204:205]
	v_pk_fma_f32 v[206:207], v[14:15], v[162:163], v[206:207]
	v_fmac_f32_dpp v204, v44, v176 row_shl:1 row_mask:0xf bank_mask:0xf
	v_fmac_f32_dpp v205, v45, v177 row_shl:1 row_mask:0xf bank_mask:0xf
	v_fmac_f32_dpp v206, v46, v178 row_shl:1 row_mask:0xf bank_mask:0xf
	v_fmac_f32_dpp v207, v47, v179 row_shl:1 row_mask:0xf bank_mask:0xf
	v_pk_fma_f32 v[204:205], v[196:197], v[232:233], v[204:205]
	v_pk_fma_f32 v[206:207], v[198:199], v[234:235], v[206:207]
	s_mov_b64 exec, s[54:55]
	v_add_u32_e32 v250, 0x10800, v252
	global_store_dwordx4 v250, v[200:203], s[56:57] offset:16
	v_add_u32_e32 v250, 0x13400, v252
	global_store_dwordx4 v250, v[204:207], s[56:57] offset:16
	s_mov_b64 exec, -1
	s_nop 4
	v_pk_mul_f32 v[208:209], v[200:201], s[58:59]
	v_pk_mul_f32 v[210:211], v[202:203], s[58:59]
	v_exp_f32_e32 v208, v208
	v_exp_f32_e32 v209, v209
	v_exp_f32_e32 v210, v210
	v_exp_f32_e32 v211, v211
	v_pk_add_f32 v[208:209], v[208:209], s[60:61]
	v_pk_add_f32 v[210:211], v[210:211], s[60:61]
	v_rcp_f32_e32 v208, v208
	v_rcp_f32_e32 v209, v209
	v_rcp_f32_e32 v210, v210
	v_rcp_f32_e32 v211, v211
	v_pk_mul_f32 v[200:201], v[200:201], v[208:209]
	v_pk_mul_f32 v[202:203], v[202:203], v[210:211]
	v_pk_mul_f32 v[200:201], v[200:201], v[204:205]
	v_pk_mul_f32 v[202:203], v[202:203], v[206:207]
	v_cvt_pk_bf16_f32 v18, v200, v201
	v_cvt_pk_bf16_f32 v19, v202, v203
	global_store_dwordx4 v171, v[124:127], s[30:31]
	v_add_u32_e32 v250, 0x1600, v171
	global_store_dwordx4 v250, v[116:119], s[30:31]
	s_nop 0
	v_add_u32_e32 v250, 0x2c00, v171
	global_store_dwordx4 v250, v[96:99], s[30:31]
	s_nop 0
	v_add_u32_e32 v250, 0x4200, v171
	global_store_dwordx4 v250, v[80:83], s[30:31]
	s_nop 0
	v_add_u32_e32 v250, 0xb0000, v171
	global_store_dwordx4 v250, v[60:63], s[30:31]
	s_nop 0
	v_add_u32_e32 v250, 0xb1600, v171
	global_store_dwordx4 v250, v[48:51], s[30:31]
	s_nop 0
	v_add_u32_e32 v250, 0xb2c00, v171
	global_store_dwordx4 v250, v[32:35], s[30:31]
	s_nop 0
	v_add_u32_e32 v250, 0xb4200, v171
	global_store_dwordx4 v250, v[16:19], s[30:31]
	s_nop 0
	s_and_b64 s[34:35], s[4:5], exec
	s_cbranch_scc0 .LepC_nonext
	s_xor_b32 s101, s101, 1
	s_or_b32 s101, s101, 2
	s_and_b32 s32, s101, 1
	s_mulk_i32 s32, 0x1800
	s_add_i32 s32, s32, 0x22c00
	v_readfirstlane_b32 s79, v230
	s_cmp_lt_u32 s79, 64
	s_cbranch_scc0 .LepC_nfe
	s_add_i32 s30, s24, 0
	s_ashr_i32 s30, s30, 2
	s_add_i32 s30, s30, 1
	s_cmp_gt_i32 s24, -1
	s_cselect_b32 s30, s30, 0
	s_mul_hi_i32 s31, s30, 0x5800
	s_mulk_i32 s30, 0x5800
	s_add_u32 s30, s33, s30
	s_addc_u32 s31, s50, s31
	v_readlane_b32 s34, v254, 5
	v_readlane_b32 s35, v254, 6
	v_readlane_b32 s36, v254, 7
	v_readlane_b32 s37, v254, 8
	s_nop 0
	s_add_u32 s34, s34, 0x10800
	s_addc_u32 s35, s35, 0
	s_add_u32 s36, s36, 0x5800
	s_addc_u32 s37, s37, 0
	v_and_b32_e32 v238, 63, v230
	v_lshrrev_b32_e32 v239, 5, v238
	v_and_b32_e32 v240, 31, v238
	v_lshlrev_b32_e32 v240, 4, v240
	s_lshl_b32 s79, s22, 9
	v_add_u32_e32 v240, s79, v240
	v_mul_u32_u24_e32 v241, 0x2c00, v239
	v_mul_u32_u24_e32 v242, 0x5800, v239
	v_add_u32_e32 v241, v241, v240
	v_add_u32_e32 v242, v242, v240
	v_lshlrev_b32_e32 v243, 4, v238
	s_lshl_b32 s79, s24, 10
	v_add_u32_e32 v243, s79, v243
	s_mov_b32 m0, s32
	s_nop 0
	global_load_lds_dwordx4 v243, s[10:11]
	s_add_i32 m0, s32, 1024
	s_nop 0
	global_load_lds_dwordx4 v241, s[30:31]
	s_add_i32 m0, s32, 2048
	s_nop 0
	global_load_lds_dwordx4 v242, s[34:35]
	v_add_u32_e32 v243, 0x2c00, v242
	s_add_i32 m0, s32, 3072
	s_nop 0
	global_load_lds_dwordx4 v243, s[34:35]
	v_add_u32_e32 v243, 0xb000, v241
	s_add_i32 m0, s32, 4096
	s_nop 0
	global_load_lds_dwordx4 v243, s[34:35]
	s_add_i32 m0, s32, 5120
	s_nop 0
	global_load_lds_dwordx4 v241, s[36:37]
